# w2 with the per-phase s_setprio flips deleted from the GEMM K-loops (both wave halves at priority 0)
# speedup vs baseline: 1.0001x; 1.0001x over previous
; #define PG8_STAGE(bufoff, gbase, voff) do { _Pragma("unroll") for (int _i = 0; _i < 2; ++_i) \
;         __builtin_amdgcn_global_load_lds((const unsigned*)((const char*)(gbase) + (voff)[_i]), (LAS unsigned*)(lds + (bufoff) + ldsw + _i * 8192), 16, 0, 0); } while (0)
; #define PG8_LDA(dst, b, h) do { _Pragma("unroll") for (int m = 0; m < 4; ++m) _Pragma("unroll") for (int k = 0; k < 2; ++k) dst[m][k] = *(const LAS bf16x8*)(lds + PG8_SA(b, h) + aoff + m * 2048 + k * 1024); } while (0)
; #define PG8_LDB(dst, b, h) do { _Pragma("unroll") for (int n = 0; n < 2; ++n) _Pragma("unroll") for (int k = 0; k < 2; ++k) dst[n][k] = *(const LAS bf16x8*)(lds + PG8_SB(b, h) + boff + n * 2048 + k * 1024); } while (0)
; #define PG8_MMA(ai, bj, At, Bt) do { __builtin_amdgcn_s_setprio(1); _Pragma("unroll") for (int m = 0; m < 4; ++m) _Pragma("unroll") for (int n = 0; n < 2; ++n) _Pragma("unroll") for (int k = 0; k < 2; ++k) \
;         acc[ai][bj][m][n] = __builtin_amdgcn_mfma_f32_16x16x32_bf16(Bt[n][k], At[m][k], acc[ai][bj][m][n], 0, 0, 0); __builtin_amdgcn_s_setprio(0); } while (0)
; #define PG8_WAIT_V(n) asm volatile("s_waitcnt vmcnt(" #n ")" ::: "memory")
; #define PG8_BAR __builtin_amdgcn_s_barrier()
; template <class Epi>
; __device__ __forceinline__ void gemm_phase(LAS unsigned char* lds, const Gemm g, const StaticOrder& S, const Epi& E) {
;     ...
;             PG8_LDB(B0, 0, 0); PG8_LDB(B1, 0, 1); PG8_SCHED; PG8_LDA(At, 0, 0); PG8_STAGE(PG8_SA(1, 1), a1 + hstep, voffA);
;             PG8_WAIT_V(8); PG8_WAIT_L(0); PG8_BAR; PG8_MMA(0, 0, At, B0); PG8_MMA(0, 1, At, B1); PG8_BAR; PG8_SCHED;
;             PG8_LDA(At, 0, 1); PG8_STAGE(PG8_SB(0, 0), b2, voffB); PG8_STAGE(PG8_SB(0, 1), b2 + hstep, voffB); PG8_STAGE(PG8_SA(0, 0), a2, voffA);
;             PG8_WAIT_V(8); PG8_WAIT_L(0); PG8_BAR; PG8_MMA(1, 0, At, B0); PG8_MMA(1, 1, At, B1); PG8_BAR; PG8_SCHED;
;             PG8_LDB(B0, 1, 0); PG8_LDB(B1, 1, 1); PG8_SCHED; PG8_LDA(At, 1, 0); PG8_STAGE(PG8_SA(0, 1), a2 + hstep, voffA);
;             PG8_WAIT_V(8); PG8_WAIT_L(0); PG8_BAR; PG8_MMA(0, 0, At, B0); PG8_MMA(0, 1, At, B1); PG8_BAR; PG8_SCHED;
;             PG8_LDA(At, 1, 1); PG8_STAGE(PG8_SB(1, 0), b3, voffB); PG8_STAGE(PG8_SB(1, 1), b3 + hstep, voffB); PG8_STAGE(PG8_SA(1, 0), a3, voffA);
;             PG8_WAIT_V(8); PG8_WAIT_L(0); PG8_BAR; PG8_MMA(1, 0, At, B0); PG8_MMA(1, 1, At, B1); PG8_BAR; PG8_SCHED;
.LBB0_134:
	ds_read_b128 v[158:161], v150
	ds_read_b128 v[162:165], v150 offset:1024
	ds_read_b128 v[166:169], v150 offset:2048
	ds_read_b128 v[174:177], v150 offset:3072
	ds_read_b128 v[178:181], v151
	ds_read_b128 v[182:185], v151 offset:1024
	ds_read_b128 v[186:189], v151 offset:2048
	ds_read_b128 v[190:193], v151 offset:3072
	s_add_u32 s66, s64, 0xfffc0080
	s_addc_u32 s67, s65, -1
	s_cmp_eq_u32 s92, 12
	s_cselect_b32 s69, s87, s67
	s_cselect_b32 s68, s88, s66
	s_cselect_b32 s67, s47, s91
	s_cselect_b32 s66, s89, s90
	s_add_i32 m0, s61, 0xc000
	ds_read_b128 v[194:197], v152
	ds_read_b128 v[198:201], v152 offset:1024
	ds_read_b128 v[202:205], v152 offset:2048
	ds_read_b128 v[206:209], v152 offset:3072
	ds_read_b128 v[210:213], v152 offset:4096
	ds_read_b128 v[214:217], v152 offset:5120
	ds_read_b128 v[218:221], v152 offset:6144
	ds_read_b128 v[222:225], v152 offset:7168
	global_load_lds_dwordx4 v140, s[64:65]
	s_add_i32 m0, s61, 0xe000
	s_nop 0
	global_load_lds_dwordx4 v142, s[64:65]
	s_waitcnt vmcnt(8)
	s_waitcnt lgkmcnt(0)
	s_barrier
	v_mfma_f32_16x16x32_bf16 v[126:129], v[158:161], v[194:197], v[126:129]
	v_mfma_f32_16x16x32_bf16 v[118:121], v[166:169], v[194:197], v[118:121]
	v_mfma_f32_16x16x32_bf16 v[110:113], v[158:161], v[202:205], v[110:113]
	v_mfma_f32_16x16x32_bf16 v[102:105], v[166:169], v[202:205], v[102:105]
	v_mfma_f32_16x16x32_bf16 v[94:97], v[158:161], v[210:213], v[94:97]
	v_mfma_f32_16x16x32_bf16 v[86:89], v[166:169], v[210:213], v[86:89]
	v_mfma_f32_16x16x32_bf16 v[78:81], v[158:161], v[218:221], v[78:81]
	v_mfma_f32_16x16x32_bf16 v[70:73], v[166:169], v[218:221], v[70:73]
	v_mfma_f32_16x16x32_bf16 v[126:129], v[162:165], v[198:201], v[126:129]
	v_mfma_f32_16x16x32_bf16 v[118:121], v[174:177], v[198:201], v[118:121]
	v_mfma_f32_16x16x32_bf16 v[110:113], v[162:165], v[206:209], v[110:113]
	v_mfma_f32_16x16x32_bf16 v[102:105], v[174:177], v[206:209], v[102:105]
	v_mfma_f32_16x16x32_bf16 v[94:97], v[162:165], v[214:217], v[94:97]
	v_mfma_f32_16x16x32_bf16 v[86:89], v[174:177], v[214:217], v[86:89]
	v_mfma_f32_16x16x32_bf16 v[78:81], v[162:165], v[222:225], v[78:81]
	v_mfma_f32_16x16x32_bf16 v[70:73], v[174:177], v[222:225], v[70:73]
	v_mfma_f32_16x16x32_bf16 v[122:125], v[178:181], v[194:197], v[122:125]
	v_mfma_f32_16x16x32_bf16 v[114:117], v[186:189], v[194:197], v[114:117]
	v_mfma_f32_16x16x32_bf16 v[106:109], v[178:181], v[202:205], v[106:109]
	v_mfma_f32_16x16x32_bf16 v[98:101], v[186:189], v[202:205], v[98:101]
	v_mfma_f32_16x16x32_bf16 v[90:93], v[178:181], v[210:213], v[90:93]
	v_mfma_f32_16x16x32_bf16 v[82:85], v[186:189], v[210:213], v[82:85]
	v_mfma_f32_16x16x32_bf16 v[74:77], v[178:181], v[218:221], v[74:77]
	v_mfma_f32_16x16x32_bf16 v[66:69], v[186:189], v[218:221], v[66:69]
	v_mfma_f32_16x16x32_bf16 v[122:125], v[182:185], v[198:201], v[122:125]
	v_mfma_f32_16x16x32_bf16 v[114:117], v[190:193], v[198:201], v[114:117]
	v_mfma_f32_16x16x32_bf16 v[106:109], v[182:185], v[206:209], v[106:109]
	v_mfma_f32_16x16x32_bf16 v[98:101], v[190:193], v[206:209], v[98:101]
	v_mfma_f32_16x16x32_bf16 v[90:93], v[182:185], v[214:217], v[90:93]
	v_mfma_f32_16x16x32_bf16 v[82:85], v[190:193], v[214:217], v[82:85]
	v_mfma_f32_16x16x32_bf16 v[74:77], v[182:185], v[222:225], v[74:77]
	v_mfma_f32_16x16x32_bf16 v[66:69], v[190:193], v[222:225], v[66:69]
	s_barrier
	s_add_u32 s98, s66, s8
	s_addc_u32 s99, s67, s9
	s_add_u32 s100, s68, s8
	s_addc_u32 s101, s69, s9
	s_add_i32 s93, s83, s6
	s_mov_b32 m0, s93
	ds_read_b128 v[194:197], v152 offset:16384
	ds_read_b128 v[198:201], v152 offset:17408
	ds_read_b128 v[202:205], v152 offset:18432
	ds_read_b128 v[206:209], v152 offset:19456
	ds_read_b128 v[210:213], v152 offset:20480
	ds_read_b128 v[214:217], v152 offset:21504
	ds_read_b128 v[218:221], v152 offset:22528
	ds_read_b128 v[222:225], v152 offset:23552
	global_load_lds_dwordx4 v132, s[66:67]
	s_add_i32 m0, s93, 0x2000
	s_add_u32 s94, s66, 0x40000
	s_addc_u32 s95, s67, 0
	s_add_i32 s93, s84, s6
	global_load_lds_dwordx4 v136, s[66:67]
	s_mov_b32 m0, s93
	s_nop 0
	global_load_lds_dwordx4 v132, s[94:95]
	s_add_i32 m0, s93, 0x2000
	s_nop 0
	global_load_lds_dwordx4 v136, s[94:95]
	s_mov_b32 m0, s61
	s_nop 0
	global_load_lds_dwordx4 v130, s[68:69]
	s_mov_b32 m0, s63
	s_nop 0
	global_load_lds_dwordx4 v134, s[68:69]
	s_waitcnt vmcnt(8)
	s_waitcnt lgkmcnt(0)
	s_barrier
	v_mfma_f32_16x16x32_bf16 v[62:65], v[158:161], v[194:197], v[62:65]
	v_mfma_f32_16x16x32_bf16 v[54:57], v[166:169], v[194:197], v[54:57]
	v_mfma_f32_16x16x32_bf16 v[46:49], v[158:161], v[202:205], v[46:49]
	v_mfma_f32_16x16x32_bf16 v[38:41], v[166:169], v[202:205], v[38:41]
	v_mfma_f32_16x16x32_bf16 v[30:33], v[158:161], v[210:213], v[30:33]
	v_mfma_f32_16x16x32_bf16 v[22:25], v[166:169], v[210:213], v[22:25]
	v_mfma_f32_16x16x32_bf16 v[14:17], v[158:161], v[218:221], v[14:17]
	v_mfma_f32_16x16x32_bf16 v[6:9], v[166:169], v[218:221], v[6:9]
	v_mfma_f32_16x16x32_bf16 v[62:65], v[162:165], v[198:201], v[62:65]
	v_mfma_f32_16x16x32_bf16 v[54:57], v[174:177], v[198:201], v[54:57]
	v_mfma_f32_16x16x32_bf16 v[46:49], v[162:165], v[206:209], v[46:49]
	v_mfma_f32_16x16x32_bf16 v[38:41], v[174:177], v[206:209], v[38:41]
	v_mfma_f32_16x16x32_bf16 v[30:33], v[162:165], v[214:217], v[30:33]
	v_mfma_f32_16x16x32_bf16 v[22:25], v[174:177], v[214:217], v[22:25]
	v_mfma_f32_16x16x32_bf16 v[14:17], v[162:165], v[222:225], v[14:17]
	v_mfma_f32_16x16x32_bf16 v[6:9], v[174:177], v[222:225], v[6:9]
	v_mfma_f32_16x16x32_bf16 v[58:61], v[178:181], v[194:197], v[58:61]
	v_mfma_f32_16x16x32_bf16 v[50:53], v[186:189], v[194:197], v[50:53]
	v_mfma_f32_16x16x32_bf16 v[42:45], v[178:181], v[202:205], v[42:45]
	v_mfma_f32_16x16x32_bf16 v[34:37], v[186:189], v[202:205], v[34:37]
	v_mfma_f32_16x16x32_bf16 v[26:29], v[178:181], v[210:213], v[26:29]
	v_mfma_f32_16x16x32_bf16 v[18:21], v[186:189], v[210:213], v[18:21]
	v_mfma_f32_16x16x32_bf16 v[10:13], v[178:181], v[218:221], v[10:13]
	v_mfma_f32_16x16x32_bf16 v[2:5], v[186:189], v[218:221], v[2:5]
	v_mfma_f32_16x16x32_bf16 v[58:61], v[182:185], v[198:201], v[58:61]
	v_mfma_f32_16x16x32_bf16 v[50:53], v[190:193], v[198:201], v[50:53]
	v_mfma_f32_16x16x32_bf16 v[42:45], v[182:185], v[206:209], v[42:45]
	v_mfma_f32_16x16x32_bf16 v[34:37], v[190:193], v[206:209], v[34:37]
	v_mfma_f32_16x16x32_bf16 v[26:29], v[182:185], v[214:217], v[26:29]
	v_mfma_f32_16x16x32_bf16 v[18:21], v[190:193], v[214:217], v[18:21]
	v_mfma_f32_16x16x32_bf16 v[10:13], v[182:185], v[222:225], v[10:13]
	v_mfma_f32_16x16x32_bf16 v[2:5], v[190:193], v[222:225], v[2:5]
	s_barrier
; #define PG8_STAGE(bufoff, gbase, voff) do { _Pragma("unroll") for (int _i = 0; _i < 2; ++_i) \
;         __builtin_amdgcn_global_load_lds((const unsigned*)((const char*)(gbase) + (voff)[_i]), (LAS unsigned*)(lds + (bufoff) + ldsw + _i * 8192), 16, 0, 0); } while (0)
; #define PG8_LDA(dst, b, h) do { _Pragma("unroll") for (int m = 0; m < 4; ++m) _Pragma("unroll") for (int k = 0; k < 2; ++k) dst[m][k] = *(const LAS bf16x8*)(lds + PG8_SA(b, h) + aoff + m * 2048 + k * 1024); } while (0)
; #define PG8_LDB(dst, b, h) do { _Pragma("unroll") for (int n = 0; n < 2; ++n) _Pragma("unroll") for (int k = 0; k < 2; ++k) dst[n][k] = *(const LAS bf16x8*)(lds + PG8_SB(b, h) + boff + n * 2048 + k * 1024); } while (0)
; #define PG8_MMA(ai, bj, At, Bt) do { __builtin_amdgcn_s_setprio(1); _Pragma("unroll") for (int m = 0; m < 4; ++m) _Pragma("unroll") for (int n = 0; n < 2; ++n) _Pragma("unroll") for (int k = 0; k < 2; ++k) \
;         acc[ai][bj][m][n] = __builtin_amdgcn_mfma_f32_16x16x32_bf16(Bt[n][k], At[m][k], acc[ai][bj][m][n], 0, 0, 0); __builtin_amdgcn_s_setprio(0); } while (0)
; #define PG8_WAIT_V(n) asm volatile("s_waitcnt vmcnt(" #n ")" ::: "memory")
; #define PG8_BAR __builtin_amdgcn_s_barrier()
; template <class Epi>
; __device__ __forceinline__ void gemm_phase(LAS unsigned char* lds, const Gemm g, const StaticOrder& S, const Epi& E) {
;     ...
;             PG8_LDB(B0, 0, 0); PG8_LDB(B1, 0, 1); PG8_SCHED; PG8_LDA(At, 0, 0); PG8_STAGE(PG8_SA(1, 1), a1 + hstep, voffA);
;             PG8_WAIT_V(8); PG8_WAIT_L(0); PG8_BAR; PG8_MMA(0, 0, At, B0); PG8_MMA(0, 1, At, B1); PG8_BAR; PG8_SCHED;
;             PG8_LDA(At, 0, 1); PG8_STAGE(PG8_SB(0, 0), b2, voffB); PG8_STAGE(PG8_SB(0, 1), b2 + hstep, voffB); PG8_STAGE(PG8_SA(0, 0), a2, voffA);
;             PG8_WAIT_V(8); PG8_WAIT_L(0); PG8_BAR; PG8_MMA(1, 0, At, B0); PG8_MMA(1, 1, At, B1); PG8_BAR; PG8_SCHED;
;             PG8_LDB(B0, 1, 0); PG8_LDB(B1, 1, 1); PG8_SCHED; PG8_LDA(At, 1, 0); PG8_STAGE(PG8_SA(0, 1), a2 + hstep, voffA);
;             PG8_WAIT_V(8); PG8_WAIT_L(0); PG8_BAR; PG8_MMA(0, 0, At, B0); PG8_MMA(0, 1, At, B1); PG8_BAR; PG8_SCHED;
;             PG8_LDA(At, 1, 1); PG8_STAGE(PG8_SB(1, 0), b3, voffB); PG8_STAGE(PG8_SB(1, 1), b3 + hstep, voffB); PG8_STAGE(PG8_SA(1, 0), a3, voffA);
;             PG8_WAIT_V(8); PG8_WAIT_L(0); PG8_BAR; PG8_MMA(1, 0, At, B0); PG8_MMA(1, 1, At, B1); PG8_BAR; PG8_SCHED;
	s_add_i32 s93, 0, 0x18000
	s_add_i32 s94, 0, 0x1c000
	v_add_u32_e32 v174, s93, v148
	v_add_u32_e32 v190, s94, v148
	ds_read_b128 v[158:161], v174
	ds_read_b128 v[162:165], v174 offset:1024
	ds_read_b128 v[166:169], v174 offset:2048
	ds_read_b128 v[174:177], v174 offset:3072
	ds_read_b128 v[178:181], v190
	ds_read_b128 v[182:185], v190 offset:1024
	ds_read_b128 v[186:189], v190 offset:2048
	ds_read_b128 v[190:193], v190 offset:3072
	s_add_u32 s68, s68, 0x40000
	s_addc_u32 s69, s69, 0
	s_mov_b32 m0, s77
	ds_read_b128 v[194:197], v152 offset:32768
	ds_read_b128 v[198:201], v152 offset:33792
	ds_read_b128 v[202:205], v152 offset:34816
	ds_read_b128 v[206:209], v152 offset:35840
	ds_read_b128 v[210:213], v152 offset:36864
	ds_read_b128 v[214:217], v152 offset:37888
	ds_read_b128 v[218:221], v152 offset:38912
	ds_read_b128 v[222:225], v152 offset:39936
	global_load_lds_dwordx4 v130, s[68:69]
	s_mov_b32 m0, s78
	s_nop 0
	global_load_lds_dwordx4 v134, s[68:69]
	s_waitcnt vmcnt(8)
	s_waitcnt lgkmcnt(0)
	s_barrier
	v_mfma_f32_16x16x32_bf16 v[126:129], v[158:161], v[194:197], v[126:129]
	v_mfma_f32_16x16x32_bf16 v[118:121], v[166:169], v[194:197], v[118:121]
	v_mfma_f32_16x16x32_bf16 v[110:113], v[158:161], v[202:205], v[110:113]
	v_mfma_f32_16x16x32_bf16 v[102:105], v[166:169], v[202:205], v[102:105]
	v_mfma_f32_16x16x32_bf16 v[94:97], v[158:161], v[210:213], v[94:97]
	v_mfma_f32_16x16x32_bf16 v[86:89], v[166:169], v[210:213], v[86:89]
	v_mfma_f32_16x16x32_bf16 v[78:81], v[158:161], v[218:221], v[78:81]
	v_mfma_f32_16x16x32_bf16 v[70:73], v[166:169], v[218:221], v[70:73]
	v_mfma_f32_16x16x32_bf16 v[126:129], v[162:165], v[198:201], v[126:129]
	v_mfma_f32_16x16x32_bf16 v[118:121], v[174:177], v[198:201], v[118:121]
	v_mfma_f32_16x16x32_bf16 v[110:113], v[162:165], v[206:209], v[110:113]
	v_mfma_f32_16x16x32_bf16 v[102:105], v[174:177], v[206:209], v[102:105]
	v_mfma_f32_16x16x32_bf16 v[94:97], v[162:165], v[214:217], v[94:97]
	v_mfma_f32_16x16x32_bf16 v[86:89], v[174:177], v[214:217], v[86:89]
	v_mfma_f32_16x16x32_bf16 v[78:81], v[162:165], v[222:225], v[78:81]
	v_mfma_f32_16x16x32_bf16 v[70:73], v[174:177], v[222:225], v[70:73]
	v_mfma_f32_16x16x32_bf16 v[122:125], v[178:181], v[194:197], v[122:125]
	v_mfma_f32_16x16x32_bf16 v[114:117], v[186:189], v[194:197], v[114:117]
	v_mfma_f32_16x16x32_bf16 v[106:109], v[178:181], v[202:205], v[106:109]
	v_mfma_f32_16x16x32_bf16 v[98:101], v[186:189], v[202:205], v[98:101]
	v_mfma_f32_16x16x32_bf16 v[90:93], v[178:181], v[210:213], v[90:93]
	v_mfma_f32_16x16x32_bf16 v[82:85], v[186:189], v[210:213], v[82:85]
	v_mfma_f32_16x16x32_bf16 v[74:77], v[178:181], v[218:221], v[74:77]
	v_mfma_f32_16x16x32_bf16 v[66:69], v[186:189], v[218:221], v[66:69]
	v_mfma_f32_16x16x32_bf16 v[122:125], v[182:185], v[198:201], v[122:125]
	v_mfma_f32_16x16x32_bf16 v[114:117], v[190:193], v[198:201], v[114:117]
	v_mfma_f32_16x16x32_bf16 v[106:109], v[182:185], v[206:209], v[106:109]
	v_mfma_f32_16x16x32_bf16 v[98:101], v[190:193], v[206:209], v[98:101]
	v_mfma_f32_16x16x32_bf16 v[90:93], v[182:185], v[214:217], v[90:93]
	v_mfma_f32_16x16x32_bf16 v[82:85], v[190:193], v[214:217], v[82:85]
	v_mfma_f32_16x16x32_bf16 v[74:77], v[182:185], v[222:225], v[74:77]
	v_mfma_f32_16x16x32_bf16 v[66:69], v[190:193], v[222:225], v[66:69]
	s_barrier
	s_add_i32 s68, s93, s6
	s_mov_b32 m0, s68
	ds_read_b128 v[194:197], v152 offset:49152
	ds_read_b128 v[198:201], v152 offset:50176
	ds_read_b128 v[202:205], v152 offset:51200
	ds_read_b128 v[206:209], v152 offset:52224
	ds_read_b128 v[210:213], v152 offset:53248
	ds_read_b128 v[214:217], v152 offset:54272
	ds_read_b128 v[218:221], v152 offset:55296
	ds_read_b128 v[222:225], v152 offset:56320
	global_load_lds_dwordx4 v132, s[98:99]
	s_add_i32 m0, s68, 0x2000
	s_add_u32 s66, s66, 0x40080
	s_addc_u32 s67, s67, 0
	s_add_i32 s68, s94, s6
	global_load_lds_dwordx4 v136, s[98:99]
	s_mov_b32 m0, s68
	s_nop 0
	global_load_lds_dwordx4 v132, s[66:67]
	s_add_i32 m0, s68, 0x2000
	s_nop 0
	global_load_lds_dwordx4 v136, s[66:67]
	s_mov_b32 m0, s79
	s_nop 0
	global_load_lds_dwordx4 v130, s[100:101]
	s_mov_b32 m0, s80
	s_nop 0
	global_load_lds_dwordx4 v134, s[100:101]
	s_waitcnt vmcnt(8)
	s_waitcnt lgkmcnt(0)
	s_barrier
	v_mfma_f32_16x16x32_bf16 v[62:65], v[158:161], v[194:197], v[62:65]
	v_mfma_f32_16x16x32_bf16 v[54:57], v[166:169], v[194:197], v[54:57]
	v_mfma_f32_16x16x32_bf16 v[46:49], v[158:161], v[202:205], v[46:49]
	v_mfma_f32_16x16x32_bf16 v[38:41], v[166:169], v[202:205], v[38:41]
	v_mfma_f32_16x16x32_bf16 v[30:33], v[158:161], v[210:213], v[30:33]
	v_mfma_f32_16x16x32_bf16 v[22:25], v[166:169], v[210:213], v[22:25]
	v_mfma_f32_16x16x32_bf16 v[14:17], v[158:161], v[218:221], v[14:17]
	v_mfma_f32_16x16x32_bf16 v[6:9], v[166:169], v[218:221], v[6:9]
	v_mfma_f32_16x16x32_bf16 v[62:65], v[162:165], v[198:201], v[62:65]
	v_mfma_f32_16x16x32_bf16 v[54:57], v[174:177], v[198:201], v[54:57]
	v_mfma_f32_16x16x32_bf16 v[46:49], v[162:165], v[206:209], v[46:49]
	v_mfma_f32_16x16x32_bf16 v[38:41], v[174:177], v[206:209], v[38:41]
	v_mfma_f32_16x16x32_bf16 v[30:33], v[162:165], v[214:217], v[30:33]
	v_mfma_f32_16x16x32_bf16 v[22:25], v[174:177], v[214:217], v[22:25]
	v_mfma_f32_16x16x32_bf16 v[14:17], v[162:165], v[222:225], v[14:17]
	v_mfma_f32_16x16x32_bf16 v[6:9], v[174:177], v[222:225], v[6:9]
	v_mfma_f32_16x16x32_bf16 v[58:61], v[178:181], v[194:197], v[58:61]
	v_mfma_f32_16x16x32_bf16 v[50:53], v[186:189], v[194:197], v[50:53]
	v_mfma_f32_16x16x32_bf16 v[42:45], v[178:181], v[202:205], v[42:45]
	v_mfma_f32_16x16x32_bf16 v[34:37], v[186:189], v[202:205], v[34:37]
	v_mfma_f32_16x16x32_bf16 v[26:29], v[178:181], v[210:213], v[26:29]
	v_mfma_f32_16x16x32_bf16 v[18:21], v[186:189], v[210:213], v[18:21]
	v_mfma_f32_16x16x32_bf16 v[10:13], v[178:181], v[218:221], v[10:13]
	v_mfma_f32_16x16x32_bf16 v[2:5], v[186:189], v[218:221], v[2:5]
	v_mfma_f32_16x16x32_bf16 v[58:61], v[182:185], v[198:201], v[58:61]
	v_mfma_f32_16x16x32_bf16 v[50:53], v[190:193], v[198:201], v[50:53]
	v_mfma_f32_16x16x32_bf16 v[42:45], v[182:185], v[206:209], v[42:45]
	v_mfma_f32_16x16x32_bf16 v[34:37], v[190:193], v[206:209], v[34:37]
	v_mfma_f32_16x16x32_bf16 v[26:29], v[182:185], v[214:217], v[26:29]
	v_mfma_f32_16x16x32_bf16 v[18:21], v[190:193], v[214:217], v[18:21]
	v_mfma_f32_16x16x32_bf16 v[10:13], v[182:185], v[222:225], v[10:13]
	v_mfma_f32_16x16x32_bf16 v[2:5], v[190:193], v[222:225], v[2:5]
	s_barrier
	s_add_i32 s92, s92, 2
	s_add_u32 s64, s64, 0x100
	s_addc_u32 s65, s65, 0
	s_add_u32 s90, s90, 0x100
	s_addc_u32 s91, s91, 0
	s_cmp_gt_u32 s92, 13
	s_cbranch_scc0 .LBB0_134
	s_and_b64 vcc, exec, s[38:39]
	s_cbranch_vccz .LBB0_137
	s_barrier

; #define PG8_STAGE(bufoff, gbase, voff) do { _Pragma("unroll") for (int _i = 0; _i < 2; ++_i) \
;         __builtin_amdgcn_global_load_lds((const unsigned*)((const char*)(gbase) + (voff)[_i]), (LAS unsigned*)(lds + (bufoff) + ldsw + _i * 8192), 16, 0, 0); } while (0)
; #define PG8_LDA(dst, b, h) do { _Pragma("unroll") for (int m = 0; m < 4; ++m) _Pragma("unroll") for (int k = 0; k < 2; ++k) dst[m][k] = *(const LAS bf16x8*)(lds + PG8_SA(b, h) + aoff + m * 2048 + k * 1024); } while (0)
; #define PG8_LDB(dst, b, h) do { _Pragma("unroll") for (int n = 0; n < 2; ++n) _Pragma("unroll") for (int k = 0; k < 2; ++k) dst[n][k] = *(const LAS bf16x8*)(lds + PG8_SB(b, h) + boff + n * 2048 + k * 1024); } while (0)
; #define PG8_MMA(ai, bj, At, Bt) do { __builtin_amdgcn_s_setprio(1); _Pragma("unroll") for (int m = 0; m < 4; ++m) _Pragma("unroll") for (int n = 0; n < 2; ++n) _Pragma("unroll") for (int k = 0; k < 2; ++k) \
;         acc[ai][bj][m][n] = __builtin_amdgcn_mfma_f32_16x16x32_bf16(Bt[n][k], At[m][k], acc[ai][bj][m][n], 0, 0, 0); __builtin_amdgcn_s_setprio(0); } while (0)
; #define PG8_WAIT_V(n) asm volatile("s_waitcnt vmcnt(" #n ")" ::: "memory")
; #define PG8_BAR __builtin_amdgcn_s_barrier()
; template <class Epi>
; __device__ __forceinline__ void gemm_phase(LAS unsigned char* lds, const Gemm g, const StaticOrder& S, const Epi& E) {
;     ...
;             PG8_LDB(B0, 0, 0); PG8_LDB(B1, 0, 1); PG8_SCHED; PG8_LDA(At, 0, 0); PG8_STAGE(PG8_SA(1, 1), a1 + hstep, voffA);
;             PG8_WAIT_V(8); PG8_WAIT_L(0); PG8_BAR; PG8_MMA(0, 0, At, B0); PG8_MMA(0, 1, At, B1); PG8_BAR; PG8_SCHED;
;             PG8_LDA(At, 0, 1); PG8_STAGE(PG8_SB(0, 0), b2, voffB); PG8_STAGE(PG8_SB(0, 1), b2 + hstep, voffB); PG8_STAGE(PG8_SA(0, 0), a2, voffA);
;             PG8_WAIT_V(8); PG8_WAIT_L(0); PG8_BAR; PG8_MMA(1, 0, At, B0); PG8_MMA(1, 1, At, B1); PG8_BAR; PG8_SCHED;
;             PG8_LDB(B0, 1, 0); PG8_LDB(B1, 1, 1); PG8_SCHED; PG8_LDA(At, 1, 0); PG8_STAGE(PG8_SA(0, 1), a2 + hstep, voffA);
;             PG8_WAIT_V(8); PG8_WAIT_L(0); PG8_BAR; PG8_MMA(0, 0, At, B0); PG8_MMA(0, 1, At, B1); PG8_BAR; PG8_SCHED;
;             PG8_LDA(At, 1, 1); PG8_STAGE(PG8_SB(1, 0), b3, voffB); PG8_STAGE(PG8_SB(1, 1), b3 + hstep, voffB); PG8_STAGE(PG8_SA(1, 0), a3, voffA);
;             PG8_WAIT_V(8); PG8_WAIT_L(0); PG8_BAR; PG8_MMA(1, 0, At, B0); PG8_MMA(1, 1, At, B1); PG8_BAR; PG8_SCHED;
.LBB0_221:
	ds_read_b128 v[130:133], v162
	ds_read_b128 v[134:137], v162 offset:1024
	ds_read_b128 v[154:157], v162 offset:2048
	ds_read_b128 v[166:169], v162 offset:3072
	ds_read_b128 v[174:177], v163
	ds_read_b128 v[178:181], v163 offset:1024
	ds_read_b128 v[182:185], v163 offset:2048
	ds_read_b128 v[186:189], v163 offset:3072
	s_add_u32 s48, s46, 0xfff50080
	s_addc_u32 s49, s47, -1
	s_cmp_eq_u32 s84, 40
	s_cselect_b32 s51, s5, s49
	s_cselect_b32 s50, s4, s48
	s_cselect_b32 s49, s45, s83
	s_cselect_b32 s48, s44, s82
	s_add_i32 m0, s59, 0xc000
	ds_read_b128 v[190:193], v164
	ds_read_b128 v[194:197], v164 offset:1024
	ds_read_b128 v[198:201], v164 offset:2048
	ds_read_b128 v[202:205], v164 offset:3072
	ds_read_b128 v[206:209], v164 offset:4096
	ds_read_b128 v[210:213], v164 offset:5120
	ds_read_b128 v[214:217], v164 offset:6144
	ds_read_b128 v[218:221], v164 offset:7168
	global_load_lds_dwordx4 v146, s[46:47]
	s_add_i32 m0, s59, 0xe000
	s_nop 0
	global_load_lds_dwordx4 v148, s[46:47]
	s_waitcnt vmcnt(8)
	s_waitcnt lgkmcnt(0)
	s_barrier
	v_mfma_f32_16x16x32_bf16 v[126:129], v[130:133], v[190:193], v[126:129]
	v_mfma_f32_16x16x32_bf16 v[122:125], v[154:157], v[190:193], v[122:125]
	v_mfma_f32_16x16x32_bf16 v[110:113], v[130:133], v[198:201], v[110:113]
	v_mfma_f32_16x16x32_bf16 v[106:109], v[154:157], v[198:201], v[106:109]
	v_mfma_f32_16x16x32_bf16 v[94:97], v[130:133], v[206:209], v[94:97]
	v_mfma_f32_16x16x32_bf16 v[90:93], v[154:157], v[206:209], v[90:93]
	v_mfma_f32_16x16x32_bf16 v[78:81], v[130:133], v[214:217], v[78:81]
	v_mfma_f32_16x16x32_bf16 v[74:77], v[154:157], v[214:217], v[74:77]
	v_mfma_f32_16x16x32_bf16 v[126:129], v[134:137], v[194:197], v[126:129]
	v_mfma_f32_16x16x32_bf16 v[122:125], v[166:169], v[194:197], v[122:125]
	v_mfma_f32_16x16x32_bf16 v[110:113], v[134:137], v[202:205], v[110:113]
	v_mfma_f32_16x16x32_bf16 v[106:109], v[166:169], v[202:205], v[106:109]
	v_mfma_f32_16x16x32_bf16 v[94:97], v[134:137], v[210:213], v[94:97]
	v_mfma_f32_16x16x32_bf16 v[90:93], v[166:169], v[210:213], v[90:93]
	v_mfma_f32_16x16x32_bf16 v[78:81], v[134:137], v[218:221], v[78:81]
	v_mfma_f32_16x16x32_bf16 v[74:77], v[166:169], v[218:221], v[74:77]
	v_mfma_f32_16x16x32_bf16 v[118:121], v[174:177], v[190:193], v[118:121]
	v_mfma_f32_16x16x32_bf16 v[114:117], v[182:185], v[190:193], v[114:117]
	v_mfma_f32_16x16x32_bf16 v[102:105], v[174:177], v[198:201], v[102:105]
	v_mfma_f32_16x16x32_bf16 v[98:101], v[182:185], v[198:201], v[98:101]
	v_mfma_f32_16x16x32_bf16 v[86:89], v[174:177], v[206:209], v[86:89]
	v_mfma_f32_16x16x32_bf16 v[82:85], v[182:185], v[206:209], v[82:85]
	v_mfma_f32_16x16x32_bf16 v[70:73], v[174:177], v[214:217], v[70:73]
	v_mfma_f32_16x16x32_bf16 v[66:69], v[182:185], v[214:217], v[66:69]
	v_mfma_f32_16x16x32_bf16 v[118:121], v[178:181], v[194:197], v[118:121]
	v_mfma_f32_16x16x32_bf16 v[114:117], v[186:189], v[194:197], v[114:117]
	v_mfma_f32_16x16x32_bf16 v[102:105], v[178:181], v[202:205], v[102:105]
	v_mfma_f32_16x16x32_bf16 v[98:101], v[186:189], v[202:205], v[98:101]
	v_mfma_f32_16x16x32_bf16 v[86:89], v[178:181], v[210:213], v[86:89]
	v_mfma_f32_16x16x32_bf16 v[82:85], v[186:189], v[210:213], v[82:85]
	v_mfma_f32_16x16x32_bf16 v[70:73], v[178:181], v[218:221], v[70:73]
	v_mfma_f32_16x16x32_bf16 v[66:69], v[186:189], v[218:221], v[66:69]
	s_barrier
	s_add_u32 s98, s48, s38
	s_addc_u32 s99, s49, s39
	s_add_u32 s100, s50, s38
	s_addc_u32 s101, s51, s39
	s_add_i32 s85, s76, s58
	s_mov_b32 m0, s85
	ds_read_b128 v[190:193], v164 offset:16384
	ds_read_b128 v[194:197], v164 offset:17408
	ds_read_b128 v[198:201], v164 offset:18432
	ds_read_b128 v[202:205], v164 offset:19456
	ds_read_b128 v[206:209], v164 offset:20480
	ds_read_b128 v[210:213], v164 offset:21504
	ds_read_b128 v[214:217], v164 offset:22528
	ds_read_b128 v[218:221], v164 offset:23552
	global_load_lds_dwordx4 v140, s[48:49]
	s_add_i32 m0, s85, 0x2000
	s_add_u32 s86, s48, 0xb0000
	s_addc_u32 s87, s49, 0
	s_add_i32 s85, s77, s58
	global_load_lds_dwordx4 v144, s[48:49]
	s_mov_b32 m0, s85
	s_nop 0
	global_load_lds_dwordx4 v140, s[86:87]
	s_add_i32 m0, s85, 0x2000
	s_nop 0
	global_load_lds_dwordx4 v144, s[86:87]
	s_mov_b32 m0, s59
	s_nop 0
	global_load_lds_dwordx4 v138, s[50:51]
	s_mov_b32 m0, s60
	s_nop 0
	global_load_lds_dwordx4 v142, s[50:51]
	s_waitcnt vmcnt(8)
	s_waitcnt lgkmcnt(0)
	s_barrier
	v_mfma_f32_16x16x32_bf16 v[62:65], v[130:133], v[190:193], v[62:65]
	v_mfma_f32_16x16x32_bf16 v[58:61], v[154:157], v[190:193], v[58:61]
	v_mfma_f32_16x16x32_bf16 v[46:49], v[130:133], v[198:201], v[46:49]
	v_mfma_f32_16x16x32_bf16 v[42:45], v[154:157], v[198:201], v[42:45]
	v_mfma_f32_16x16x32_bf16 v[30:33], v[130:133], v[206:209], v[30:33]
	v_mfma_f32_16x16x32_bf16 v[26:29], v[154:157], v[206:209], v[26:29]
	v_mfma_f32_16x16x32_bf16 v[14:17], v[130:133], v[214:217], v[14:17]
	v_mfma_f32_16x16x32_bf16 v[10:13], v[154:157], v[214:217], v[10:13]
	v_mfma_f32_16x16x32_bf16 v[62:65], v[134:137], v[194:197], v[62:65]
	v_mfma_f32_16x16x32_bf16 v[58:61], v[166:169], v[194:197], v[58:61]
	v_mfma_f32_16x16x32_bf16 v[46:49], v[134:137], v[202:205], v[46:49]
	v_mfma_f32_16x16x32_bf16 v[42:45], v[166:169], v[202:205], v[42:45]
	v_mfma_f32_16x16x32_bf16 v[30:33], v[134:137], v[210:213], v[30:33]
	v_mfma_f32_16x16x32_bf16 v[26:29], v[166:169], v[210:213], v[26:29]
	v_mfma_f32_16x16x32_bf16 v[14:17], v[134:137], v[218:221], v[14:17]
	v_mfma_f32_16x16x32_bf16 v[10:13], v[166:169], v[218:221], v[10:13]
	v_mfma_f32_16x16x32_bf16 v[54:57], v[174:177], v[190:193], v[54:57]
	v_mfma_f32_16x16x32_bf16 v[50:53], v[182:185], v[190:193], v[50:53]
	v_mfma_f32_16x16x32_bf16 v[38:41], v[174:177], v[198:201], v[38:41]
	v_mfma_f32_16x16x32_bf16 v[34:37], v[182:185], v[198:201], v[34:37]
	v_mfma_f32_16x16x32_bf16 v[22:25], v[174:177], v[206:209], v[22:25]
	v_mfma_f32_16x16x32_bf16 v[18:21], v[182:185], v[206:209], v[18:21]
	v_mfma_f32_16x16x32_bf16 v[6:9], v[174:177], v[214:217], v[6:9]
	v_mfma_f32_16x16x32_bf16 v[2:5], v[182:185], v[214:217], v[2:5]
	v_mfma_f32_16x16x32_bf16 v[54:57], v[178:181], v[194:197], v[54:57]
	v_mfma_f32_16x16x32_bf16 v[50:53], v[186:189], v[194:197], v[50:53]
	v_mfma_f32_16x16x32_bf16 v[38:41], v[178:181], v[202:205], v[38:41]
	v_mfma_f32_16x16x32_bf16 v[34:37], v[186:189], v[202:205], v[34:37]
	v_mfma_f32_16x16x32_bf16 v[22:25], v[178:181], v[210:213], v[22:25]
	v_mfma_f32_16x16x32_bf16 v[18:21], v[186:189], v[210:213], v[18:21]
	v_mfma_f32_16x16x32_bf16 v[6:9], v[178:181], v[218:221], v[6:9]
	v_mfma_f32_16x16x32_bf16 v[2:5], v[186:189], v[218:221], v[2:5]
	s_barrier
; #define PG8_STAGE(bufoff, gbase, voff) do { _Pragma("unroll") for (int _i = 0; _i < 2; ++_i) \
;         __builtin_amdgcn_global_load_lds((const unsigned*)((const char*)(gbase) + (voff)[_i]), (LAS unsigned*)(lds + (bufoff) + ldsw + _i * 8192), 16, 0, 0); } while (0)
; #define PG8_LDA(dst, b, h) do { _Pragma("unroll") for (int m = 0; m < 4; ++m) _Pragma("unroll") for (int k = 0; k < 2; ++k) dst[m][k] = *(const LAS bf16x8*)(lds + PG8_SA(b, h) + aoff + m * 2048 + k * 1024); } while (0)
; #define PG8_LDB(dst, b, h) do { _Pragma("unroll") for (int n = 0; n < 2; ++n) _Pragma("unroll") for (int k = 0; k < 2; ++k) dst[n][k] = *(const LAS bf16x8*)(lds + PG8_SB(b, h) + boff + n * 2048 + k * 1024); } while (0)
; #define PG8_MMA(ai, bj, At, Bt) do { __builtin_amdgcn_s_setprio(1); _Pragma("unroll") for (int m = 0; m < 4; ++m) _Pragma("unroll") for (int n = 0; n < 2; ++n) _Pragma("unroll") for (int k = 0; k < 2; ++k) \
;         acc[ai][bj][m][n] = __builtin_amdgcn_mfma_f32_16x16x32_bf16(Bt[n][k], At[m][k], acc[ai][bj][m][n], 0, 0, 0); __builtin_amdgcn_s_setprio(0); } while (0)
; #define PG8_WAIT_V(n) asm volatile("s_waitcnt vmcnt(" #n ")" ::: "memory")
; #define PG8_BAR __builtin_amdgcn_s_barrier()
; template <class Epi>
; __device__ __forceinline__ void gemm_phase(LAS unsigned char* lds, const Gemm g, const StaticOrder& S, const Epi& E) {
;     ...
;             PG8_LDB(B0, 0, 0); PG8_LDB(B1, 0, 1); PG8_SCHED; PG8_LDA(At, 0, 0); PG8_STAGE(PG8_SA(1, 1), a1 + hstep, voffA);
;             PG8_WAIT_V(8); PG8_WAIT_L(0); PG8_BAR; PG8_MMA(0, 0, At, B0); PG8_MMA(0, 1, At, B1); PG8_BAR; PG8_SCHED;
;             PG8_LDA(At, 0, 1); PG8_STAGE(PG8_SB(0, 0), b2, voffB); PG8_STAGE(PG8_SB(0, 1), b2 + hstep, voffB); PG8_STAGE(PG8_SA(0, 0), a2, voffA);
;             PG8_WAIT_V(8); PG8_WAIT_L(0); PG8_BAR; PG8_MMA(1, 0, At, B0); PG8_MMA(1, 1, At, B1); PG8_BAR; PG8_SCHED;
;             PG8_LDB(B0, 1, 0); PG8_LDB(B1, 1, 1); PG8_SCHED; PG8_LDA(At, 1, 0); PG8_STAGE(PG8_SA(0, 1), a2 + hstep, voffA);
;             PG8_WAIT_V(8); PG8_WAIT_L(0); PG8_BAR; PG8_MMA(0, 0, At, B0); PG8_MMA(0, 1, At, B1); PG8_BAR; PG8_SCHED;
;             PG8_LDA(At, 1, 1); PG8_STAGE(PG8_SB(1, 0), b3, voffB); PG8_STAGE(PG8_SB(1, 1), b3 + hstep, voffB); PG8_STAGE(PG8_SA(1, 0), a3, voffA);
;             PG8_WAIT_V(8); PG8_WAIT_L(0); PG8_BAR; PG8_MMA(1, 0, At, B0); PG8_MMA(1, 1, At, B1); PG8_BAR; PG8_SCHED;
	s_add_i32 s85, 0, 0x18000
	s_add_i32 s86, 0, 0x1c000
	v_add_u32_e32 v166, s85, v160
	v_add_u32_e32 v186, s86, v160
	ds_read_b128 v[130:133], v166
	ds_read_b128 v[134:137], v166 offset:1024
	ds_read_b128 v[154:157], v166 offset:2048
	ds_read_b128 v[166:169], v166 offset:3072
	ds_read_b128 v[174:177], v186
	ds_read_b128 v[178:181], v186 offset:1024
	ds_read_b128 v[182:185], v186 offset:2048
	ds_read_b128 v[186:189], v186 offset:3072
	s_add_u32 s50, s50, 0xb0000
	s_addc_u32 s51, s51, 0
	s_mov_b32 m0, s61
	ds_read_b128 v[190:193], v164 offset:32768
	ds_read_b128 v[194:197], v164 offset:33792
	ds_read_b128 v[198:201], v164 offset:34816
	ds_read_b128 v[202:205], v164 offset:35840
	ds_read_b128 v[206:209], v164 offset:36864
	ds_read_b128 v[210:213], v164 offset:37888
	ds_read_b128 v[214:217], v164 offset:38912
	ds_read_b128 v[218:221], v164 offset:39936
	global_load_lds_dwordx4 v138, s[50:51]
	s_mov_b32 m0, s62
	s_nop 0
	global_load_lds_dwordx4 v142, s[50:51]
	s_waitcnt vmcnt(8)
	s_waitcnt lgkmcnt(0)
	s_barrier
	v_mfma_f32_16x16x32_bf16 v[126:129], v[130:133], v[190:193], v[126:129]
	v_mfma_f32_16x16x32_bf16 v[122:125], v[154:157], v[190:193], v[122:125]
	v_mfma_f32_16x16x32_bf16 v[110:113], v[130:133], v[198:201], v[110:113]
	v_mfma_f32_16x16x32_bf16 v[106:109], v[154:157], v[198:201], v[106:109]
	v_mfma_f32_16x16x32_bf16 v[94:97], v[130:133], v[206:209], v[94:97]
	v_mfma_f32_16x16x32_bf16 v[90:93], v[154:157], v[206:209], v[90:93]
	v_mfma_f32_16x16x32_bf16 v[78:81], v[130:133], v[214:217], v[78:81]
	v_mfma_f32_16x16x32_bf16 v[74:77], v[154:157], v[214:217], v[74:77]
	v_mfma_f32_16x16x32_bf16 v[126:129], v[134:137], v[194:197], v[126:129]
	v_mfma_f32_16x16x32_bf16 v[122:125], v[166:169], v[194:197], v[122:125]
	v_mfma_f32_16x16x32_bf16 v[110:113], v[134:137], v[202:205], v[110:113]
	v_mfma_f32_16x16x32_bf16 v[106:109], v[166:169], v[202:205], v[106:109]
	v_mfma_f32_16x16x32_bf16 v[94:97], v[134:137], v[210:213], v[94:97]
	v_mfma_f32_16x16x32_bf16 v[90:93], v[166:169], v[210:213], v[90:93]
	v_mfma_f32_16x16x32_bf16 v[78:81], v[134:137], v[218:221], v[78:81]
	v_mfma_f32_16x16x32_bf16 v[74:77], v[166:169], v[218:221], v[74:77]
	v_mfma_f32_16x16x32_bf16 v[118:121], v[174:177], v[190:193], v[118:121]
	v_mfma_f32_16x16x32_bf16 v[114:117], v[182:185], v[190:193], v[114:117]
	v_mfma_f32_16x16x32_bf16 v[102:105], v[174:177], v[198:201], v[102:105]
	v_mfma_f32_16x16x32_bf16 v[98:101], v[182:185], v[198:201], v[98:101]
	v_mfma_f32_16x16x32_bf16 v[86:89], v[174:177], v[206:209], v[86:89]
	v_mfma_f32_16x16x32_bf16 v[82:85], v[182:185], v[206:209], v[82:85]
	v_mfma_f32_16x16x32_bf16 v[70:73], v[174:177], v[214:217], v[70:73]
	v_mfma_f32_16x16x32_bf16 v[66:69], v[182:185], v[214:217], v[66:69]
	v_mfma_f32_16x16x32_bf16 v[118:121], v[178:181], v[194:197], v[118:121]
	v_mfma_f32_16x16x32_bf16 v[114:117], v[186:189], v[194:197], v[114:117]
	v_mfma_f32_16x16x32_bf16 v[102:105], v[178:181], v[202:205], v[102:105]
	v_mfma_f32_16x16x32_bf16 v[98:101], v[186:189], v[202:205], v[98:101]
	v_mfma_f32_16x16x32_bf16 v[86:89], v[178:181], v[210:213], v[86:89]
	v_mfma_f32_16x16x32_bf16 v[82:85], v[186:189], v[210:213], v[82:85]
	v_mfma_f32_16x16x32_bf16 v[70:73], v[178:181], v[218:221], v[70:73]
	v_mfma_f32_16x16x32_bf16 v[66:69], v[186:189], v[218:221], v[66:69]
	s_barrier
	s_add_i32 s50, s85, s58
	s_mov_b32 m0, s50
	ds_read_b128 v[190:193], v164 offset:49152
	ds_read_b128 v[194:197], v164 offset:50176
	ds_read_b128 v[198:201], v164 offset:51200
	ds_read_b128 v[202:205], v164 offset:52224
	ds_read_b128 v[206:209], v164 offset:53248
	ds_read_b128 v[210:213], v164 offset:54272
	ds_read_b128 v[214:217], v164 offset:55296
	ds_read_b128 v[218:221], v164 offset:56320
	global_load_lds_dwordx4 v140, s[98:99]
	s_add_i32 m0, s50, 0x2000
	s_add_u32 s48, s48, 0xb0080
	s_addc_u32 s49, s49, 0
	s_add_i32 s50, s86, s58
	global_load_lds_dwordx4 v144, s[98:99]
	s_mov_b32 m0, s50
	s_nop 0
	global_load_lds_dwordx4 v140, s[48:49]
	s_add_i32 m0, s50, 0x2000
	s_nop 0
	global_load_lds_dwordx4 v144, s[48:49]
	s_mov_b32 m0, s64
	s_nop 0
	global_load_lds_dwordx4 v138, s[100:101]
	s_mov_b32 m0, s65
	s_nop 0
	global_load_lds_dwordx4 v142, s[100:101]
	s_waitcnt vmcnt(8)
	s_waitcnt lgkmcnt(0)
	s_barrier
	v_mfma_f32_16x16x32_bf16 v[62:65], v[130:133], v[190:193], v[62:65]
	v_mfma_f32_16x16x32_bf16 v[58:61], v[154:157], v[190:193], v[58:61]
	v_mfma_f32_16x16x32_bf16 v[46:49], v[130:133], v[198:201], v[46:49]
	v_mfma_f32_16x16x32_bf16 v[42:45], v[154:157], v[198:201], v[42:45]
	v_mfma_f32_16x16x32_bf16 v[30:33], v[130:133], v[206:209], v[30:33]
	v_mfma_f32_16x16x32_bf16 v[26:29], v[154:157], v[206:209], v[26:29]
	v_mfma_f32_16x16x32_bf16 v[14:17], v[130:133], v[214:217], v[14:17]
	v_mfma_f32_16x16x32_bf16 v[10:13], v[154:157], v[214:217], v[10:13]
	v_mfma_f32_16x16x32_bf16 v[62:65], v[134:137], v[194:197], v[62:65]
	v_mfma_f32_16x16x32_bf16 v[58:61], v[166:169], v[194:197], v[58:61]
	v_mfma_f32_16x16x32_bf16 v[46:49], v[134:137], v[202:205], v[46:49]
	v_mfma_f32_16x16x32_bf16 v[42:45], v[166:169], v[202:205], v[42:45]
	v_mfma_f32_16x16x32_bf16 v[30:33], v[134:137], v[210:213], v[30:33]
	v_mfma_f32_16x16x32_bf16 v[26:29], v[166:169], v[210:213], v[26:29]
	v_mfma_f32_16x16x32_bf16 v[14:17], v[134:137], v[218:221], v[14:17]
	v_mfma_f32_16x16x32_bf16 v[10:13], v[166:169], v[218:221], v[10:13]
	v_mfma_f32_16x16x32_bf16 v[54:57], v[174:177], v[190:193], v[54:57]
	v_mfma_f32_16x16x32_bf16 v[50:53], v[182:185], v[190:193], v[50:53]
	v_mfma_f32_16x16x32_bf16 v[38:41], v[174:177], v[198:201], v[38:41]
	v_mfma_f32_16x16x32_bf16 v[34:37], v[182:185], v[198:201], v[34:37]
	v_mfma_f32_16x16x32_bf16 v[22:25], v[174:177], v[206:209], v[22:25]
	v_mfma_f32_16x16x32_bf16 v[18:21], v[182:185], v[206:209], v[18:21]
	v_mfma_f32_16x16x32_bf16 v[6:9], v[174:177], v[214:217], v[6:9]
	v_mfma_f32_16x16x32_bf16 v[2:5], v[182:185], v[214:217], v[2:5]
	v_mfma_f32_16x16x32_bf16 v[54:57], v[178:181], v[194:197], v[54:57]
	v_mfma_f32_16x16x32_bf16 v[50:53], v[186:189], v[194:197], v[50:53]
	v_mfma_f32_16x16x32_bf16 v[38:41], v[178:181], v[202:205], v[38:41]
	v_mfma_f32_16x16x32_bf16 v[34:37], v[186:189], v[202:205], v[34:37]
	v_mfma_f32_16x16x32_bf16 v[22:25], v[178:181], v[210:213], v[22:25]
	v_mfma_f32_16x16x32_bf16 v[18:21], v[186:189], v[210:213], v[18:21]
	v_mfma_f32_16x16x32_bf16 v[6:9], v[178:181], v[218:221], v[6:9]
	v_mfma_f32_16x16x32_bf16 v[2:5], v[186:189], v[218:221], v[2:5]
	s_barrier
	s_add_i32 s84, s84, 2
	s_add_u32 s46, s46, 0x100
	s_addc_u32 s47, s47, 0
	s_add_u32 s82, s82, 0x100
	s_addc_u32 s83, s83, 0
	s_cmp_gt_u32 s84, 41
	s_cbranch_scc0 .LBB0_221
	s_and_b64 vcc, exec, s[42:43]
	s_cbranch_vccz .LBB0_224
	s_barrier

; #define PG8_STAGE(bufoff, gbase, voff) do { _Pragma("unroll") for (int _i = 0; _i < 2; ++_i) \
;         __builtin_amdgcn_global_load_lds((const unsigned*)((const char*)(gbase) + (voff)[_i]), (LAS unsigned*)(lds + (bufoff) + ldsw + _i * 8192), 16, 0, 0); } while (0)
; #define PG8_LDA(dst, b, h) do { _Pragma("unroll") for (int m = 0; m < 4; ++m) _Pragma("unroll") for (int k = 0; k < 2; ++k) dst[m][k] = *(const LAS bf16x8*)(lds + PG8_SA(b, h) + aoff + m * 2048 + k * 1024); } while (0)
; #define PG8_LDB(dst, b, h) do { _Pragma("unroll") for (int n = 0; n < 2; ++n) _Pragma("unroll") for (int k = 0; k < 2; ++k) dst[n][k] = *(const LAS bf16x8*)(lds + PG8_SB(b, h) + boff + n * 2048 + k * 1024); } while (0)
; #define PG8_MMA(ai, bj, At, Bt) do { __builtin_amdgcn_s_setprio(1); _Pragma("unroll") for (int m = 0; m < 4; ++m) _Pragma("unroll") for (int n = 0; n < 2; ++n) _Pragma("unroll") for (int k = 0; k < 2; ++k) \
;         acc[ai][bj][m][n] = __builtin_amdgcn_mfma_f32_16x16x32_bf16(Bt[n][k], At[m][k], acc[ai][bj][m][n], 0, 0, 0); __builtin_amdgcn_s_setprio(0); } while (0)
; #define PG8_WAIT_V(n) asm volatile("s_waitcnt vmcnt(" #n ")" ::: "memory")
; #define PG8_BAR __builtin_amdgcn_s_barrier()
; template <class Epi>
; __device__ __forceinline__ void gemm_phase(LAS unsigned char* lds, const Gemm g, const StaticOrder& S, const Epi& E) {
;     ...
;             PG8_LDB(B0, 0, 0); PG8_LDB(B1, 0, 1); PG8_SCHED; PG8_LDA(At, 0, 0); PG8_STAGE(PG8_SA(1, 1), a1 + hstep, voffA);
;             PG8_WAIT_V(8); PG8_WAIT_L(0); PG8_BAR; PG8_MMA(0, 0, At, B0); PG8_MMA(0, 1, At, B1); PG8_BAR; PG8_SCHED;
;             PG8_LDA(At, 0, 1); PG8_STAGE(PG8_SB(0, 0), b2, voffB); PG8_STAGE(PG8_SB(0, 1), b2 + hstep, voffB); PG8_STAGE(PG8_SA(0, 0), a2, voffA);
;             PG8_WAIT_V(8); PG8_WAIT_L(0); PG8_BAR; PG8_MMA(1, 0, At, B0); PG8_MMA(1, 1, At, B1); PG8_BAR; PG8_SCHED;
;             PG8_LDB(B0, 1, 0); PG8_LDB(B1, 1, 1); PG8_SCHED; PG8_LDA(At, 1, 0); PG8_STAGE(PG8_SA(0, 1), a2 + hstep, voffA);
;             PG8_WAIT_V(8); PG8_WAIT_L(0); PG8_BAR; PG8_MMA(0, 0, At, B0); PG8_MMA(0, 1, At, B1); PG8_BAR; PG8_SCHED;
;             PG8_LDA(At, 1, 1); PG8_STAGE(PG8_SB(1, 0), b3, voffB); PG8_STAGE(PG8_SB(1, 1), b3 + hstep, voffB); PG8_STAGE(PG8_SA(1, 0), a3, voffA);
;             PG8_WAIT_V(8); PG8_WAIT_L(0); PG8_BAR; PG8_MMA(1, 0, At, B0); PG8_MMA(1, 1, At, B1); PG8_BAR; PG8_SCHED;
.LBB0_322:
	ds_read_b128 v[130:133], v191
	ds_read_b128 v[134:137], v191 offset:1024
	ds_read_b128 v[138:141], v191 offset:2048
	ds_read_b128 v[142:145], v191 offset:3072
	ds_read_b128 v[166:169], v193
	ds_read_b128 v[172:175], v193 offset:1024
	ds_read_b128 v[176:179], v193 offset:2048
	ds_read_b128 v[180:183], v193 offset:3072
	s_add_u32 s76, s88, 0xfffc0080
	s_addc_u32 s77, s89, -1
	s_cmp_eq_u32 vcc_hi, 12
	s_cselect_b32 s93, s1, s77
	s_cselect_b32 s92, s7, s76
	s_cselect_b32 s91, s9, vcc_lo
	s_cselect_b32 s90, s46, s81
	s_add_i32 m0, s96, 0xc000
	ds_read_b128 v[200:203], v194
	ds_read_b128 v[204:207], v194 offset:1024
	ds_read_b128 v[208:211], v194 offset:2048
	ds_read_b128 v[212:215], v194 offset:3072
	ds_read_b128 v[216:219], v194 offset:4096
	ds_read_b128 v[220:223], v194 offset:5120
	ds_read_b128 v[224:227], v194 offset:6144
	ds_read_b128 v[228:231], v194 offset:7168
	global_load_lds_dwordx4 v158, s[88:89]
	s_add_i32 m0, s96, 0xe000
	s_nop 0
	global_load_lds_dwordx4 v160, s[88:89]
	s_waitcnt vmcnt(8)
	s_waitcnt lgkmcnt(0)
	s_barrier
	v_mfma_f32_16x16x32_bf16 v[126:129], v[130:133], v[200:203], v[126:129]
	v_mfma_f32_16x16x32_bf16 v[122:125], v[138:141], v[200:203], v[122:125]
	v_mfma_f32_16x16x32_bf16 v[110:113], v[130:133], v[208:211], v[110:113]
	v_mfma_f32_16x16x32_bf16 v[106:109], v[138:141], v[208:211], v[106:109]
	v_mfma_f32_16x16x32_bf16 v[94:97], v[130:133], v[216:219], v[94:97]
	v_mfma_f32_16x16x32_bf16 v[90:93], v[138:141], v[216:219], v[90:93]
	v_mfma_f32_16x16x32_bf16 v[78:81], v[130:133], v[224:227], v[78:81]
	v_mfma_f32_16x16x32_bf16 v[74:77], v[138:141], v[224:227], v[74:77]
	v_mfma_f32_16x16x32_bf16 v[126:129], v[134:137], v[204:207], v[126:129]
	v_mfma_f32_16x16x32_bf16 v[122:125], v[142:145], v[204:207], v[122:125]
	v_mfma_f32_16x16x32_bf16 v[110:113], v[134:137], v[212:215], v[110:113]
	v_mfma_f32_16x16x32_bf16 v[106:109], v[142:145], v[212:215], v[106:109]
	v_mfma_f32_16x16x32_bf16 v[94:97], v[134:137], v[220:223], v[94:97]
	v_mfma_f32_16x16x32_bf16 v[90:93], v[142:145], v[220:223], v[90:93]
	v_mfma_f32_16x16x32_bf16 v[78:81], v[134:137], v[228:231], v[78:81]
	v_mfma_f32_16x16x32_bf16 v[74:77], v[142:145], v[228:231], v[74:77]
	v_mfma_f32_16x16x32_bf16 v[118:121], v[166:169], v[200:203], v[118:121]
	v_mfma_f32_16x16x32_bf16 v[114:117], v[176:179], v[200:203], v[114:117]
	v_mfma_f32_16x16x32_bf16 v[102:105], v[166:169], v[208:211], v[102:105]
	v_mfma_f32_16x16x32_bf16 v[98:101], v[176:179], v[208:211], v[98:101]
	v_mfma_f32_16x16x32_bf16 v[86:89], v[166:169], v[216:219], v[86:89]
	v_mfma_f32_16x16x32_bf16 v[82:85], v[176:179], v[216:219], v[82:85]
	v_mfma_f32_16x16x32_bf16 v[70:73], v[166:169], v[224:227], v[70:73]
	v_mfma_f32_16x16x32_bf16 v[66:69], v[176:179], v[224:227], v[66:69]
	v_mfma_f32_16x16x32_bf16 v[118:121], v[172:175], v[204:207], v[118:121]
	v_mfma_f32_16x16x32_bf16 v[114:117], v[180:183], v[204:207], v[114:117]
	v_mfma_f32_16x16x32_bf16 v[102:105], v[172:175], v[212:215], v[102:105]
	v_mfma_f32_16x16x32_bf16 v[98:101], v[180:183], v[212:215], v[98:101]
	v_mfma_f32_16x16x32_bf16 v[86:89], v[172:175], v[220:223], v[86:89]
	v_mfma_f32_16x16x32_bf16 v[82:85], v[180:183], v[220:223], v[82:85]
	v_mfma_f32_16x16x32_bf16 v[70:73], v[172:175], v[228:231], v[70:73]
	v_mfma_f32_16x16x32_bf16 v[66:69], v[180:183], v[228:231], v[66:69]
	s_barrier
	s_add_u32 s98, s90, s50
	s_addc_u32 s99, s91, s51
	s_add_u32 s100, s92, s50
	s_addc_u32 s101, s93, s51
	s_add_i32 s76, s42, s44
	s_mov_b32 m0, s76
	ds_read_b128 v[200:203], v194 offset:16384
	ds_read_b128 v[204:207], v194 offset:17408
	ds_read_b128 v[208:211], v194 offset:18432
	ds_read_b128 v[212:215], v194 offset:19456
	ds_read_b128 v[216:219], v194 offset:20480
	ds_read_b128 v[220:223], v194 offset:21504
	ds_read_b128 v[224:227], v194 offset:22528
	ds_read_b128 v[228:231], v194 offset:23552
	global_load_lds_dwordx4 v148, s[90:91]
	s_add_i32 m0, s76, 0x2000
	s_add_u32 s76, s90, 0x40000
	s_addc_u32 s77, s91, 0
	s_add_i32 s60, s43, s44
	global_load_lds_dwordx4 v152, s[90:91]
	s_mov_b32 m0, s60
	s_nop 0
	global_load_lds_dwordx4 v148, s[76:77]
	s_add_i32 m0, s60, 0x2000
	s_nop 0
	global_load_lds_dwordx4 v152, s[76:77]
	s_mov_b32 m0, s96
	s_nop 0
	global_load_lds_dwordx4 v146, s[92:93]
	s_mov_b32 m0, s97
	s_nop 0
	global_load_lds_dwordx4 v150, s[92:93]
	s_waitcnt vmcnt(8)
	s_waitcnt lgkmcnt(0)
	s_barrier
	v_mfma_f32_16x16x32_bf16 v[62:65], v[130:133], v[200:203], v[62:65]
	v_mfma_f32_16x16x32_bf16 v[58:61], v[138:141], v[200:203], v[58:61]
	v_mfma_f32_16x16x32_bf16 v[46:49], v[130:133], v[208:211], v[46:49]
	v_mfma_f32_16x16x32_bf16 v[42:45], v[138:141], v[208:211], v[42:45]
	v_mfma_f32_16x16x32_bf16 v[30:33], v[130:133], v[216:219], v[30:33]
	v_mfma_f32_16x16x32_bf16 v[26:29], v[138:141], v[216:219], v[26:29]
	v_mfma_f32_16x16x32_bf16 v[14:17], v[130:133], v[224:227], v[14:17]
	v_mfma_f32_16x16x32_bf16 v[10:13], v[138:141], v[224:227], v[10:13]
	v_mfma_f32_16x16x32_bf16 v[62:65], v[134:137], v[204:207], v[62:65]
	v_mfma_f32_16x16x32_bf16 v[58:61], v[142:145], v[204:207], v[58:61]
	v_mfma_f32_16x16x32_bf16 v[46:49], v[134:137], v[212:215], v[46:49]
	v_mfma_f32_16x16x32_bf16 v[42:45], v[142:145], v[212:215], v[42:45]
	v_mfma_f32_16x16x32_bf16 v[30:33], v[134:137], v[220:223], v[30:33]
	v_mfma_f32_16x16x32_bf16 v[26:29], v[142:145], v[220:223], v[26:29]
	v_mfma_f32_16x16x32_bf16 v[14:17], v[134:137], v[228:231], v[14:17]
	v_mfma_f32_16x16x32_bf16 v[10:13], v[142:145], v[228:231], v[10:13]
	v_mfma_f32_16x16x32_bf16 v[54:57], v[166:169], v[200:203], v[54:57]
	v_mfma_f32_16x16x32_bf16 v[50:53], v[176:179], v[200:203], v[50:53]
	v_mfma_f32_16x16x32_bf16 v[38:41], v[166:169], v[208:211], v[38:41]
	v_mfma_f32_16x16x32_bf16 v[34:37], v[176:179], v[208:211], v[34:37]
	v_mfma_f32_16x16x32_bf16 v[22:25], v[166:169], v[216:219], v[22:25]
	v_mfma_f32_16x16x32_bf16 v[18:21], v[176:179], v[216:219], v[18:21]
	v_mfma_f32_16x16x32_bf16 v[6:9], v[166:169], v[224:227], v[6:9]
	v_mfma_f32_16x16x32_bf16 v[2:5], v[176:179], v[224:227], v[2:5]
	v_mfma_f32_16x16x32_bf16 v[54:57], v[172:175], v[204:207], v[54:57]
	v_mfma_f32_16x16x32_bf16 v[50:53], v[180:183], v[204:207], v[50:53]
	v_mfma_f32_16x16x32_bf16 v[38:41], v[172:175], v[212:215], v[38:41]
	v_mfma_f32_16x16x32_bf16 v[34:37], v[180:183], v[212:215], v[34:37]
	v_mfma_f32_16x16x32_bf16 v[22:25], v[172:175], v[220:223], v[22:25]
	v_mfma_f32_16x16x32_bf16 v[18:21], v[180:183], v[220:223], v[18:21]
	v_mfma_f32_16x16x32_bf16 v[6:9], v[172:175], v[228:231], v[6:9]
	v_mfma_f32_16x16x32_bf16 v[2:5], v[180:183], v[228:231], v[2:5]
	s_barrier
; #define PG8_STAGE(bufoff, gbase, voff) do { _Pragma("unroll") for (int _i = 0; _i < 2; ++_i) \
;         __builtin_amdgcn_global_load_lds((const unsigned*)((const char*)(gbase) + (voff)[_i]), (LAS unsigned*)(lds + (bufoff) + ldsw + _i * 8192), 16, 0, 0); } while (0)
; #define PG8_LDA(dst, b, h) do { _Pragma("unroll") for (int m = 0; m < 4; ++m) _Pragma("unroll") for (int k = 0; k < 2; ++k) dst[m][k] = *(const LAS bf16x8*)(lds + PG8_SA(b, h) + aoff + m * 2048 + k * 1024); } while (0)
; #define PG8_LDB(dst, b, h) do { _Pragma("unroll") for (int n = 0; n < 2; ++n) _Pragma("unroll") for (int k = 0; k < 2; ++k) dst[n][k] = *(const LAS bf16x8*)(lds + PG8_SB(b, h) + boff + n * 2048 + k * 1024); } while (0)
; #define PG8_MMA(ai, bj, At, Bt) do { __builtin_amdgcn_s_setprio(1); _Pragma("unroll") for (int m = 0; m < 4; ++m) _Pragma("unroll") for (int n = 0; n < 2; ++n) _Pragma("unroll") for (int k = 0; k < 2; ++k) \
;         acc[ai][bj][m][n] = __builtin_amdgcn_mfma_f32_16x16x32_bf16(Bt[n][k], At[m][k], acc[ai][bj][m][n], 0, 0, 0); __builtin_amdgcn_s_setprio(0); } while (0)
; #define PG8_WAIT_V(n) asm volatile("s_waitcnt vmcnt(" #n ")" ::: "memory")
; #define PG8_BAR __builtin_amdgcn_s_barrier()
; template <class Epi>
; __device__ __forceinline__ void gemm_phase(LAS unsigned char* lds, const Gemm g, const StaticOrder& S, const Epi& E) {
;     ...
;             PG8_LDB(B0, 0, 0); PG8_LDB(B1, 0, 1); PG8_SCHED; PG8_LDA(At, 0, 0); PG8_STAGE(PG8_SA(1, 1), a1 + hstep, voffA);
;             PG8_WAIT_V(8); PG8_WAIT_L(0); PG8_BAR; PG8_MMA(0, 0, At, B0); PG8_MMA(0, 1, At, B1); PG8_BAR; PG8_SCHED;
;             PG8_LDA(At, 0, 1); PG8_STAGE(PG8_SB(0, 0), b2, voffB); PG8_STAGE(PG8_SB(0, 1), b2 + hstep, voffB); PG8_STAGE(PG8_SA(0, 0), a2, voffA);
;             PG8_WAIT_V(8); PG8_WAIT_L(0); PG8_BAR; PG8_MMA(1, 0, At, B0); PG8_MMA(1, 1, At, B1); PG8_BAR; PG8_SCHED;
;             PG8_LDB(B0, 1, 0); PG8_LDB(B1, 1, 1); PG8_SCHED; PG8_LDA(At, 1, 0); PG8_STAGE(PG8_SA(0, 1), a2 + hstep, voffA);
;             PG8_WAIT_V(8); PG8_WAIT_L(0); PG8_BAR; PG8_MMA(0, 0, At, B0); PG8_MMA(0, 1, At, B1); PG8_BAR; PG8_SCHED;
;             PG8_LDA(At, 1, 1); PG8_STAGE(PG8_SB(1, 0), b3, voffB); PG8_STAGE(PG8_SB(1, 1), b3 + hstep, voffB); PG8_STAGE(PG8_SA(1, 0), a3, voffA);
;             PG8_WAIT_V(8); PG8_WAIT_L(0); PG8_BAR; PG8_MMA(1, 0, At, B0); PG8_MMA(1, 1, At, B1); PG8_BAR; PG8_SCHED;
	s_add_i32 s60, 0, 0x18000
	s_add_i32 s61, 0, 0x1c000
	v_add_u32_e32 v142, s60, v187
	v_add_u32_e32 v180, s61, v187
	ds_read_b128 v[130:133], v142
	ds_read_b128 v[134:137], v142 offset:1024
	ds_read_b128 v[138:141], v142 offset:2048
	ds_read_b128 v[142:145], v142 offset:3072
	ds_read_b128 v[166:169], v180
	ds_read_b128 v[172:175], v180 offset:1024
	ds_read_b128 v[176:179], v180 offset:2048
	ds_read_b128 v[180:183], v180 offset:3072
	s_add_u32 s76, s92, 0x40000
	s_addc_u32 s77, s93, 0
	s_mov_b32 m0, s11
	ds_read_b128 v[200:203], v194 offset:32768
	ds_read_b128 v[204:207], v194 offset:33792
	ds_read_b128 v[208:211], v194 offset:34816
	ds_read_b128 v[212:215], v194 offset:35840
	ds_read_b128 v[216:219], v194 offset:36864
	ds_read_b128 v[220:223], v194 offset:37888
	ds_read_b128 v[224:227], v194 offset:38912
	ds_read_b128 v[228:231], v194 offset:39936
	global_load_lds_dwordx4 v146, s[76:77]
	s_mov_b32 m0, s94
	s_nop 0
	global_load_lds_dwordx4 v150, s[76:77]
	s_waitcnt vmcnt(8)
	s_waitcnt lgkmcnt(0)
	s_barrier
	v_mfma_f32_16x16x32_bf16 v[126:129], v[130:133], v[200:203], v[126:129]
	v_mfma_f32_16x16x32_bf16 v[122:125], v[138:141], v[200:203], v[122:125]
	v_mfma_f32_16x16x32_bf16 v[110:113], v[130:133], v[208:211], v[110:113]
	v_mfma_f32_16x16x32_bf16 v[106:109], v[138:141], v[208:211], v[106:109]
	v_mfma_f32_16x16x32_bf16 v[94:97], v[130:133], v[216:219], v[94:97]
	v_mfma_f32_16x16x32_bf16 v[90:93], v[138:141], v[216:219], v[90:93]
	v_mfma_f32_16x16x32_bf16 v[78:81], v[130:133], v[224:227], v[78:81]
	v_mfma_f32_16x16x32_bf16 v[74:77], v[138:141], v[224:227], v[74:77]
	v_mfma_f32_16x16x32_bf16 v[126:129], v[134:137], v[204:207], v[126:129]
	v_mfma_f32_16x16x32_bf16 v[122:125], v[142:145], v[204:207], v[122:125]
	v_mfma_f32_16x16x32_bf16 v[110:113], v[134:137], v[212:215], v[110:113]
	v_mfma_f32_16x16x32_bf16 v[106:109], v[142:145], v[212:215], v[106:109]
	v_mfma_f32_16x16x32_bf16 v[94:97], v[134:137], v[220:223], v[94:97]
	v_mfma_f32_16x16x32_bf16 v[90:93], v[142:145], v[220:223], v[90:93]
	v_mfma_f32_16x16x32_bf16 v[78:81], v[134:137], v[228:231], v[78:81]
	v_mfma_f32_16x16x32_bf16 v[74:77], v[142:145], v[228:231], v[74:77]
	v_mfma_f32_16x16x32_bf16 v[118:121], v[166:169], v[200:203], v[118:121]
	v_mfma_f32_16x16x32_bf16 v[114:117], v[176:179], v[200:203], v[114:117]
	v_mfma_f32_16x16x32_bf16 v[102:105], v[166:169], v[208:211], v[102:105]
	v_mfma_f32_16x16x32_bf16 v[98:101], v[176:179], v[208:211], v[98:101]
	v_mfma_f32_16x16x32_bf16 v[86:89], v[166:169], v[216:219], v[86:89]
	v_mfma_f32_16x16x32_bf16 v[82:85], v[176:179], v[216:219], v[82:85]
	v_mfma_f32_16x16x32_bf16 v[70:73], v[166:169], v[224:227], v[70:73]
	v_mfma_f32_16x16x32_bf16 v[66:69], v[176:179], v[224:227], v[66:69]
	v_mfma_f32_16x16x32_bf16 v[118:121], v[172:175], v[204:207], v[118:121]
	v_mfma_f32_16x16x32_bf16 v[114:117], v[180:183], v[204:207], v[114:117]
	v_mfma_f32_16x16x32_bf16 v[102:105], v[172:175], v[212:215], v[102:105]
	v_mfma_f32_16x16x32_bf16 v[98:101], v[180:183], v[212:215], v[98:101]
	v_mfma_f32_16x16x32_bf16 v[86:89], v[172:175], v[220:223], v[86:89]
	v_mfma_f32_16x16x32_bf16 v[82:85], v[180:183], v[220:223], v[82:85]
	v_mfma_f32_16x16x32_bf16 v[70:73], v[172:175], v[228:231], v[70:73]
	v_mfma_f32_16x16x32_bf16 v[66:69], v[180:183], v[228:231], v[66:69]
	s_barrier
	s_add_i32 s60, s60, s44
	s_mov_b32 m0, s60
	ds_read_b128 v[200:203], v194 offset:49152
	ds_read_b128 v[204:207], v194 offset:50176
	ds_read_b128 v[208:211], v194 offset:51200
	ds_read_b128 v[212:215], v194 offset:52224
	ds_read_b128 v[216:219], v194 offset:53248
	ds_read_b128 v[220:223], v194 offset:54272
	ds_read_b128 v[224:227], v194 offset:55296
	ds_read_b128 v[228:231], v194 offset:56320
	global_load_lds_dwordx4 v148, s[98:99]
	s_add_i32 m0, s60, 0x2000
	s_add_u32 s76, s90, 0x40080
	s_addc_u32 s77, s91, 0
	s_add_i32 s60, s61, s44
	global_load_lds_dwordx4 v152, s[98:99]
	s_mov_b32 m0, s60
	s_nop 0
	global_load_lds_dwordx4 v148, s[76:77]
	s_add_i32 m0, s60, 0x2000
	s_nop 0
	global_load_lds_dwordx4 v152, s[76:77]
	s_mov_b32 m0, s79
	s_nop 0
	global_load_lds_dwordx4 v146, s[100:101]
	s_mov_b32 m0, s33
	s_nop 0
	global_load_lds_dwordx4 v150, s[100:101]
	s_waitcnt vmcnt(8)
	s_waitcnt lgkmcnt(0)
	s_barrier
	v_mfma_f32_16x16x32_bf16 v[62:65], v[130:133], v[200:203], v[62:65]
	v_mfma_f32_16x16x32_bf16 v[58:61], v[138:141], v[200:203], v[58:61]
	v_mfma_f32_16x16x32_bf16 v[46:49], v[130:133], v[208:211], v[46:49]
	v_mfma_f32_16x16x32_bf16 v[42:45], v[138:141], v[208:211], v[42:45]
	v_mfma_f32_16x16x32_bf16 v[30:33], v[130:133], v[216:219], v[30:33]
	v_mfma_f32_16x16x32_bf16 v[26:29], v[138:141], v[216:219], v[26:29]
	v_mfma_f32_16x16x32_bf16 v[14:17], v[130:133], v[224:227], v[14:17]
	v_mfma_f32_16x16x32_bf16 v[10:13], v[138:141], v[224:227], v[10:13]
	v_mfma_f32_16x16x32_bf16 v[62:65], v[134:137], v[204:207], v[62:65]
	v_mfma_f32_16x16x32_bf16 v[58:61], v[142:145], v[204:207], v[58:61]
	v_mfma_f32_16x16x32_bf16 v[46:49], v[134:137], v[212:215], v[46:49]
	v_mfma_f32_16x16x32_bf16 v[42:45], v[142:145], v[212:215], v[42:45]
	v_mfma_f32_16x16x32_bf16 v[30:33], v[134:137], v[220:223], v[30:33]
	v_mfma_f32_16x16x32_bf16 v[26:29], v[142:145], v[220:223], v[26:29]
	v_mfma_f32_16x16x32_bf16 v[14:17], v[134:137], v[228:231], v[14:17]
	v_mfma_f32_16x16x32_bf16 v[10:13], v[142:145], v[228:231], v[10:13]
	v_mfma_f32_16x16x32_bf16 v[54:57], v[166:169], v[200:203], v[54:57]
	v_mfma_f32_16x16x32_bf16 v[50:53], v[176:179], v[200:203], v[50:53]
	v_mfma_f32_16x16x32_bf16 v[38:41], v[166:169], v[208:211], v[38:41]
	v_mfma_f32_16x16x32_bf16 v[34:37], v[176:179], v[208:211], v[34:37]
	v_mfma_f32_16x16x32_bf16 v[22:25], v[166:169], v[216:219], v[22:25]
	v_mfma_f32_16x16x32_bf16 v[18:21], v[176:179], v[216:219], v[18:21]
	v_mfma_f32_16x16x32_bf16 v[6:9], v[166:169], v[224:227], v[6:9]
	v_mfma_f32_16x16x32_bf16 v[2:5], v[176:179], v[224:227], v[2:5]
	v_mfma_f32_16x16x32_bf16 v[54:57], v[172:175], v[204:207], v[54:57]
	v_mfma_f32_16x16x32_bf16 v[50:53], v[180:183], v[204:207], v[50:53]
	v_mfma_f32_16x16x32_bf16 v[38:41], v[172:175], v[212:215], v[38:41]
	v_mfma_f32_16x16x32_bf16 v[34:37], v[180:183], v[212:215], v[34:37]
	v_mfma_f32_16x16x32_bf16 v[22:25], v[172:175], v[220:223], v[22:25]
	v_mfma_f32_16x16x32_bf16 v[18:21], v[180:183], v[220:223], v[18:21]
	v_mfma_f32_16x16x32_bf16 v[6:9], v[172:175], v[228:231], v[6:9]
	v_mfma_f32_16x16x32_bf16 v[2:5], v[180:183], v[228:231], v[2:5]
	s_barrier
	s_add_i32 vcc_hi, vcc_hi, 2
	s_add_u32 s88, s88, 0x100
	s_addc_u32 s89, s89, 0
	s_add_u32 s81, s81, 0x100
	s_addc_u32 vcc_lo, vcc_lo, 0
	s_cmp_gt_u32 vcc_hi, 13
	s_cbranch_scc0 .LBB0_322
	s_and_b64 vcc, exec, s[58:59]
	s_cbranch_vccz .LBB0_325
	s_barrier

; #define PG8_STAGE(bufoff, gbase, voff) do { _Pragma("unroll") for (int _i = 0; _i < 2; ++_i) \
;         __builtin_amdgcn_global_load_lds((const unsigned*)((const char*)(gbase) + (voff)[_i]), (LAS unsigned*)(lds + (bufoff) + ldsw + _i * 8192), 16, 0, 0); } while (0)
; #define PG8_LDA(dst, b, h) do { _Pragma("unroll") for (int m = 0; m < 4; ++m) _Pragma("unroll") for (int k = 0; k < 2; ++k) dst[m][k] = *(const LAS bf16x8*)(lds + PG8_SA(b, h) + aoff + m * 2048 + k * 1024); } while (0)
; #define PG8_LDB(dst, b, h) do { _Pragma("unroll") for (int n = 0; n < 2; ++n) _Pragma("unroll") for (int k = 0; k < 2; ++k) dst[n][k] = *(const LAS bf16x8*)(lds + PG8_SB(b, h) + boff + n * 2048 + k * 1024); } while (0)
; #define PG8_MMA(ai, bj, At, Bt) do { __builtin_amdgcn_s_setprio(1); _Pragma("unroll") for (int m = 0; m < 4; ++m) _Pragma("unroll") for (int n = 0; n < 2; ++n) _Pragma("unroll") for (int k = 0; k < 2; ++k) \
;         acc[ai][bj][m][n] = __builtin_amdgcn_mfma_f32_16x16x32_bf16(Bt[n][k], At[m][k], acc[ai][bj][m][n], 0, 0, 0); __builtin_amdgcn_s_setprio(0); } while (0)
; #define PG8_WAIT_V(n) asm volatile("s_waitcnt vmcnt(" #n ")" ::: "memory")
; #define PG8_BAR __builtin_amdgcn_s_barrier()
; template <class Epi>
; __device__ __forceinline__ void gemm_phase(LAS unsigned char* lds, const Gemm g, const StaticOrder& S, const Epi& E) {
;     ...
;             PG8_LDB(B0, 0, 0); PG8_LDB(B1, 0, 1); PG8_SCHED; PG8_LDA(At, 0, 0); PG8_STAGE(PG8_SA(1, 1), a1 + hstep, voffA);
;             PG8_WAIT_V(8); PG8_WAIT_L(0); PG8_BAR; PG8_MMA(0, 0, At, B0); PG8_MMA(0, 1, At, B1); PG8_BAR; PG8_SCHED;
;             PG8_LDA(At, 0, 1); PG8_STAGE(PG8_SB(0, 0), b2, voffB); PG8_STAGE(PG8_SB(0, 1), b2 + hstep, voffB); PG8_STAGE(PG8_SA(0, 0), a2, voffA);
;             PG8_WAIT_V(8); PG8_WAIT_L(0); PG8_BAR; PG8_MMA(1, 0, At, B0); PG8_MMA(1, 1, At, B1); PG8_BAR; PG8_SCHED;
;             PG8_LDB(B0, 1, 0); PG8_LDB(B1, 1, 1); PG8_SCHED; PG8_LDA(At, 1, 0); PG8_STAGE(PG8_SA(0, 1), a2 + hstep, voffA);
;             PG8_WAIT_V(8); PG8_WAIT_L(0); PG8_BAR; PG8_MMA(0, 0, At, B0); PG8_MMA(0, 1, At, B1); PG8_BAR; PG8_SCHED;
;             PG8_LDA(At, 1, 1); PG8_STAGE(PG8_SB(1, 0), b3, voffB); PG8_STAGE(PG8_SB(1, 1), b3 + hstep, voffB); PG8_STAGE(PG8_SA(1, 0), a3, voffA);
;             PG8_WAIT_V(8); PG8_WAIT_L(0); PG8_BAR; PG8_MMA(1, 0, At, B0); PG8_MMA(1, 1, At, B1); PG8_BAR; PG8_SCHED;
.LBB0_619:
	ds_read_b128 v[154:157], v174
	ds_read_b128 v[158:161], v174 offset:1024
	ds_read_b128 v[162:165], v174 offset:2048
	ds_read_b128 v[166:169], v174 offset:3072
	ds_read_b128 v[182:185], v175
	ds_read_b128 v[186:189], v175 offset:1024
	ds_read_b128 v[190:193], v175 offset:2048
	ds_read_b128 v[194:197], v175 offset:3072
	s_add_u32 s46, s44, 0xfffc0080
	s_addc_u32 s47, s45, -1
	s_cmp_eq_u32 s69, 12
	s_cselect_b32 s49, s64, s47
	s_cselect_b32 s48, s65, s46
	s_cselect_b32 s47, s25, s68
	s_cselect_b32 s46, s66, s67
	s_add_i32 m0, s43, 0xc000
	ds_read_b128 v[198:201], v176
	ds_read_b128 v[202:205], v176 offset:1024
	ds_read_b128 v[206:209], v176 offset:2048
	ds_read_b128 v[210:213], v176 offset:3072
	ds_read_b128 v[214:217], v176 offset:4096
	ds_read_b128 v[218:221], v176 offset:5120
	ds_read_b128 v[222:225], v176 offset:6144
	ds_read_b128 v[226:229], v176 offset:7168
	global_load_lds_dwordx4 v144, s[44:45]
	s_add_i32 m0, s43, 0xe000
	s_nop 0
	global_load_lds_dwordx4 v146, s[44:45]
	s_waitcnt vmcnt(8)
	s_waitcnt lgkmcnt(0)
	s_barrier
	v_mfma_f32_16x16x32_bf16 v[126:129], v[154:157], v[198:201], v[126:129]
	v_mfma_f32_16x16x32_bf16 v[122:125], v[162:165], v[198:201], v[122:125]
	v_mfma_f32_16x16x32_bf16 v[110:113], v[154:157], v[206:209], v[110:113]
	v_mfma_f32_16x16x32_bf16 v[106:109], v[162:165], v[206:209], v[106:109]
	v_mfma_f32_16x16x32_bf16 v[94:97], v[154:157], v[214:217], v[94:97]
	v_mfma_f32_16x16x32_bf16 v[90:93], v[162:165], v[214:217], v[90:93]
	v_mfma_f32_16x16x32_bf16 v[78:81], v[154:157], v[222:225], v[78:81]
	v_mfma_f32_16x16x32_bf16 v[74:77], v[162:165], v[222:225], v[74:77]
	v_mfma_f32_16x16x32_bf16 v[126:129], v[158:161], v[202:205], v[126:129]
	v_mfma_f32_16x16x32_bf16 v[122:125], v[166:169], v[202:205], v[122:125]
	v_mfma_f32_16x16x32_bf16 v[110:113], v[158:161], v[210:213], v[110:113]
	v_mfma_f32_16x16x32_bf16 v[106:109], v[166:169], v[210:213], v[106:109]
	v_mfma_f32_16x16x32_bf16 v[94:97], v[158:161], v[218:221], v[94:97]
	v_mfma_f32_16x16x32_bf16 v[90:93], v[166:169], v[218:221], v[90:93]
	v_mfma_f32_16x16x32_bf16 v[78:81], v[158:161], v[226:229], v[78:81]
	v_mfma_f32_16x16x32_bf16 v[74:77], v[166:169], v[226:229], v[74:77]
	v_mfma_f32_16x16x32_bf16 v[118:121], v[182:185], v[198:201], v[118:121]
	v_mfma_f32_16x16x32_bf16 v[114:117], v[190:193], v[198:201], v[114:117]
	v_mfma_f32_16x16x32_bf16 v[102:105], v[182:185], v[206:209], v[102:105]
	v_mfma_f32_16x16x32_bf16 v[98:101], v[190:193], v[206:209], v[98:101]
	v_mfma_f32_16x16x32_bf16 v[86:89], v[182:185], v[214:217], v[86:89]
	v_mfma_f32_16x16x32_bf16 v[82:85], v[190:193], v[214:217], v[82:85]
	v_mfma_f32_16x16x32_bf16 v[70:73], v[182:185], v[222:225], v[70:73]
	v_mfma_f32_16x16x32_bf16 v[66:69], v[190:193], v[222:225], v[66:69]
	v_mfma_f32_16x16x32_bf16 v[118:121], v[186:189], v[202:205], v[118:121]
	v_mfma_f32_16x16x32_bf16 v[114:117], v[194:197], v[202:205], v[114:117]
	v_mfma_f32_16x16x32_bf16 v[102:105], v[186:189], v[210:213], v[102:105]
	v_mfma_f32_16x16x32_bf16 v[98:101], v[194:197], v[210:213], v[98:101]
	v_mfma_f32_16x16x32_bf16 v[86:89], v[186:189], v[218:221], v[86:89]
	v_mfma_f32_16x16x32_bf16 v[82:85], v[194:197], v[218:221], v[82:85]
	v_mfma_f32_16x16x32_bf16 v[70:73], v[186:189], v[226:229], v[70:73]
	v_mfma_f32_16x16x32_bf16 v[66:69], v[194:197], v[226:229], v[66:69]
	s_barrier
	s_add_u32 s98, s46, s8
	s_addc_u32 s99, s47, s9
	s_add_u32 s100, s48, s8
	s_addc_u32 s101, s49, s9
	s_add_i32 s76, s60, s6
	s_mov_b32 m0, s76
	ds_read_b128 v[198:201], v176 offset:16384
	ds_read_b128 v[202:205], v176 offset:17408
	ds_read_b128 v[206:209], v176 offset:18432
	ds_read_b128 v[210:213], v176 offset:19456
	ds_read_b128 v[214:217], v176 offset:20480
	ds_read_b128 v[218:221], v176 offset:21504
	ds_read_b128 v[222:225], v176 offset:22528
	ds_read_b128 v[226:229], v176 offset:23552
	global_load_lds_dwordx4 v132, s[46:47]
	s_add_i32 m0, s76, 0x2000
	s_add_u32 s76, s46, 0x40000
	s_addc_u32 s77, s47, 0
	s_add_i32 s78, s61, s6
	global_load_lds_dwordx4 v136, s[46:47]
	s_mov_b32 m0, s78
	s_nop 0
	global_load_lds_dwordx4 v132, s[76:77]
	s_add_i32 m0, s78, 0x2000
	s_nop 0
	global_load_lds_dwordx4 v136, s[76:77]
	s_mov_b32 m0, s43
	s_nop 0
	global_load_lds_dwordx4 v130, s[48:49]
	s_mov_b32 m0, s51
	s_nop 0
	global_load_lds_dwordx4 v134, s[48:49]
	s_waitcnt vmcnt(8)
	s_waitcnt lgkmcnt(0)
	s_barrier
	v_mfma_f32_16x16x32_bf16 v[62:65], v[154:157], v[198:201], v[62:65]
	v_mfma_f32_16x16x32_bf16 v[58:61], v[162:165], v[198:201], v[58:61]
	v_mfma_f32_16x16x32_bf16 v[46:49], v[154:157], v[206:209], v[46:49]
	v_mfma_f32_16x16x32_bf16 v[42:45], v[162:165], v[206:209], v[42:45]
	v_mfma_f32_16x16x32_bf16 v[30:33], v[154:157], v[214:217], v[30:33]
	v_mfma_f32_16x16x32_bf16 v[26:29], v[162:165], v[214:217], v[26:29]
	v_mfma_f32_16x16x32_bf16 v[14:17], v[154:157], v[222:225], v[14:17]
	v_mfma_f32_16x16x32_bf16 v[10:13], v[162:165], v[222:225], v[10:13]
	v_mfma_f32_16x16x32_bf16 v[62:65], v[158:161], v[202:205], v[62:65]
	v_mfma_f32_16x16x32_bf16 v[58:61], v[166:169], v[202:205], v[58:61]
	v_mfma_f32_16x16x32_bf16 v[46:49], v[158:161], v[210:213], v[46:49]
	v_mfma_f32_16x16x32_bf16 v[42:45], v[166:169], v[210:213], v[42:45]
	v_mfma_f32_16x16x32_bf16 v[30:33], v[158:161], v[218:221], v[30:33]
	v_mfma_f32_16x16x32_bf16 v[26:29], v[166:169], v[218:221], v[26:29]
	v_mfma_f32_16x16x32_bf16 v[14:17], v[158:161], v[226:229], v[14:17]
	v_mfma_f32_16x16x32_bf16 v[10:13], v[166:169], v[226:229], v[10:13]
	v_mfma_f32_16x16x32_bf16 v[54:57], v[182:185], v[198:201], v[54:57]
	v_mfma_f32_16x16x32_bf16 v[50:53], v[190:193], v[198:201], v[50:53]
	v_mfma_f32_16x16x32_bf16 v[38:41], v[182:185], v[206:209], v[38:41]
	v_mfma_f32_16x16x32_bf16 v[34:37], v[190:193], v[206:209], v[34:37]
	v_mfma_f32_16x16x32_bf16 v[22:25], v[182:185], v[214:217], v[22:25]
	v_mfma_f32_16x16x32_bf16 v[18:21], v[190:193], v[214:217], v[18:21]
	v_mfma_f32_16x16x32_bf16 v[6:9], v[182:185], v[222:225], v[6:9]
	v_mfma_f32_16x16x32_bf16 v[2:5], v[190:193], v[222:225], v[2:5]
	v_mfma_f32_16x16x32_bf16 v[54:57], v[186:189], v[202:205], v[54:57]
	v_mfma_f32_16x16x32_bf16 v[50:53], v[194:197], v[202:205], v[50:53]
	v_mfma_f32_16x16x32_bf16 v[38:41], v[186:189], v[210:213], v[38:41]
	v_mfma_f32_16x16x32_bf16 v[34:37], v[194:197], v[210:213], v[34:37]
	v_mfma_f32_16x16x32_bf16 v[22:25], v[186:189], v[218:221], v[22:25]
	v_mfma_f32_16x16x32_bf16 v[18:21], v[194:197], v[218:221], v[18:21]
	v_mfma_f32_16x16x32_bf16 v[6:9], v[186:189], v[226:229], v[6:9]
	v_mfma_f32_16x16x32_bf16 v[2:5], v[194:197], v[226:229], v[2:5]
	s_barrier
; #define PG8_STAGE(bufoff, gbase, voff) do { _Pragma("unroll") for (int _i = 0; _i < 2; ++_i) \
;         __builtin_amdgcn_global_load_lds((const unsigned*)((const char*)(gbase) + (voff)[_i]), (LAS unsigned*)(lds + (bufoff) + ldsw + _i * 8192), 16, 0, 0); } while (0)
; #define PG8_LDA(dst, b, h) do { _Pragma("unroll") for (int m = 0; m < 4; ++m) _Pragma("unroll") for (int k = 0; k < 2; ++k) dst[m][k] = *(const LAS bf16x8*)(lds + PG8_SA(b, h) + aoff + m * 2048 + k * 1024); } while (0)
; #define PG8_LDB(dst, b, h) do { _Pragma("unroll") for (int n = 0; n < 2; ++n) _Pragma("unroll") for (int k = 0; k < 2; ++k) dst[n][k] = *(const LAS bf16x8*)(lds + PG8_SB(b, h) + boff + n * 2048 + k * 1024); } while (0)
; #define PG8_MMA(ai, bj, At, Bt) do { __builtin_amdgcn_s_setprio(1); _Pragma("unroll") for (int m = 0; m < 4; ++m) _Pragma("unroll") for (int n = 0; n < 2; ++n) _Pragma("unroll") for (int k = 0; k < 2; ++k) \
;         acc[ai][bj][m][n] = __builtin_amdgcn_mfma_f32_16x16x32_bf16(Bt[n][k], At[m][k], acc[ai][bj][m][n], 0, 0, 0); __builtin_amdgcn_s_setprio(0); } while (0)
; #define PG8_WAIT_V(n) asm volatile("s_waitcnt vmcnt(" #n ")" ::: "memory")
; #define PG8_BAR __builtin_amdgcn_s_barrier()
; template <class Epi>
; __device__ __forceinline__ void gemm_phase(LAS unsigned char* lds, const Gemm g, const StaticOrder& S, const Epi& E) {
;     ...
;             PG8_LDB(B0, 0, 0); PG8_LDB(B1, 0, 1); PG8_SCHED; PG8_LDA(At, 0, 0); PG8_STAGE(PG8_SA(1, 1), a1 + hstep, voffA);
;             PG8_WAIT_V(8); PG8_WAIT_L(0); PG8_BAR; PG8_MMA(0, 0, At, B0); PG8_MMA(0, 1, At, B1); PG8_BAR; PG8_SCHED;
;             PG8_LDA(At, 0, 1); PG8_STAGE(PG8_SB(0, 0), b2, voffB); PG8_STAGE(PG8_SB(0, 1), b2 + hstep, voffB); PG8_STAGE(PG8_SA(0, 0), a2, voffA);
;             PG8_WAIT_V(8); PG8_WAIT_L(0); PG8_BAR; PG8_MMA(1, 0, At, B0); PG8_MMA(1, 1, At, B1); PG8_BAR; PG8_SCHED;
;             PG8_LDB(B0, 1, 0); PG8_LDB(B1, 1, 1); PG8_SCHED; PG8_LDA(At, 1, 0); PG8_STAGE(PG8_SA(0, 1), a2 + hstep, voffA);
;             PG8_WAIT_V(8); PG8_WAIT_L(0); PG8_BAR; PG8_MMA(0, 0, At, B0); PG8_MMA(0, 1, At, B1); PG8_BAR; PG8_SCHED;
;             PG8_LDA(At, 1, 1); PG8_STAGE(PG8_SB(1, 0), b3, voffB); PG8_STAGE(PG8_SB(1, 1), b3 + hstep, voffB); PG8_STAGE(PG8_SA(1, 0), a3, voffA);
;             PG8_WAIT_V(8); PG8_WAIT_L(0); PG8_BAR; PG8_MMA(1, 0, At, B0); PG8_MMA(1, 1, At, B1); PG8_BAR; PG8_SCHED;
	s_add_i32 s76, 0, 0x18000
	v_add_u32_e32 v138, s76, v172
	s_add_i32 s77, 0, 0x1c000
	ds_read_b128 v[154:157], v138
	ds_read_b128 v[158:161], v138 offset:1024
	ds_read_b128 v[162:165], v138 offset:2048
	ds_read_b128 v[166:169], v138 offset:3072
	v_add_u32_e32 v138, s77, v172
	ds_read_b128 v[182:185], v138
	ds_read_b128 v[186:189], v138 offset:1024
	ds_read_b128 v[190:193], v138 offset:2048
	ds_read_b128 v[194:197], v138 offset:3072
	s_add_u32 s48, s48, 0x40000
	s_addc_u32 s49, s49, 0
	s_mov_b32 m0, s52
	ds_read_b128 v[198:201], v176 offset:32768
	ds_read_b128 v[202:205], v176 offset:33792
	ds_read_b128 v[206:209], v176 offset:34816
	ds_read_b128 v[210:213], v176 offset:35840
	ds_read_b128 v[214:217], v176 offset:36864
	ds_read_b128 v[218:221], v176 offset:37888
	ds_read_b128 v[222:225], v176 offset:38912
	ds_read_b128 v[226:229], v176 offset:39936
	global_load_lds_dwordx4 v130, s[48:49]
	s_mov_b32 m0, s53
	s_nop 0
	global_load_lds_dwordx4 v134, s[48:49]
	s_waitcnt vmcnt(8)
	s_waitcnt lgkmcnt(0)
	s_barrier
	v_mfma_f32_16x16x32_bf16 v[126:129], v[154:157], v[198:201], v[126:129]
	v_mfma_f32_16x16x32_bf16 v[122:125], v[162:165], v[198:201], v[122:125]
	v_mfma_f32_16x16x32_bf16 v[110:113], v[154:157], v[206:209], v[110:113]
	v_mfma_f32_16x16x32_bf16 v[106:109], v[162:165], v[206:209], v[106:109]
	v_mfma_f32_16x16x32_bf16 v[94:97], v[154:157], v[214:217], v[94:97]
	v_mfma_f32_16x16x32_bf16 v[90:93], v[162:165], v[214:217], v[90:93]
	v_mfma_f32_16x16x32_bf16 v[78:81], v[154:157], v[222:225], v[78:81]
	v_mfma_f32_16x16x32_bf16 v[74:77], v[162:165], v[222:225], v[74:77]
	v_mfma_f32_16x16x32_bf16 v[126:129], v[158:161], v[202:205], v[126:129]
	v_mfma_f32_16x16x32_bf16 v[122:125], v[166:169], v[202:205], v[122:125]
	v_mfma_f32_16x16x32_bf16 v[110:113], v[158:161], v[210:213], v[110:113]
	v_mfma_f32_16x16x32_bf16 v[106:109], v[166:169], v[210:213], v[106:109]
	v_mfma_f32_16x16x32_bf16 v[94:97], v[158:161], v[218:221], v[94:97]
	v_mfma_f32_16x16x32_bf16 v[90:93], v[166:169], v[218:221], v[90:93]
	v_mfma_f32_16x16x32_bf16 v[78:81], v[158:161], v[226:229], v[78:81]
	v_mfma_f32_16x16x32_bf16 v[74:77], v[166:169], v[226:229], v[74:77]
	v_mfma_f32_16x16x32_bf16 v[118:121], v[182:185], v[198:201], v[118:121]
	v_mfma_f32_16x16x32_bf16 v[114:117], v[190:193], v[198:201], v[114:117]
	v_mfma_f32_16x16x32_bf16 v[102:105], v[182:185], v[206:209], v[102:105]
	v_mfma_f32_16x16x32_bf16 v[98:101], v[190:193], v[206:209], v[98:101]
	v_mfma_f32_16x16x32_bf16 v[86:89], v[182:185], v[214:217], v[86:89]
	v_mfma_f32_16x16x32_bf16 v[82:85], v[190:193], v[214:217], v[82:85]
	v_mfma_f32_16x16x32_bf16 v[70:73], v[182:185], v[222:225], v[70:73]
	v_mfma_f32_16x16x32_bf16 v[66:69], v[190:193], v[222:225], v[66:69]
	v_mfma_f32_16x16x32_bf16 v[118:121], v[186:189], v[202:205], v[118:121]
	v_mfma_f32_16x16x32_bf16 v[114:117], v[194:197], v[202:205], v[114:117]
	v_mfma_f32_16x16x32_bf16 v[102:105], v[186:189], v[210:213], v[102:105]
	v_mfma_f32_16x16x32_bf16 v[98:101], v[194:197], v[210:213], v[98:101]
	v_mfma_f32_16x16x32_bf16 v[86:89], v[186:189], v[218:221], v[86:89]
	v_mfma_f32_16x16x32_bf16 v[82:85], v[194:197], v[218:221], v[82:85]
	v_mfma_f32_16x16x32_bf16 v[70:73], v[186:189], v[226:229], v[70:73]
	v_mfma_f32_16x16x32_bf16 v[66:69], v[194:197], v[226:229], v[66:69]
	s_barrier
	s_add_i32 s48, s76, s6
	s_mov_b32 m0, s48
	ds_read_b128 v[198:201], v176 offset:49152
	ds_read_b128 v[202:205], v176 offset:50176
	ds_read_b128 v[206:209], v176 offset:51200
	ds_read_b128 v[210:213], v176 offset:52224
	ds_read_b128 v[214:217], v176 offset:53248
	ds_read_b128 v[218:221], v176 offset:54272
	ds_read_b128 v[222:225], v176 offset:55296
	ds_read_b128 v[226:229], v176 offset:56320
	global_load_lds_dwordx4 v132, s[98:99]
	s_add_i32 m0, s48, 0x2000
	s_add_u32 s46, s46, 0x40080
	s_addc_u32 s47, s47, 0
	s_add_i32 s48, s77, s6
	global_load_lds_dwordx4 v136, s[98:99]
	s_mov_b32 m0, s48
	s_nop 0
	global_load_lds_dwordx4 v132, s[46:47]
	s_add_i32 m0, s48, 0x2000
	s_nop 0
	global_load_lds_dwordx4 v136, s[46:47]
	s_mov_b32 m0, s56
	s_nop 0
	global_load_lds_dwordx4 v130, s[100:101]
	s_mov_b32 m0, s57
	s_nop 0
	global_load_lds_dwordx4 v134, s[100:101]
	s_waitcnt vmcnt(8)
	s_waitcnt lgkmcnt(0)
	s_barrier
	v_mfma_f32_16x16x32_bf16 v[62:65], v[154:157], v[198:201], v[62:65]
	v_mfma_f32_16x16x32_bf16 v[58:61], v[162:165], v[198:201], v[58:61]
	v_mfma_f32_16x16x32_bf16 v[46:49], v[154:157], v[206:209], v[46:49]
	v_mfma_f32_16x16x32_bf16 v[42:45], v[162:165], v[206:209], v[42:45]
	v_mfma_f32_16x16x32_bf16 v[30:33], v[154:157], v[214:217], v[30:33]
	v_mfma_f32_16x16x32_bf16 v[26:29], v[162:165], v[214:217], v[26:29]
	v_mfma_f32_16x16x32_bf16 v[14:17], v[154:157], v[222:225], v[14:17]
	v_mfma_f32_16x16x32_bf16 v[10:13], v[162:165], v[222:225], v[10:13]
	v_mfma_f32_16x16x32_bf16 v[62:65], v[158:161], v[202:205], v[62:65]
	v_mfma_f32_16x16x32_bf16 v[58:61], v[166:169], v[202:205], v[58:61]
	v_mfma_f32_16x16x32_bf16 v[46:49], v[158:161], v[210:213], v[46:49]
	v_mfma_f32_16x16x32_bf16 v[42:45], v[166:169], v[210:213], v[42:45]
	v_mfma_f32_16x16x32_bf16 v[30:33], v[158:161], v[218:221], v[30:33]
	v_mfma_f32_16x16x32_bf16 v[26:29], v[166:169], v[218:221], v[26:29]
	v_mfma_f32_16x16x32_bf16 v[14:17], v[158:161], v[226:229], v[14:17]
	v_mfma_f32_16x16x32_bf16 v[10:13], v[166:169], v[226:229], v[10:13]
	v_mfma_f32_16x16x32_bf16 v[54:57], v[182:185], v[198:201], v[54:57]
	v_mfma_f32_16x16x32_bf16 v[50:53], v[190:193], v[198:201], v[50:53]
	v_mfma_f32_16x16x32_bf16 v[38:41], v[182:185], v[206:209], v[38:41]
	v_mfma_f32_16x16x32_bf16 v[34:37], v[190:193], v[206:209], v[34:37]
	v_mfma_f32_16x16x32_bf16 v[22:25], v[182:185], v[214:217], v[22:25]
	v_mfma_f32_16x16x32_bf16 v[18:21], v[190:193], v[214:217], v[18:21]
	v_mfma_f32_16x16x32_bf16 v[6:9], v[182:185], v[222:225], v[6:9]
	v_mfma_f32_16x16x32_bf16 v[2:5], v[190:193], v[222:225], v[2:5]
	v_mfma_f32_16x16x32_bf16 v[54:57], v[186:189], v[202:205], v[54:57]
	v_mfma_f32_16x16x32_bf16 v[50:53], v[194:197], v[202:205], v[50:53]
	v_mfma_f32_16x16x32_bf16 v[38:41], v[186:189], v[210:213], v[38:41]
	v_mfma_f32_16x16x32_bf16 v[34:37], v[194:197], v[210:213], v[34:37]
	v_mfma_f32_16x16x32_bf16 v[22:25], v[186:189], v[218:221], v[22:25]
	v_mfma_f32_16x16x32_bf16 v[18:21], v[194:197], v[218:221], v[18:21]
	v_mfma_f32_16x16x32_bf16 v[6:9], v[186:189], v[226:229], v[6:9]
	v_mfma_f32_16x16x32_bf16 v[2:5], v[194:197], v[226:229], v[2:5]
	s_barrier
	s_add_i32 s69, s69, 2
	s_add_u32 s44, s44, 0x100
	s_addc_u32 s45, s45, 0
	s_add_u32 s67, s67, 0x100
	s_addc_u32 s68, s68, 0
	s_cmp_gt_u32 s69, 13
	s_cbranch_scc0 .LBB0_619
	s_and_b64 vcc, exec, s[18:19]
	s_cbranch_vccz .LBB0_622
	s_barrier

; #define PG8_STAGE(bufoff, gbase, voff) do { _Pragma("unroll") for (int _i = 0; _i < 2; ++_i) \
;         __builtin_amdgcn_global_load_lds((const unsigned*)((const char*)(gbase) + (voff)[_i]), (LAS unsigned*)(lds + (bufoff) + ldsw + _i * 8192), 16, 0, 0); } while (0)
; #define PG8_LDA(dst, b, h) do { _Pragma("unroll") for (int m = 0; m < 4; ++m) _Pragma("unroll") for (int k = 0; k < 2; ++k) dst[m][k] = *(const LAS bf16x8*)(lds + PG8_SA(b, h) + aoff + m * 2048 + k * 1024); } while (0)
; #define PG8_LDB(dst, b, h) do { _Pragma("unroll") for (int n = 0; n < 2; ++n) _Pragma("unroll") for (int k = 0; k < 2; ++k) dst[n][k] = *(const LAS bf16x8*)(lds + PG8_SB(b, h) + boff + n * 2048 + k * 1024); } while (0)
; #define PG8_MMA(ai, bj, At, Bt) do { __builtin_amdgcn_s_setprio(1); _Pragma("unroll") for (int m = 0; m < 4; ++m) _Pragma("unroll") for (int n = 0; n < 2; ++n) _Pragma("unroll") for (int k = 0; k < 2; ++k) \
;         acc[ai][bj][m][n] = __builtin_amdgcn_mfma_f32_16x16x32_bf16(Bt[n][k], At[m][k], acc[ai][bj][m][n], 0, 0, 0); __builtin_amdgcn_s_setprio(0); } while (0)
; #define PG8_WAIT_V(n) asm volatile("s_waitcnt vmcnt(" #n ")" ::: "memory")
; #define PG8_BAR __builtin_amdgcn_s_barrier()
; template <class Epi>
; __device__ __forceinline__ void gemm_phase(LAS unsigned char* lds, const Gemm g, const StaticOrder& S, const Epi& E) {
;     ...
;             PG8_LDB(B0, 0, 0); PG8_LDB(B1, 0, 1); PG8_SCHED; PG8_LDA(At, 0, 0); PG8_STAGE(PG8_SA(1, 1), a1 + hstep, voffA);
;             PG8_WAIT_V(8); PG8_WAIT_L(0); PG8_BAR; PG8_MMA(0, 0, At, B0); PG8_MMA(0, 1, At, B1); PG8_BAR; PG8_SCHED;
;             PG8_LDA(At, 0, 1); PG8_STAGE(PG8_SB(0, 0), b2, voffB); PG8_STAGE(PG8_SB(0, 1), b2 + hstep, voffB); PG8_STAGE(PG8_SA(0, 0), a2, voffA);
;             PG8_WAIT_V(8); PG8_WAIT_L(0); PG8_BAR; PG8_MMA(1, 0, At, B0); PG8_MMA(1, 1, At, B1); PG8_BAR; PG8_SCHED;
;             PG8_LDB(B0, 1, 0); PG8_LDB(B1, 1, 1); PG8_SCHED; PG8_LDA(At, 1, 0); PG8_STAGE(PG8_SA(0, 1), a2 + hstep, voffA);
;             PG8_WAIT_V(8); PG8_WAIT_L(0); PG8_BAR; PG8_MMA(0, 0, At, B0); PG8_MMA(0, 1, At, B1); PG8_BAR; PG8_SCHED;
;             PG8_LDA(At, 1, 1); PG8_STAGE(PG8_SB(1, 0), b3, voffB); PG8_STAGE(PG8_SB(1, 1), b3 + hstep, voffB); PG8_STAGE(PG8_SA(1, 0), a3, voffA);
;             PG8_WAIT_V(8); PG8_WAIT_L(0); PG8_BAR; PG8_MMA(1, 0, At, B0); PG8_MMA(1, 1, At, B1); PG8_BAR; PG8_SCHED;
.LBB0_700:
	v_add_u32_e32 v3, s68, v198
	ds_read_b128 v[134:137], v3
	ds_read_b128 v[138:141], v3 offset:1024
	ds_read_b128 v[142:145], v3 offset:2048
	ds_read_b128 v[146:149], v3 offset:3072
	v_add_u32_e32 v3, s69, v198
	s_add_u32 s52, s48, s50
	ds_read_b128 v[158:161], v3
	ds_read_b128 v[162:165], v3 offset:1024
	ds_read_b128 v[166:169], v3 offset:2048
	ds_read_b128 v[188:191], v3 offset:3072
	s_addc_u32 s53, s49, s51
	s_add_u32 s52, s52, 0x100
	s_addc_u32 s53, s53, 0
	s_add_u32 s81, s78, s50
	s_addc_u32 s82, s79, s51
	s_cmpk_eq_i32 s50, 0x700
	s_cselect_b32 s55, s43, s53
	s_cselect_b32 s54, s76, s52
	s_cselect_b32 s53, s41, s82
	s_cselect_b32 s52, s77, s81
	v_lshl_add_u64 v[4:5], v[154:155], 0, s[50:51]
	s_add_i32 m0, s59, 0xc000
	ds_read_b128 v[192:195], v200
	ds_read_b128 v[202:205], v200 offset:1024
	ds_read_b128 v[206:209], v200 offset:2048
	ds_read_b128 v[210:213], v200 offset:3072
	ds_read_b128 v[214:217], v200 offset:4096
	ds_read_b128 v[218:221], v200 offset:5120
	ds_read_b128 v[222:225], v200 offset:6144
	ds_read_b128 v[226:229], v200 offset:7168
	global_load_lds_dwordx4 v[4:5], off
	v_lshl_add_u64 v[4:5], v[156:157], 0, s[50:51]
	s_add_i32 m0, s59, 0xe000
	s_nop 0
	global_load_lds_dwordx4 v[4:5], off
	s_waitcnt vmcnt(8)
	s_waitcnt lgkmcnt(0)
	s_barrier
	v_mfma_f32_16x16x32_bf16 v[130:133], v[134:137], v[192:195], v[130:133]
	v_mfma_f32_16x16x32_bf16 v[126:129], v[142:145], v[192:195], v[126:129]
	v_mfma_f32_16x16x32_bf16 v[114:117], v[134:137], v[206:209], v[114:117]
	v_mfma_f32_16x16x32_bf16 v[110:113], v[142:145], v[206:209], v[110:113]
	v_mfma_f32_16x16x32_bf16 v[98:101], v[134:137], v[214:217], v[98:101]
	v_mfma_f32_16x16x32_bf16 v[94:97], v[142:145], v[214:217], v[94:97]
	v_mfma_f32_16x16x32_bf16 v[82:85], v[134:137], v[222:225], v[82:85]
	v_mfma_f32_16x16x32_bf16 v[78:81], v[142:145], v[222:225], v[78:81]
	v_mfma_f32_16x16x32_bf16 v[130:133], v[138:141], v[202:205], v[130:133]
	v_mfma_f32_16x16x32_bf16 v[126:129], v[146:149], v[202:205], v[126:129]
	v_mfma_f32_16x16x32_bf16 v[114:117], v[138:141], v[210:213], v[114:117]
	v_mfma_f32_16x16x32_bf16 v[110:113], v[146:149], v[210:213], v[110:113]
	v_mfma_f32_16x16x32_bf16 v[98:101], v[138:141], v[218:221], v[98:101]
	v_mfma_f32_16x16x32_bf16 v[94:97], v[146:149], v[218:221], v[94:97]
	v_mfma_f32_16x16x32_bf16 v[82:85], v[138:141], v[226:229], v[82:85]
	v_mfma_f32_16x16x32_bf16 v[78:81], v[146:149], v[226:229], v[78:81]
	v_mfma_f32_16x16x32_bf16 v[122:125], v[158:161], v[192:195], v[122:125]
	v_mfma_f32_16x16x32_bf16 v[118:121], v[166:169], v[192:195], v[118:121]
	v_mfma_f32_16x16x32_bf16 v[106:109], v[158:161], v[206:209], v[106:109]
	v_mfma_f32_16x16x32_bf16 v[102:105], v[166:169], v[206:209], v[102:105]
	v_mfma_f32_16x16x32_bf16 v[90:93], v[158:161], v[214:217], v[90:93]
	v_mfma_f32_16x16x32_bf16 v[86:89], v[166:169], v[214:217], v[86:89]
	v_mfma_f32_16x16x32_bf16 v[74:77], v[158:161], v[222:225], v[74:77]
	v_mfma_f32_16x16x32_bf16 v[70:73], v[166:169], v[222:225], v[70:73]
	v_mfma_f32_16x16x32_bf16 v[122:125], v[162:165], v[202:205], v[122:125]
	v_mfma_f32_16x16x32_bf16 v[118:121], v[188:191], v[202:205], v[118:121]
	v_mfma_f32_16x16x32_bf16 v[106:109], v[162:165], v[210:213], v[106:109]
	v_mfma_f32_16x16x32_bf16 v[102:105], v[188:191], v[210:213], v[102:105]
	v_mfma_f32_16x16x32_bf16 v[90:93], v[162:165], v[218:221], v[90:93]
	v_mfma_f32_16x16x32_bf16 v[86:89], v[188:191], v[218:221], v[86:89]
	v_mfma_f32_16x16x32_bf16 v[74:77], v[162:165], v[226:229], v[74:77]
	v_mfma_f32_16x16x32_bf16 v[70:73], v[188:191], v[226:229], v[70:73]
	s_barrier
	s_add_u32 s98, s52, s12
	s_addc_u32 s99, s53, s13
	s_add_u32 s100, s54, s12
	s_addc_u32 s101, s55, s13
	s_add_i32 s81, s68, s56
	s_mov_b32 m0, s81
	ds_read_b128 v[192:195], v200 offset:16384
	ds_read_b128 v[202:205], v200 offset:17408
	ds_read_b128 v[206:209], v200 offset:18432
	ds_read_b128 v[210:213], v200 offset:19456
	ds_read_b128 v[214:217], v200 offset:20480
	ds_read_b128 v[218:221], v200 offset:21504
	ds_read_b128 v[222:225], v200 offset:22528
	ds_read_b128 v[226:229], v200 offset:23552
	global_load_lds_dwordx4 v176, s[52:53]
	s_add_i32 m0, s81, 0x2000
	s_add_u32 s82, s52, 0x40000
	s_addc_u32 s83, s53, 0
	s_add_i32 s81, s69, s56
	global_load_lds_dwordx4 v172, s[52:53]
	s_mov_b32 m0, s81
	s_nop 0
	global_load_lds_dwordx4 v176, s[82:83]
	v_lshl_add_u64 v[4:5], s[82:83], 0, v[172:173]
	s_add_i32 m0, s81, 0x2000
	v_lshl_add_u64 v[234:235], s[54:55], 0, v[174:175]
	global_load_lds_dwordx4 v172, s[82:83]
	s_mov_b32 m0, s59
	s_nop 0
	global_load_lds_dwordx4 v178, s[54:55]
	s_mov_b32 m0, s60
	s_nop 0
	global_load_lds_dwordx4 v174, s[54:55]
	s_waitcnt vmcnt(8)
	s_waitcnt lgkmcnt(0)
	s_barrier
; #define PG8_STAGE(bufoff, gbase, voff) do { _Pragma("unroll") for (int _i = 0; _i < 2; ++_i) \
;         __builtin_amdgcn_global_load_lds((const unsigned*)((const char*)(gbase) + (voff)[_i]), (LAS unsigned*)(lds + (bufoff) + ldsw + _i * 8192), 16, 0, 0); } while (0)
; #define PG8_LDA(dst, b, h) do { _Pragma("unroll") for (int m = 0; m < 4; ++m) _Pragma("unroll") for (int k = 0; k < 2; ++k) dst[m][k] = *(const LAS bf16x8*)(lds + PG8_SA(b, h) + aoff + m * 2048 + k * 1024); } while (0)
; #define PG8_LDB(dst, b, h) do { _Pragma("unroll") for (int n = 0; n < 2; ++n) _Pragma("unroll") for (int k = 0; k < 2; ++k) dst[n][k] = *(const LAS bf16x8*)(lds + PG8_SB(b, h) + boff + n * 2048 + k * 1024); } while (0)
; #define PG8_MMA(ai, bj, At, Bt) do { __builtin_amdgcn_s_setprio(1); _Pragma("unroll") for (int m = 0; m < 4; ++m) _Pragma("unroll") for (int n = 0; n < 2; ++n) _Pragma("unroll") for (int k = 0; k < 2; ++k) \
;         acc[ai][bj][m][n] = __builtin_amdgcn_mfma_f32_16x16x32_bf16(Bt[n][k], At[m][k], acc[ai][bj][m][n], 0, 0, 0); __builtin_amdgcn_s_setprio(0); } while (0)
; #define PG8_WAIT_V(n) asm volatile("s_waitcnt vmcnt(" #n ")" ::: "memory")
; #define PG8_BAR __builtin_amdgcn_s_barrier()
; template <class Epi>
; __device__ __forceinline__ void gemm_phase(LAS unsigned char* lds, const Gemm g, const StaticOrder& S, const Epi& E) {
;     ...
;             PG8_LDB(B0, 0, 0); PG8_LDB(B1, 0, 1); PG8_SCHED; PG8_LDA(At, 0, 0); PG8_STAGE(PG8_SA(1, 1), a1 + hstep, voffA);
;             PG8_WAIT_V(8); PG8_WAIT_L(0); PG8_BAR; PG8_MMA(0, 0, At, B0); PG8_MMA(0, 1, At, B1); PG8_BAR; PG8_SCHED;
;             PG8_LDA(At, 0, 1); PG8_STAGE(PG8_SB(0, 0), b2, voffB); PG8_STAGE(PG8_SB(0, 1), b2 + hstep, voffB); PG8_STAGE(PG8_SA(0, 0), a2, voffA);
;             PG8_WAIT_V(8); PG8_WAIT_L(0); PG8_BAR; PG8_MMA(1, 0, At, B0); PG8_MMA(1, 1, At, B1); PG8_BAR; PG8_SCHED;
;             PG8_LDB(B0, 1, 0); PG8_LDB(B1, 1, 1); PG8_SCHED; PG8_LDA(At, 1, 0); PG8_STAGE(PG8_SA(0, 1), a2 + hstep, voffA);
;             PG8_WAIT_V(8); PG8_WAIT_L(0); PG8_BAR; PG8_MMA(0, 0, At, B0); PG8_MMA(0, 1, At, B1); PG8_BAR; PG8_SCHED;
;             PG8_LDA(At, 1, 1); PG8_STAGE(PG8_SB(1, 0), b3, voffB); PG8_STAGE(PG8_SB(1, 1), b3 + hstep, voffB); PG8_STAGE(PG8_SA(1, 0), a3, voffA);
;             PG8_WAIT_V(8); PG8_WAIT_L(0); PG8_BAR; PG8_MMA(1, 0, At, B0); PG8_MMA(1, 1, At, B1); PG8_BAR; PG8_SCHED;
	v_mfma_f32_16x16x32_bf16 v[66:69], v[134:137], v[192:195], v[66:69]
	v_mfma_f32_16x16x32_bf16 v[62:65], v[142:145], v[192:195], v[62:65]
	v_mfma_f32_16x16x32_bf16 v[50:53], v[134:137], v[206:209], v[50:53]
	v_mfma_f32_16x16x32_bf16 v[46:49], v[142:145], v[206:209], v[46:49]
	v_mfma_f32_16x16x32_bf16 v[34:37], v[134:137], v[214:217], v[34:37]
	v_mfma_f32_16x16x32_bf16 v[30:33], v[142:145], v[214:217], v[30:33]
	v_mfma_f32_16x16x32_bf16 v[18:21], v[134:137], v[222:225], v[18:21]
	v_mfma_f32_16x16x32_bf16 v[14:17], v[142:145], v[222:225], v[14:17]
	v_mfma_f32_16x16x32_bf16 v[66:69], v[138:141], v[202:205], v[66:69]
	v_mfma_f32_16x16x32_bf16 v[62:65], v[146:149], v[202:205], v[62:65]
	v_mfma_f32_16x16x32_bf16 v[50:53], v[138:141], v[210:213], v[50:53]
	v_mfma_f32_16x16x32_bf16 v[46:49], v[146:149], v[210:213], v[46:49]
	v_mfma_f32_16x16x32_bf16 v[34:37], v[138:141], v[218:221], v[34:37]
	v_mfma_f32_16x16x32_bf16 v[30:33], v[146:149], v[218:221], v[30:33]
	v_mfma_f32_16x16x32_bf16 v[18:21], v[138:141], v[226:229], v[18:21]
	v_mfma_f32_16x16x32_bf16 v[14:17], v[146:149], v[226:229], v[14:17]
	v_mfma_f32_16x16x32_bf16 v[58:61], v[158:161], v[192:195], v[58:61]
	v_mfma_f32_16x16x32_bf16 v[54:57], v[166:169], v[192:195], v[54:57]
	v_mfma_f32_16x16x32_bf16 v[42:45], v[158:161], v[206:209], v[42:45]
	v_mfma_f32_16x16x32_bf16 v[38:41], v[166:169], v[206:209], v[38:41]
	v_mfma_f32_16x16x32_bf16 v[26:29], v[158:161], v[214:217], v[26:29]
	v_mfma_f32_16x16x32_bf16 v[22:25], v[166:169], v[214:217], v[22:25]
	v_mfma_f32_16x16x32_bf16 v[10:13], v[158:161], v[222:225], v[10:13]
	v_mfma_f32_16x16x32_bf16 v[4:7], v[166:169], v[222:225], v[6:9]
	v_mfma_f32_16x16x32_bf16 v[58:61], v[162:165], v[202:205], v[58:61]
	v_mfma_f32_16x16x32_bf16 v[54:57], v[188:191], v[202:205], v[54:57]
	v_mfma_f32_16x16x32_bf16 v[42:45], v[162:165], v[210:213], v[42:45]
	v_mfma_f32_16x16x32_bf16 v[38:41], v[188:191], v[210:213], v[38:41]
	v_mfma_f32_16x16x32_bf16 v[26:29], v[162:165], v[218:221], v[26:29]
	v_mfma_f32_16x16x32_bf16 v[22:25], v[188:191], v[218:221], v[22:25]
	v_mfma_f32_16x16x32_bf16 v[10:13], v[162:165], v[226:229], v[10:13]
	v_mfma_f32_16x16x32_bf16 v[4:7], v[188:191], v[226:229], v[4:7]
	s_barrier
	s_add_i32 s81, 0, 0x18000
	v_add_u32_e32 v3, s81, v198
	s_add_i32 s82, 0, 0x1c000
	ds_read_b128 v[134:137], v3
	ds_read_b128 v[138:141], v3 offset:1024
	ds_read_b128 v[142:145], v3 offset:2048
	ds_read_b128 v[146:149], v3 offset:3072
	v_add_u32_e32 v3, s82, v198
	ds_read_b128 v[158:161], v3
	ds_read_b128 v[162:165], v3 offset:1024
	ds_read_b128 v[166:169], v3 offset:2048
	ds_read_b128 v[188:191], v3 offset:3072
	s_add_u32 s54, s54, 0x40000
	s_addc_u32 s55, s55, 0
	s_mov_b32 m0, s61
	ds_read_b128 v[192:195], v200 offset:32768
	ds_read_b128 v[202:205], v200 offset:33792
	ds_read_b128 v[206:209], v200 offset:34816
	ds_read_b128 v[210:213], v200 offset:35840
	ds_read_b128 v[214:217], v200 offset:36864
	ds_read_b128 v[218:221], v200 offset:37888
	ds_read_b128 v[222:225], v200 offset:38912
	ds_read_b128 v[226:229], v200 offset:39936
	global_load_lds_dwordx4 v178, s[54:55]
	s_mov_b32 m0, s62
	s_nop 0
	global_load_lds_dwordx4 v174, s[54:55]
	s_waitcnt vmcnt(8)
	s_waitcnt lgkmcnt(0)
	s_barrier
	v_mfma_f32_16x16x32_bf16 v[130:133], v[134:137], v[192:195], v[130:133]
	v_mfma_f32_16x16x32_bf16 v[126:129], v[142:145], v[192:195], v[126:129]
	v_mfma_f32_16x16x32_bf16 v[114:117], v[134:137], v[206:209], v[114:117]
	v_mfma_f32_16x16x32_bf16 v[110:113], v[142:145], v[206:209], v[110:113]
	v_mfma_f32_16x16x32_bf16 v[98:101], v[134:137], v[214:217], v[98:101]
	v_mfma_f32_16x16x32_bf16 v[94:97], v[142:145], v[214:217], v[94:97]
	v_mfma_f32_16x16x32_bf16 v[82:85], v[134:137], v[222:225], v[82:85]
	v_mfma_f32_16x16x32_bf16 v[78:81], v[142:145], v[222:225], v[78:81]
	v_mfma_f32_16x16x32_bf16 v[130:133], v[138:141], v[202:205], v[130:133]
	v_mfma_f32_16x16x32_bf16 v[126:129], v[146:149], v[202:205], v[126:129]
	v_mfma_f32_16x16x32_bf16 v[114:117], v[138:141], v[210:213], v[114:117]
	v_mfma_f32_16x16x32_bf16 v[110:113], v[146:149], v[210:213], v[110:113]
	v_mfma_f32_16x16x32_bf16 v[98:101], v[138:141], v[218:221], v[98:101]
	v_mfma_f32_16x16x32_bf16 v[94:97], v[146:149], v[218:221], v[94:97]
	v_mfma_f32_16x16x32_bf16 v[82:85], v[138:141], v[226:229], v[82:85]
	v_mfma_f32_16x16x32_bf16 v[78:81], v[146:149], v[226:229], v[78:81]
	v_mfma_f32_16x16x32_bf16 v[122:125], v[158:161], v[192:195], v[122:125]
	v_mfma_f32_16x16x32_bf16 v[118:121], v[166:169], v[192:195], v[118:121]
	v_mfma_f32_16x16x32_bf16 v[106:109], v[158:161], v[206:209], v[106:109]
	v_mfma_f32_16x16x32_bf16 v[102:105], v[166:169], v[206:209], v[102:105]
	v_mfma_f32_16x16x32_bf16 v[90:93], v[158:161], v[214:217], v[90:93]
	v_mfma_f32_16x16x32_bf16 v[86:89], v[166:169], v[214:217], v[86:89]
	v_mfma_f32_16x16x32_bf16 v[74:77], v[158:161], v[222:225], v[74:77]
	v_mfma_f32_16x16x32_bf16 v[70:73], v[166:169], v[222:225], v[70:73]
	v_mfma_f32_16x16x32_bf16 v[122:125], v[162:165], v[202:205], v[122:125]
	v_mfma_f32_16x16x32_bf16 v[118:121], v[188:191], v[202:205], v[118:121]
	v_mfma_f32_16x16x32_bf16 v[106:109], v[162:165], v[210:213], v[106:109]
	v_mfma_f32_16x16x32_bf16 v[102:105], v[188:191], v[210:213], v[102:105]
	v_mfma_f32_16x16x32_bf16 v[90:93], v[162:165], v[218:221], v[90:93]
	v_mfma_f32_16x16x32_bf16 v[86:89], v[188:191], v[218:221], v[86:89]
	v_mfma_f32_16x16x32_bf16 v[74:77], v[162:165], v[226:229], v[74:77]
	v_mfma_f32_16x16x32_bf16 v[70:73], v[188:191], v[226:229], v[70:73]
	s_barrier
; #define PG8_STAGE(bufoff, gbase, voff) do { _Pragma("unroll") for (int _i = 0; _i < 2; ++_i) \
;         __builtin_amdgcn_global_load_lds((const unsigned*)((const char*)(gbase) + (voff)[_i]), (LAS unsigned*)(lds + (bufoff) + ldsw + _i * 8192), 16, 0, 0); } while (0)
; #define PG8_LDA(dst, b, h) do { _Pragma("unroll") for (int m = 0; m < 4; ++m) _Pragma("unroll") for (int k = 0; k < 2; ++k) dst[m][k] = *(const LAS bf16x8*)(lds + PG8_SA(b, h) + aoff + m * 2048 + k * 1024); } while (0)
; #define PG8_LDB(dst, b, h) do { _Pragma("unroll") for (int n = 0; n < 2; ++n) _Pragma("unroll") for (int k = 0; k < 2; ++k) dst[n][k] = *(const LAS bf16x8*)(lds + PG8_SB(b, h) + boff + n * 2048 + k * 1024); } while (0)
; #define PG8_MMA(ai, bj, At, Bt) do { __builtin_amdgcn_s_setprio(1); _Pragma("unroll") for (int m = 0; m < 4; ++m) _Pragma("unroll") for (int n = 0; n < 2; ++n) _Pragma("unroll") for (int k = 0; k < 2; ++k) \
;         acc[ai][bj][m][n] = __builtin_amdgcn_mfma_f32_16x16x32_bf16(Bt[n][k], At[m][k], acc[ai][bj][m][n], 0, 0, 0); __builtin_amdgcn_s_setprio(0); } while (0)
; #define PG8_WAIT_V(n) asm volatile("s_waitcnt vmcnt(" #n ")" ::: "memory")
; #define PG8_BAR __builtin_amdgcn_s_barrier()
; template <class Epi>
; __device__ __forceinline__ void gemm_phase(LAS unsigned char* lds, const Gemm g, const StaticOrder& S, const Epi& E) {
;     ...
;             PG8_LDB(B0, 0, 0); PG8_LDB(B1, 0, 1); PG8_SCHED; PG8_LDA(At, 0, 0); PG8_STAGE(PG8_SA(1, 1), a1 + hstep, voffA);
;             PG8_WAIT_V(8); PG8_WAIT_L(0); PG8_BAR; PG8_MMA(0, 0, At, B0); PG8_MMA(0, 1, At, B1); PG8_BAR; PG8_SCHED;
;             PG8_LDA(At, 0, 1); PG8_STAGE(PG8_SB(0, 0), b2, voffB); PG8_STAGE(PG8_SB(0, 1), b2 + hstep, voffB); PG8_STAGE(PG8_SA(0, 0), a2, voffA);
;             PG8_WAIT_V(8); PG8_WAIT_L(0); PG8_BAR; PG8_MMA(1, 0, At, B0); PG8_MMA(1, 1, At, B1); PG8_BAR; PG8_SCHED;
;             PG8_LDB(B0, 1, 0); PG8_LDB(B1, 1, 1); PG8_SCHED; PG8_LDA(At, 1, 0); PG8_STAGE(PG8_SA(0, 1), a2 + hstep, voffA);
;             PG8_WAIT_V(8); PG8_WAIT_L(0); PG8_BAR; PG8_MMA(0, 0, At, B0); PG8_MMA(0, 1, At, B1); PG8_BAR; PG8_SCHED;
;             PG8_LDA(At, 1, 1); PG8_STAGE(PG8_SB(1, 0), b3, voffB); PG8_STAGE(PG8_SB(1, 1), b3 + hstep, voffB); PG8_STAGE(PG8_SA(1, 0), a3, voffA);
;             PG8_WAIT_V(8); PG8_WAIT_L(0); PG8_BAR; PG8_MMA(1, 0, At, B0); PG8_MMA(1, 1, At, B1); PG8_BAR; PG8_SCHED;
	s_add_i32 s54, s81, s56
	s_mov_b32 m0, s54
	ds_read_b128 v[192:195], v200 offset:49152
	ds_read_b128 v[202:205], v200 offset:50176
	ds_read_b128 v[206:209], v200 offset:51200
	ds_read_b128 v[210:213], v200 offset:52224
	ds_read_b128 v[214:217], v200 offset:53248
	ds_read_b128 v[218:221], v200 offset:54272
	ds_read_b128 v[222:225], v200 offset:55296
	ds_read_b128 v[226:229], v200 offset:56320
	global_load_lds_dwordx4 v176, s[98:99]
	s_add_i32 m0, s54, 0x2000
	s_add_u32 s52, s52, 0x40080
	s_addc_u32 s53, s53, 0
	s_add_i32 s54, s82, s56
	global_load_lds_dwordx4 v172, s[98:99]
	s_mov_b32 m0, s54
	s_nop 0
	global_load_lds_dwordx4 v176, s[52:53]
	s_add_i32 m0, s54, 0x2000
	s_nop 0
	global_load_lds_dwordx4 v172, s[52:53]
	s_mov_b32 m0, s64
	s_nop 0
	global_load_lds_dwordx4 v178, s[100:101]
	v_lshl_add_u64 v[8:9], v[234:235], 0, s[12:13]
	s_mov_b32 m0, s65
	s_nop 0
	global_load_lds_dwordx4 v174, s[100:101]
	s_waitcnt vmcnt(8)
	s_waitcnt lgkmcnt(0)
	s_barrier
	v_mfma_f32_16x16x32_bf16 v[66:69], v[134:137], v[192:195], v[66:69]
	v_mfma_f32_16x16x32_bf16 v[62:65], v[142:145], v[192:195], v[62:65]
	v_mfma_f32_16x16x32_bf16 v[50:53], v[134:137], v[206:209], v[50:53]
	v_mfma_f32_16x16x32_bf16 v[46:49], v[142:145], v[206:209], v[46:49]
	v_mfma_f32_16x16x32_bf16 v[34:37], v[134:137], v[214:217], v[34:37]
	v_mfma_f32_16x16x32_bf16 v[30:33], v[142:145], v[214:217], v[30:33]
	v_mfma_f32_16x16x32_bf16 v[18:21], v[134:137], v[222:225], v[18:21]
	v_mfma_f32_16x16x32_bf16 v[14:17], v[142:145], v[222:225], v[14:17]
	v_mfma_f32_16x16x32_bf16 v[66:69], v[138:141], v[202:205], v[66:69]
	v_mfma_f32_16x16x32_bf16 v[62:65], v[146:149], v[202:205], v[62:65]
	v_mfma_f32_16x16x32_bf16 v[50:53], v[138:141], v[210:213], v[50:53]
	v_mfma_f32_16x16x32_bf16 v[46:49], v[146:149], v[210:213], v[46:49]
	v_mfma_f32_16x16x32_bf16 v[34:37], v[138:141], v[218:221], v[34:37]
	v_mfma_f32_16x16x32_bf16 v[30:33], v[146:149], v[218:221], v[30:33]
	v_mfma_f32_16x16x32_bf16 v[18:21], v[138:141], v[226:229], v[18:21]
	v_mfma_f32_16x16x32_bf16 v[14:17], v[146:149], v[226:229], v[14:17]
	v_mfma_f32_16x16x32_bf16 v[58:61], v[158:161], v[192:195], v[58:61]
	v_mfma_f32_16x16x32_bf16 v[54:57], v[166:169], v[192:195], v[54:57]
	v_mfma_f32_16x16x32_bf16 v[42:45], v[158:161], v[206:209], v[42:45]
	v_mfma_f32_16x16x32_bf16 v[38:41], v[166:169], v[206:209], v[38:41]
	v_mfma_f32_16x16x32_bf16 v[26:29], v[158:161], v[214:217], v[26:29]
	v_mfma_f32_16x16x32_bf16 v[22:25], v[166:169], v[214:217], v[22:25]
	v_mfma_f32_16x16x32_bf16 v[8:11], v[158:161], v[222:225], v[10:13]
	v_mfma_f32_16x16x32_bf16 v[4:7], v[166:169], v[222:225], v[4:7]
	v_mfma_f32_16x16x32_bf16 v[58:61], v[162:165], v[202:205], v[58:61]
	v_mfma_f32_16x16x32_bf16 v[54:57], v[188:191], v[202:205], v[54:57]
	v_mfma_f32_16x16x32_bf16 v[42:45], v[162:165], v[210:213], v[42:45]
	v_mfma_f32_16x16x32_bf16 v[38:41], v[188:191], v[210:213], v[38:41]
	v_mfma_f32_16x16x32_bf16 v[26:29], v[162:165], v[218:221], v[26:29]
	v_mfma_f32_16x16x32_bf16 v[22:25], v[188:191], v[218:221], v[22:25]
	v_mfma_f32_16x16x32_bf16 v[10:13], v[162:165], v[226:229], v[8:11]
	v_mfma_f32_16x16x32_bf16 v[6:9], v[188:191], v[226:229], v[4:7]
	s_barrier
	s_add_i32 s80, s80, 2
	s_add_u32 s50, s50, 0x100
	s_addc_u32 s51, s51, 0
	s_cmp_gt_u32 s80, 13
	s_cbranch_scc1 .LBB0_703

; #define PG8_STAGE(bufoff, gbase, voff) do { _Pragma("unroll") for (int _i = 0; _i < 2; ++_i) \
;         __builtin_amdgcn_global_load_lds((const unsigned*)((const char*)(gbase) + (voff)[_i]), (LAS unsigned*)(lds + (bufoff) + ldsw + _i * 8192), 16, 0, 0); } while (0)
; #define PG8_LDA(dst, b, h) do { _Pragma("unroll") for (int m = 0; m < 4; ++m) _Pragma("unroll") for (int k = 0; k < 2; ++k) dst[m][k] = *(const LAS bf16x8*)(lds + PG8_SA(b, h) + aoff + m * 2048 + k * 1024); } while (0)
; #define PG8_LDB(dst, b, h) do { _Pragma("unroll") for (int n = 0; n < 2; ++n) _Pragma("unroll") for (int k = 0; k < 2; ++k) dst[n][k] = *(const LAS bf16x8*)(lds + PG8_SB(b, h) + boff + n * 2048 + k * 1024); } while (0)
; #define PG8_MMA(ai, bj, At, Bt) do { __builtin_amdgcn_s_setprio(1); _Pragma("unroll") for (int m = 0; m < 4; ++m) _Pragma("unroll") for (int n = 0; n < 2; ++n) _Pragma("unroll") for (int k = 0; k < 2; ++k) \
;         acc[ai][bj][m][n] = __builtin_amdgcn_mfma_f32_16x16x32_bf16(Bt[n][k], At[m][k], acc[ai][bj][m][n], 0, 0, 0); __builtin_amdgcn_s_setprio(0); } while (0)
; #define PG8_WAIT_V(n) asm volatile("s_waitcnt vmcnt(" #n ")" ::: "memory")
; #define PG8_WAIT_L(n) asm volatile("s_waitcnt lgkmcnt(" #n ")" ::: "memory")
; #define PG8_BAR __builtin_amdgcn_s_barrier()
; template <class Epi>
; __device__ __forceinline__ void gemm_phase(LAS unsigned char* lds, const Gemm g, const StaticOrder& S, const Epi& E) {
;     ...
;         for (int t = 0; t < nt; t += 2) {
;             const bool last = (t == nt - 2);
;             const char* a1 = cA + (size_t)(t + 1) * kstep;
;             const char* a2 = last ? nA : cA + (size_t)(t + 2) * kstep; const char* b2 = last ? nB : cB + (size_t)(t + 2) * kstep;
;             const char* a3 = a2 + kstep; const char* b3 = b2 + kstep;
;             if constexpr (Epi::MIDK > 0) { if (t == Epi::MIDK) E.mid(acc, cur, wr, wc, fr, fq); }
;             PG8_LDB(B0, 0, 0); PG8_LDB(B1, 0, 1); PG8_SCHED; PG8_LDA(At, 0, 0); PG8_STAGE(PG8_SA(1, 1), a1 + hstep, voffA);
;             PG8_WAIT_V(8); PG8_WAIT_L(0); PG8_BAR; PG8_MMA(0, 0, At, B0); PG8_MMA(0, 1, At, B1); PG8_BAR; PG8_SCHED;
;             PG8_LDA(At, 0, 1); PG8_STAGE(PG8_SB(0, 0), b2, voffB); PG8_STAGE(PG8_SB(0, 1), b2 + hstep, voffB); PG8_STAGE(PG8_SA(0, 0), a2, voffA);
;             PG8_WAIT_V(8); PG8_WAIT_L(0); PG8_BAR; PG8_MMA(1, 0, At, B0); PG8_MMA(1, 1, At, B1); PG8_BAR; PG8_SCHED;
.LBB0_785:
	ds_read_b128 v[130:133], v162
	ds_read_b128 v[134:137], v162 offset:1024
	ds_read_b128 v[154:157], v162 offset:2048
	ds_read_b128 v[166:169], v162 offset:3072
	ds_read_b128 v[172:175], v163
	ds_read_b128 v[176:179], v163 offset:1024
	ds_read_b128 v[180:183], v163 offset:2048
	ds_read_b128 v[184:187], v163 offset:3072
	s_add_u32 s40, s38, 0xfffc0080
	s_addc_u32 s41, s39, -1
	s_cmp_eq_u32 s63, 12
	s_cselect_b32 s43, s21, s41
	s_cselect_b32 s42, s27, s40
	s_cselect_b32 s41, s19, s62
	s_cselect_b32 s40, s60, s61
	s_add_i32 m0, s45, 0xc000
	ds_read_b128 v[188:191], v164
	ds_read_b128 v[192:195], v164 offset:1024
	ds_read_b128 v[196:199], v164 offset:2048
	ds_read_b128 v[200:203], v164 offset:3072
	ds_read_b128 v[204:207], v164 offset:4096
	ds_read_b128 v[208:211], v164 offset:5120
	ds_read_b128 v[212:215], v164 offset:6144
	ds_read_b128 v[216:219], v164 offset:7168
	global_load_lds_dwordx4 v146, s[38:39]
	s_add_i32 m0, s45, 0xe000
	s_nop 0
	global_load_lds_dwordx4 v148, s[38:39]
	s_waitcnt vmcnt(8)
	s_waitcnt lgkmcnt(0)
	s_barrier
	v_mfma_f32_16x16x32_bf16 v[126:129], v[130:133], v[188:191], v[126:129]
	v_mfma_f32_16x16x32_bf16 v[122:125], v[154:157], v[188:191], v[122:125]
	v_mfma_f32_16x16x32_bf16 v[110:113], v[130:133], v[196:199], v[110:113]
	v_mfma_f32_16x16x32_bf16 v[106:109], v[154:157], v[196:199], v[106:109]
	v_mfma_f32_16x16x32_bf16 v[94:97], v[130:133], v[204:207], v[94:97]
	v_mfma_f32_16x16x32_bf16 v[90:93], v[154:157], v[204:207], v[90:93]
	v_mfma_f32_16x16x32_bf16 v[78:81], v[130:133], v[212:215], v[78:81]
	v_mfma_f32_16x16x32_bf16 v[74:77], v[154:157], v[212:215], v[74:77]
	v_mfma_f32_16x16x32_bf16 v[126:129], v[134:137], v[192:195], v[126:129]
	v_mfma_f32_16x16x32_bf16 v[122:125], v[166:169], v[192:195], v[122:125]
	v_mfma_f32_16x16x32_bf16 v[110:113], v[134:137], v[200:203], v[110:113]
	v_mfma_f32_16x16x32_bf16 v[106:109], v[166:169], v[200:203], v[106:109]
	v_mfma_f32_16x16x32_bf16 v[94:97], v[134:137], v[208:211], v[94:97]
	v_mfma_f32_16x16x32_bf16 v[90:93], v[166:169], v[208:211], v[90:93]
	v_mfma_f32_16x16x32_bf16 v[78:81], v[134:137], v[216:219], v[78:81]
	v_mfma_f32_16x16x32_bf16 v[74:77], v[166:169], v[216:219], v[74:77]
	v_mfma_f32_16x16x32_bf16 v[118:121], v[172:175], v[188:191], v[118:121]
	v_mfma_f32_16x16x32_bf16 v[114:117], v[180:183], v[188:191], v[114:117]
	v_mfma_f32_16x16x32_bf16 v[102:105], v[172:175], v[196:199], v[102:105]
	v_mfma_f32_16x16x32_bf16 v[98:101], v[180:183], v[196:199], v[98:101]
	v_mfma_f32_16x16x32_bf16 v[86:89], v[172:175], v[204:207], v[86:89]
	v_mfma_f32_16x16x32_bf16 v[82:85], v[180:183], v[204:207], v[82:85]
	v_mfma_f32_16x16x32_bf16 v[70:73], v[172:175], v[212:215], v[70:73]
	v_mfma_f32_16x16x32_bf16 v[66:69], v[180:183], v[212:215], v[66:69]
	v_mfma_f32_16x16x32_bf16 v[118:121], v[176:179], v[192:195], v[118:121]
	v_mfma_f32_16x16x32_bf16 v[114:117], v[184:187], v[192:195], v[114:117]
	v_mfma_f32_16x16x32_bf16 v[102:105], v[176:179], v[200:203], v[102:105]
	v_mfma_f32_16x16x32_bf16 v[98:101], v[184:187], v[200:203], v[98:101]
	v_mfma_f32_16x16x32_bf16 v[86:89], v[176:179], v[208:211], v[86:89]
	v_mfma_f32_16x16x32_bf16 v[82:85], v[184:187], v[208:211], v[82:85]
	v_mfma_f32_16x16x32_bf16 v[70:73], v[176:179], v[216:219], v[70:73]
	v_mfma_f32_16x16x32_bf16 v[66:69], v[184:187], v[216:219], v[66:69]
	s_barrier
	s_add_u32 s98, s40, s12
	s_addc_u32 s99, s41, s13
	s_add_u32 s100, s42, s12
	s_addc_u32 s101, s43, s13
	s_add_i32 s64, s57, s44
	s_mov_b32 m0, s64
	ds_read_b128 v[188:191], v164 offset:16384
	ds_read_b128 v[192:195], v164 offset:17408
	ds_read_b128 v[196:199], v164 offset:18432
	ds_read_b128 v[200:203], v164 offset:19456
	ds_read_b128 v[204:207], v164 offset:20480
	ds_read_b128 v[208:211], v164 offset:21504
	ds_read_b128 v[212:215], v164 offset:22528
	ds_read_b128 v[216:219], v164 offset:23552
	global_load_lds_dwordx4 v140, s[40:41]
	s_add_i32 m0, s64, 0x2000
	s_add_u32 s64, s40, 0x40000
	s_addc_u32 s65, s41, 0
	s_add_i32 s66, s58, s44
	global_load_lds_dwordx4 v144, s[40:41]
	s_mov_b32 m0, s66
	s_nop 0
	global_load_lds_dwordx4 v140, s[64:65]
	s_add_i32 m0, s66, 0x2000
	s_nop 0
	global_load_lds_dwordx4 v144, s[64:65]
	s_mov_b32 m0, s45
	s_nop 0
	global_load_lds_dwordx4 v138, s[42:43]
	s_mov_b32 m0, s46
	s_nop 0
	global_load_lds_dwordx4 v142, s[42:43]
	s_waitcnt vmcnt(8)
	s_waitcnt lgkmcnt(0)
	s_barrier
	v_mfma_f32_16x16x32_bf16 v[62:65], v[130:133], v[188:191], v[62:65]
	v_mfma_f32_16x16x32_bf16 v[58:61], v[154:157], v[188:191], v[58:61]
	v_mfma_f32_16x16x32_bf16 v[46:49], v[130:133], v[196:199], v[46:49]
	v_mfma_f32_16x16x32_bf16 v[42:45], v[154:157], v[196:199], v[42:45]
	v_mfma_f32_16x16x32_bf16 v[30:33], v[130:133], v[204:207], v[30:33]
	v_mfma_f32_16x16x32_bf16 v[26:29], v[154:157], v[204:207], v[26:29]
	v_mfma_f32_16x16x32_bf16 v[14:17], v[130:133], v[212:215], v[14:17]
	v_mfma_f32_16x16x32_bf16 v[10:13], v[154:157], v[212:215], v[10:13]
	v_mfma_f32_16x16x32_bf16 v[62:65], v[134:137], v[192:195], v[62:65]
	v_mfma_f32_16x16x32_bf16 v[58:61], v[166:169], v[192:195], v[58:61]
	v_mfma_f32_16x16x32_bf16 v[46:49], v[134:137], v[200:203], v[46:49]
	v_mfma_f32_16x16x32_bf16 v[42:45], v[166:169], v[200:203], v[42:45]
	v_mfma_f32_16x16x32_bf16 v[30:33], v[134:137], v[208:211], v[30:33]
	v_mfma_f32_16x16x32_bf16 v[26:29], v[166:169], v[208:211], v[26:29]
	v_mfma_f32_16x16x32_bf16 v[14:17], v[134:137], v[216:219], v[14:17]
	v_mfma_f32_16x16x32_bf16 v[10:13], v[166:169], v[216:219], v[10:13]
	v_mfma_f32_16x16x32_bf16 v[54:57], v[172:175], v[188:191], v[54:57]
	v_mfma_f32_16x16x32_bf16 v[50:53], v[180:183], v[188:191], v[50:53]
	v_mfma_f32_16x16x32_bf16 v[38:41], v[172:175], v[196:199], v[38:41]
	v_mfma_f32_16x16x32_bf16 v[34:37], v[180:183], v[196:199], v[34:37]
	v_mfma_f32_16x16x32_bf16 v[22:25], v[172:175], v[204:207], v[22:25]
	v_mfma_f32_16x16x32_bf16 v[18:21], v[180:183], v[204:207], v[18:21]
	v_mfma_f32_16x16x32_bf16 v[6:9], v[172:175], v[212:215], v[6:9]
	v_mfma_f32_16x16x32_bf16 v[2:5], v[180:183], v[212:215], v[2:5]
	v_mfma_f32_16x16x32_bf16 v[54:57], v[176:179], v[192:195], v[54:57]
	v_mfma_f32_16x16x32_bf16 v[50:53], v[184:187], v[192:195], v[50:53]
	v_mfma_f32_16x16x32_bf16 v[38:41], v[176:179], v[200:203], v[38:41]
	v_mfma_f32_16x16x32_bf16 v[34:37], v[184:187], v[200:203], v[34:37]
	v_mfma_f32_16x16x32_bf16 v[22:25], v[176:179], v[208:211], v[22:25]
	v_mfma_f32_16x16x32_bf16 v[18:21], v[184:187], v[208:211], v[18:21]
	v_mfma_f32_16x16x32_bf16 v[6:9], v[176:179], v[216:219], v[6:9]
	v_mfma_f32_16x16x32_bf16 v[2:5], v[184:187], v[216:219], v[2:5]
	s_barrier
; #define PG8_STAGE(bufoff, gbase, voff) do { _Pragma("unroll") for (int _i = 0; _i < 2; ++_i) \
;         __builtin_amdgcn_global_load_lds((const unsigned*)((const char*)(gbase) + (voff)[_i]), (LAS unsigned*)(lds + (bufoff) + ldsw + _i * 8192), 16, 0, 0); } while (0)
; #define PG8_LDA(dst, b, h) do { _Pragma("unroll") for (int m = 0; m < 4; ++m) _Pragma("unroll") for (int k = 0; k < 2; ++k) dst[m][k] = *(const LAS bf16x8*)(lds + PG8_SA(b, h) + aoff + m * 2048 + k * 1024); } while (0)
; #define PG8_LDB(dst, b, h) do { _Pragma("unroll") for (int n = 0; n < 2; ++n) _Pragma("unroll") for (int k = 0; k < 2; ++k) dst[n][k] = *(const LAS bf16x8*)(lds + PG8_SB(b, h) + boff + n * 2048 + k * 1024); } while (0)
; #define PG8_MMA(ai, bj, At, Bt) do { __builtin_amdgcn_s_setprio(1); _Pragma("unroll") for (int m = 0; m < 4; ++m) _Pragma("unroll") for (int n = 0; n < 2; ++n) _Pragma("unroll") for (int k = 0; k < 2; ++k) \
;         acc[ai][bj][m][n] = __builtin_amdgcn_mfma_f32_16x16x32_bf16(Bt[n][k], At[m][k], acc[ai][bj][m][n], 0, 0, 0); __builtin_amdgcn_s_setprio(0); } while (0)
; #define PG8_WAIT_V(n) asm volatile("s_waitcnt vmcnt(" #n ")" ::: "memory")
; #define PG8_WAIT_L(n) asm volatile("s_waitcnt lgkmcnt(" #n ")" ::: "memory")
; #define PG8_BAR __builtin_amdgcn_s_barrier()
; #define PG8_SCHED __builtin_amdgcn_sched_barrier(0)
; template <class Epi>
; __device__ __forceinline__ void gemm_phase(LAS unsigned char* lds, const Gemm g, const StaticOrder& S, const Epi& E) {
;     ...
;             PG8_LDB(B0, 1, 0); PG8_LDB(B1, 1, 1); PG8_SCHED; PG8_LDA(At, 1, 0); PG8_STAGE(PG8_SA(0, 1), a2 + hstep, voffA);
;             PG8_WAIT_V(8); PG8_WAIT_L(0); PG8_BAR; PG8_MMA(0, 0, At, B0); PG8_MMA(0, 1, At, B1); PG8_BAR; PG8_SCHED;
;             PG8_LDA(At, 1, 1); PG8_STAGE(PG8_SB(1, 0), b3, voffB); PG8_STAGE(PG8_SB(1, 1), b3 + hstep, voffB); PG8_STAGE(PG8_SA(1, 0), a3, voffA);
;             PG8_WAIT_V(8); PG8_WAIT_L(0); PG8_BAR; PG8_MMA(1, 0, At, B0); PG8_MMA(1, 1, At, B1); PG8_BAR; PG8_SCHED;
;         }
	s_add_i32 s64, 0, 0x18000
	s_add_i32 s65, 0, 0x1c000
	v_add_u32_e32 v166, s64, v160
	v_add_u32_e32 v184, s65, v160
	ds_read_b128 v[130:133], v166
	ds_read_b128 v[134:137], v166 offset:1024
	ds_read_b128 v[154:157], v166 offset:2048
	ds_read_b128 v[166:169], v166 offset:3072
	ds_read_b128 v[172:175], v184
	ds_read_b128 v[176:179], v184 offset:1024
	ds_read_b128 v[180:183], v184 offset:2048
	ds_read_b128 v[184:187], v184 offset:3072
	s_add_u32 s42, s42, 0x40000
	s_addc_u32 s43, s43, 0
	s_mov_b32 m0, s47
	ds_read_b128 v[188:191], v164 offset:32768
	ds_read_b128 v[192:195], v164 offset:33792
	ds_read_b128 v[196:199], v164 offset:34816
	ds_read_b128 v[200:203], v164 offset:35840
	ds_read_b128 v[204:207], v164 offset:36864
	ds_read_b128 v[208:211], v164 offset:37888
	ds_read_b128 v[212:215], v164 offset:38912
	ds_read_b128 v[216:219], v164 offset:39936
	global_load_lds_dwordx4 v138, s[42:43]
	s_mov_b32 m0, s48
	s_nop 0
	global_load_lds_dwordx4 v142, s[42:43]
	s_waitcnt vmcnt(8)
	s_waitcnt lgkmcnt(0)
	s_barrier
	v_mfma_f32_16x16x32_bf16 v[126:129], v[130:133], v[188:191], v[126:129]
	v_mfma_f32_16x16x32_bf16 v[122:125], v[154:157], v[188:191], v[122:125]
	v_mfma_f32_16x16x32_bf16 v[110:113], v[130:133], v[196:199], v[110:113]
	v_mfma_f32_16x16x32_bf16 v[106:109], v[154:157], v[196:199], v[106:109]
	v_mfma_f32_16x16x32_bf16 v[94:97], v[130:133], v[204:207], v[94:97]
	v_mfma_f32_16x16x32_bf16 v[90:93], v[154:157], v[204:207], v[90:93]
	v_mfma_f32_16x16x32_bf16 v[78:81], v[130:133], v[212:215], v[78:81]
	v_mfma_f32_16x16x32_bf16 v[74:77], v[154:157], v[212:215], v[74:77]
	v_mfma_f32_16x16x32_bf16 v[126:129], v[134:137], v[192:195], v[126:129]
	v_mfma_f32_16x16x32_bf16 v[122:125], v[166:169], v[192:195], v[122:125]
	v_mfma_f32_16x16x32_bf16 v[110:113], v[134:137], v[200:203], v[110:113]
	v_mfma_f32_16x16x32_bf16 v[106:109], v[166:169], v[200:203], v[106:109]
	v_mfma_f32_16x16x32_bf16 v[94:97], v[134:137], v[208:211], v[94:97]
	v_mfma_f32_16x16x32_bf16 v[90:93], v[166:169], v[208:211], v[90:93]
	v_mfma_f32_16x16x32_bf16 v[78:81], v[134:137], v[216:219], v[78:81]
	v_mfma_f32_16x16x32_bf16 v[74:77], v[166:169], v[216:219], v[74:77]
	v_mfma_f32_16x16x32_bf16 v[118:121], v[172:175], v[188:191], v[118:121]
	v_mfma_f32_16x16x32_bf16 v[114:117], v[180:183], v[188:191], v[114:117]
	v_mfma_f32_16x16x32_bf16 v[102:105], v[172:175], v[196:199], v[102:105]
	v_mfma_f32_16x16x32_bf16 v[98:101], v[180:183], v[196:199], v[98:101]
	v_mfma_f32_16x16x32_bf16 v[86:89], v[172:175], v[204:207], v[86:89]
	v_mfma_f32_16x16x32_bf16 v[82:85], v[180:183], v[204:207], v[82:85]
	v_mfma_f32_16x16x32_bf16 v[70:73], v[172:175], v[212:215], v[70:73]
	v_mfma_f32_16x16x32_bf16 v[66:69], v[180:183], v[212:215], v[66:69]
	v_mfma_f32_16x16x32_bf16 v[118:121], v[176:179], v[192:195], v[118:121]
	v_mfma_f32_16x16x32_bf16 v[114:117], v[184:187], v[192:195], v[114:117]
	v_mfma_f32_16x16x32_bf16 v[102:105], v[176:179], v[200:203], v[102:105]
	v_mfma_f32_16x16x32_bf16 v[98:101], v[184:187], v[200:203], v[98:101]
	v_mfma_f32_16x16x32_bf16 v[86:89], v[176:179], v[208:211], v[86:89]
	v_mfma_f32_16x16x32_bf16 v[82:85], v[184:187], v[208:211], v[82:85]
	v_mfma_f32_16x16x32_bf16 v[70:73], v[176:179], v[216:219], v[70:73]
	v_mfma_f32_16x16x32_bf16 v[66:69], v[184:187], v[216:219], v[66:69]
	s_barrier
	s_add_i32 s42, s64, s44
	s_mov_b32 m0, s42
	ds_read_b128 v[188:191], v164 offset:49152
	ds_read_b128 v[192:195], v164 offset:50176
	ds_read_b128 v[196:199], v164 offset:51200
	ds_read_b128 v[200:203], v164 offset:52224
	ds_read_b128 v[204:207], v164 offset:53248
	ds_read_b128 v[208:211], v164 offset:54272
	ds_read_b128 v[212:215], v164 offset:55296
	ds_read_b128 v[216:219], v164 offset:56320
	global_load_lds_dwordx4 v140, s[98:99]
	s_add_i32 m0, s42, 0x2000
	s_add_u32 s40, s40, 0x40080
	s_addc_u32 s41, s41, 0
	s_add_i32 s42, s65, s44
	global_load_lds_dwordx4 v144, s[98:99]
	s_mov_b32 m0, s42
	s_nop 0
	global_load_lds_dwordx4 v140, s[40:41]
	s_add_i32 m0, s42, 0x2000
	s_nop 0
	global_load_lds_dwordx4 v144, s[40:41]
	s_mov_b32 m0, s50
	s_nop 0
	global_load_lds_dwordx4 v138, s[100:101]
	s_mov_b32 m0, s51
	s_nop 0
	global_load_lds_dwordx4 v142, s[100:101]
	s_waitcnt vmcnt(8)
	s_waitcnt lgkmcnt(0)
	s_barrier
	v_mfma_f32_16x16x32_bf16 v[62:65], v[130:133], v[188:191], v[62:65]
	v_mfma_f32_16x16x32_bf16 v[58:61], v[154:157], v[188:191], v[58:61]
	v_mfma_f32_16x16x32_bf16 v[46:49], v[130:133], v[196:199], v[46:49]
	v_mfma_f32_16x16x32_bf16 v[42:45], v[154:157], v[196:199], v[42:45]
	v_mfma_f32_16x16x32_bf16 v[30:33], v[130:133], v[204:207], v[30:33]
	v_mfma_f32_16x16x32_bf16 v[26:29], v[154:157], v[204:207], v[26:29]
	v_mfma_f32_16x16x32_bf16 v[14:17], v[130:133], v[212:215], v[14:17]
	v_mfma_f32_16x16x32_bf16 v[10:13], v[154:157], v[212:215], v[10:13]
	v_mfma_f32_16x16x32_bf16 v[62:65], v[134:137], v[192:195], v[62:65]
	v_mfma_f32_16x16x32_bf16 v[58:61], v[166:169], v[192:195], v[58:61]
	v_mfma_f32_16x16x32_bf16 v[46:49], v[134:137], v[200:203], v[46:49]
	v_mfma_f32_16x16x32_bf16 v[42:45], v[166:169], v[200:203], v[42:45]
	v_mfma_f32_16x16x32_bf16 v[30:33], v[134:137], v[208:211], v[30:33]
	v_mfma_f32_16x16x32_bf16 v[26:29], v[166:169], v[208:211], v[26:29]
	v_mfma_f32_16x16x32_bf16 v[14:17], v[134:137], v[216:219], v[14:17]
	v_mfma_f32_16x16x32_bf16 v[10:13], v[166:169], v[216:219], v[10:13]
	v_mfma_f32_16x16x32_bf16 v[54:57], v[172:175], v[188:191], v[54:57]
	v_mfma_f32_16x16x32_bf16 v[50:53], v[180:183], v[188:191], v[50:53]
	v_mfma_f32_16x16x32_bf16 v[38:41], v[172:175], v[196:199], v[38:41]
	v_mfma_f32_16x16x32_bf16 v[34:37], v[180:183], v[196:199], v[34:37]
	v_mfma_f32_16x16x32_bf16 v[22:25], v[172:175], v[204:207], v[22:25]
	v_mfma_f32_16x16x32_bf16 v[18:21], v[180:183], v[204:207], v[18:21]
	v_mfma_f32_16x16x32_bf16 v[6:9], v[172:175], v[212:215], v[6:9]
	v_mfma_f32_16x16x32_bf16 v[2:5], v[180:183], v[212:215], v[2:5]
	v_mfma_f32_16x16x32_bf16 v[54:57], v[176:179], v[192:195], v[54:57]
	v_mfma_f32_16x16x32_bf16 v[50:53], v[184:187], v[192:195], v[50:53]
	v_mfma_f32_16x16x32_bf16 v[38:41], v[176:179], v[200:203], v[38:41]
	v_mfma_f32_16x16x32_bf16 v[34:37], v[184:187], v[200:203], v[34:37]
	v_mfma_f32_16x16x32_bf16 v[22:25], v[176:179], v[208:211], v[22:25]
	v_mfma_f32_16x16x32_bf16 v[18:21], v[184:187], v[208:211], v[18:21]
	v_mfma_f32_16x16x32_bf16 v[6:9], v[176:179], v[216:219], v[6:9]
	v_mfma_f32_16x16x32_bf16 v[2:5], v[184:187], v[216:219], v[2:5]
	s_barrier
	s_add_i32 s63, s63, 2
	s_add_u32 s38, s38, 0x100
	s_addc_u32 s39, s39, 0
	s_add_u32 s61, s61, 0x100
	s_addc_u32 s62, s62, 0
	s_cmp_gt_u32 s63, 13
	s_cbranch_scc0 .LBB0_785
	s_and_b64 vcc, exec, s[14:15]
	s_cbranch_vccz .LBB0_788
	s_barrier

; #define PG8_STAGE(bufoff, gbase, voff) do { _Pragma("unroll") for (int _i = 0; _i < 2; ++_i) \
;         __builtin_amdgcn_global_load_lds((const unsigned*)((const char*)(gbase) + (voff)[_i]), (LAS unsigned*)(lds + (bufoff) + ldsw + _i * 8192), 16, 0, 0); } while (0)
; #define PG8_LDA(dst, b, h) do { _Pragma("unroll") for (int m = 0; m < 4; ++m) _Pragma("unroll") for (int k = 0; k < 2; ++k) dst[m][k] = *(const LAS bf16x8*)(lds + PG8_SA(b, h) + aoff + m * 2048 + k * 1024); } while (0)
; #define PG8_LDB(dst, b, h) do { _Pragma("unroll") for (int n = 0; n < 2; ++n) _Pragma("unroll") for (int k = 0; k < 2; ++k) dst[n][k] = *(const LAS bf16x8*)(lds + PG8_SB(b, h) + boff + n * 2048 + k * 1024); } while (0)
; #define PG8_MMA(ai, bj, At, Bt) do { __builtin_amdgcn_s_setprio(1); _Pragma("unroll") for (int m = 0; m < 4; ++m) _Pragma("unroll") for (int n = 0; n < 2; ++n) _Pragma("unroll") for (int k = 0; k < 2; ++k) \
;         acc[ai][bj][m][n] = __builtin_amdgcn_mfma_f32_16x16x32_bf16(Bt[n][k], At[m][k], acc[ai][bj][m][n], 0, 0, 0); __builtin_amdgcn_s_setprio(0); } while (0)
; #define PG8_WAIT_V(n) asm volatile("s_waitcnt vmcnt(" #n ")" ::: "memory")
; #define PG8_WAIT_L(n) asm volatile("s_waitcnt lgkmcnt(" #n ")" ::: "memory")
; #define PG8_BAR __builtin_amdgcn_s_barrier()
; template <class Epi>
; __device__ __forceinline__ void gemm_phase(LAS unsigned char* lds, const Gemm g, const StaticOrder& S, const Epi& E) {
;     ...
;         for (int t = 0; t < nt; t += 2) {
;             const bool last = (t == nt - 2);
;             const char* a1 = cA + (size_t)(t + 1) * kstep;
;             const char* a2 = last ? nA : cA + (size_t)(t + 2) * kstep; const char* b2 = last ? nB : cB + (size_t)(t + 2) * kstep;
;             const char* a3 = a2 + kstep; const char* b3 = b2 + kstep;
;             if constexpr (Epi::MIDK > 0) { if (t == Epi::MIDK) E.mid(acc, cur, wr, wc, fr, fq); }
;             PG8_LDB(B0, 0, 0); PG8_LDB(B1, 0, 1); PG8_SCHED; PG8_LDA(At, 0, 0); PG8_STAGE(PG8_SA(1, 1), a1 + hstep, voffA);
;             PG8_WAIT_V(8); PG8_WAIT_L(0); PG8_BAR; PG8_MMA(0, 0, At, B0); PG8_MMA(0, 1, At, B1); PG8_BAR; PG8_SCHED;
;             PG8_LDA(At, 0, 1); PG8_STAGE(PG8_SB(0, 0), b2, voffB); PG8_STAGE(PG8_SB(0, 1), b2 + hstep, voffB); PG8_STAGE(PG8_SA(0, 0), a2, voffA);
;             PG8_WAIT_V(8); PG8_WAIT_L(0); PG8_BAR; PG8_MMA(1, 0, At, B0); PG8_MMA(1, 1, At, B1); PG8_BAR; PG8_SCHED;
.LBB0_884:
	ds_read_b128 v[158:161], v150
	ds_read_b128 v[162:165], v150 offset:1024
	ds_read_b128 v[166:169], v150 offset:2048
	ds_read_b128 v[174:177], v150 offset:3072
	ds_read_b128 v[178:181], v151
	ds_read_b128 v[182:185], v151 offset:1024
	ds_read_b128 v[186:189], v151 offset:2048
	ds_read_b128 v[190:193], v151 offset:3072
	s_add_u32 s46, s44, 0xfffc0080
	s_addc_u32 s47, s45, -1
	s_cmp_eq_u32 s67, 12
	s_cselect_b32 s49, s62, s47
	s_cselect_b32 s48, s63, s46
	s_cselect_b32 s47, s23, s66
	s_cselect_b32 s46, s64, s65
	s_add_i32 m0, s41, 0xc000
	ds_read_b128 v[194:197], v152
	ds_read_b128 v[198:201], v152 offset:1024
	ds_read_b128 v[202:205], v152 offset:2048
	ds_read_b128 v[206:209], v152 offset:3072
	ds_read_b128 v[210:213], v152 offset:4096
	ds_read_b128 v[214:217], v152 offset:5120
	ds_read_b128 v[218:221], v152 offset:6144
	ds_read_b128 v[222:225], v152 offset:7168
	global_load_lds_dwordx4 v140, s[44:45]
	s_add_i32 m0, s41, 0xe000
	s_nop 0
	global_load_lds_dwordx4 v142, s[44:45]
	s_waitcnt vmcnt(8)
	s_waitcnt lgkmcnt(0)
	s_barrier
	v_mfma_f32_16x16x32_bf16 v[126:129], v[158:161], v[194:197], v[126:129]
	v_mfma_f32_16x16x32_bf16 v[118:121], v[166:169], v[194:197], v[118:121]
	v_mfma_f32_16x16x32_bf16 v[110:113], v[158:161], v[202:205], v[110:113]
	v_mfma_f32_16x16x32_bf16 v[102:105], v[166:169], v[202:205], v[102:105]
	v_mfma_f32_16x16x32_bf16 v[94:97], v[158:161], v[210:213], v[94:97]
	v_mfma_f32_16x16x32_bf16 v[86:89], v[166:169], v[210:213], v[86:89]
	v_mfma_f32_16x16x32_bf16 v[78:81], v[158:161], v[218:221], v[78:81]
	v_mfma_f32_16x16x32_bf16 v[70:73], v[166:169], v[218:221], v[70:73]
	v_mfma_f32_16x16x32_bf16 v[126:129], v[162:165], v[198:201], v[126:129]
	v_mfma_f32_16x16x32_bf16 v[118:121], v[174:177], v[198:201], v[118:121]
	v_mfma_f32_16x16x32_bf16 v[110:113], v[162:165], v[206:209], v[110:113]
	v_mfma_f32_16x16x32_bf16 v[102:105], v[174:177], v[206:209], v[102:105]
	v_mfma_f32_16x16x32_bf16 v[94:97], v[162:165], v[214:217], v[94:97]
	v_mfma_f32_16x16x32_bf16 v[86:89], v[174:177], v[214:217], v[86:89]
	v_mfma_f32_16x16x32_bf16 v[78:81], v[162:165], v[222:225], v[78:81]
	v_mfma_f32_16x16x32_bf16 v[70:73], v[174:177], v[222:225], v[70:73]
	v_mfma_f32_16x16x32_bf16 v[122:125], v[178:181], v[194:197], v[122:125]
	v_mfma_f32_16x16x32_bf16 v[114:117], v[186:189], v[194:197], v[114:117]
	v_mfma_f32_16x16x32_bf16 v[106:109], v[178:181], v[202:205], v[106:109]
	v_mfma_f32_16x16x32_bf16 v[98:101], v[186:189], v[202:205], v[98:101]
	v_mfma_f32_16x16x32_bf16 v[90:93], v[178:181], v[210:213], v[90:93]
	v_mfma_f32_16x16x32_bf16 v[82:85], v[186:189], v[210:213], v[82:85]
	v_mfma_f32_16x16x32_bf16 v[74:77], v[178:181], v[218:221], v[74:77]
	v_mfma_f32_16x16x32_bf16 v[66:69], v[186:189], v[218:221], v[66:69]
	v_mfma_f32_16x16x32_bf16 v[122:125], v[182:185], v[198:201], v[122:125]
	v_mfma_f32_16x16x32_bf16 v[114:117], v[190:193], v[198:201], v[114:117]
	v_mfma_f32_16x16x32_bf16 v[106:109], v[182:185], v[206:209], v[106:109]
	v_mfma_f32_16x16x32_bf16 v[98:101], v[190:193], v[206:209], v[98:101]
	v_mfma_f32_16x16x32_bf16 v[90:93], v[182:185], v[214:217], v[90:93]
	v_mfma_f32_16x16x32_bf16 v[82:85], v[190:193], v[214:217], v[82:85]
	v_mfma_f32_16x16x32_bf16 v[74:77], v[182:185], v[222:225], v[74:77]
	v_mfma_f32_16x16x32_bf16 v[66:69], v[190:193], v[222:225], v[66:69]
	s_barrier
	s_add_u32 s98, s46, s8
	s_addc_u32 s99, s47, s9
	s_add_u32 s100, s48, s8
	s_addc_u32 s101, s49, s9
	s_add_i32 s68, s58, s6
	s_mov_b32 m0, s68
	ds_read_b128 v[194:197], v152 offset:16384
	ds_read_b128 v[198:201], v152 offset:17408
	ds_read_b128 v[202:205], v152 offset:18432
	ds_read_b128 v[206:209], v152 offset:19456
	ds_read_b128 v[210:213], v152 offset:20480
	ds_read_b128 v[214:217], v152 offset:21504
	ds_read_b128 v[218:221], v152 offset:22528
	ds_read_b128 v[222:225], v152 offset:23552
	global_load_lds_dwordx4 v132, s[46:47]
	s_add_i32 m0, s68, 0x2000
	s_add_u32 s68, s46, 0x40000
	s_addc_u32 s69, s47, 0
	s_add_i32 s76, s59, s6
	global_load_lds_dwordx4 v136, s[46:47]
	s_mov_b32 m0, s76
	s_nop 0
	global_load_lds_dwordx4 v132, s[68:69]
	s_add_i32 m0, s76, 0x2000
	s_nop 0
	global_load_lds_dwordx4 v136, s[68:69]
	s_mov_b32 m0, s41
	s_nop 0
	global_load_lds_dwordx4 v130, s[48:49]
	s_mov_b32 m0, s43
	s_nop 0
	global_load_lds_dwordx4 v134, s[48:49]
	s_waitcnt vmcnt(8)
	s_waitcnt lgkmcnt(0)
	s_barrier
	v_mfma_f32_16x16x32_bf16 v[62:65], v[158:161], v[194:197], v[62:65]
	v_mfma_f32_16x16x32_bf16 v[54:57], v[166:169], v[194:197], v[54:57]
	v_mfma_f32_16x16x32_bf16 v[46:49], v[158:161], v[202:205], v[46:49]
	v_mfma_f32_16x16x32_bf16 v[38:41], v[166:169], v[202:205], v[38:41]
	v_mfma_f32_16x16x32_bf16 v[30:33], v[158:161], v[210:213], v[30:33]
	v_mfma_f32_16x16x32_bf16 v[22:25], v[166:169], v[210:213], v[22:25]
	v_mfma_f32_16x16x32_bf16 v[14:17], v[158:161], v[218:221], v[14:17]
	v_mfma_f32_16x16x32_bf16 v[6:9], v[166:169], v[218:221], v[6:9]
	v_mfma_f32_16x16x32_bf16 v[62:65], v[162:165], v[198:201], v[62:65]
	v_mfma_f32_16x16x32_bf16 v[54:57], v[174:177], v[198:201], v[54:57]
	v_mfma_f32_16x16x32_bf16 v[46:49], v[162:165], v[206:209], v[46:49]
	v_mfma_f32_16x16x32_bf16 v[38:41], v[174:177], v[206:209], v[38:41]
	v_mfma_f32_16x16x32_bf16 v[30:33], v[162:165], v[214:217], v[30:33]
	v_mfma_f32_16x16x32_bf16 v[22:25], v[174:177], v[214:217], v[22:25]
	v_mfma_f32_16x16x32_bf16 v[14:17], v[162:165], v[222:225], v[14:17]
	v_mfma_f32_16x16x32_bf16 v[6:9], v[174:177], v[222:225], v[6:9]
	v_mfma_f32_16x16x32_bf16 v[58:61], v[178:181], v[194:197], v[58:61]
	v_mfma_f32_16x16x32_bf16 v[50:53], v[186:189], v[194:197], v[50:53]
	v_mfma_f32_16x16x32_bf16 v[42:45], v[178:181], v[202:205], v[42:45]
	v_mfma_f32_16x16x32_bf16 v[34:37], v[186:189], v[202:205], v[34:37]
	v_mfma_f32_16x16x32_bf16 v[26:29], v[178:181], v[210:213], v[26:29]
	v_mfma_f32_16x16x32_bf16 v[18:21], v[186:189], v[210:213], v[18:21]
	v_mfma_f32_16x16x32_bf16 v[10:13], v[178:181], v[218:221], v[10:13]
	v_mfma_f32_16x16x32_bf16 v[2:5], v[186:189], v[218:221], v[2:5]
	v_mfma_f32_16x16x32_bf16 v[58:61], v[182:185], v[198:201], v[58:61]
	v_mfma_f32_16x16x32_bf16 v[50:53], v[190:193], v[198:201], v[50:53]
	v_mfma_f32_16x16x32_bf16 v[42:45], v[182:185], v[206:209], v[42:45]
	v_mfma_f32_16x16x32_bf16 v[34:37], v[190:193], v[206:209], v[34:37]
	v_mfma_f32_16x16x32_bf16 v[26:29], v[182:185], v[214:217], v[26:29]
	v_mfma_f32_16x16x32_bf16 v[18:21], v[190:193], v[214:217], v[18:21]
	v_mfma_f32_16x16x32_bf16 v[10:13], v[182:185], v[222:225], v[10:13]
	v_mfma_f32_16x16x32_bf16 v[2:5], v[190:193], v[222:225], v[2:5]
	s_barrier
; #define PG8_STAGE(bufoff, gbase, voff) do { _Pragma("unroll") for (int _i = 0; _i < 2; ++_i) \
;         __builtin_amdgcn_global_load_lds((const unsigned*)((const char*)(gbase) + (voff)[_i]), (LAS unsigned*)(lds + (bufoff) + ldsw + _i * 8192), 16, 0, 0); } while (0)
; #define PG8_LDA(dst, b, h) do { _Pragma("unroll") for (int m = 0; m < 4; ++m) _Pragma("unroll") for (int k = 0; k < 2; ++k) dst[m][k] = *(const LAS bf16x8*)(lds + PG8_SA(b, h) + aoff + m * 2048 + k * 1024); } while (0)
; #define PG8_LDB(dst, b, h) do { _Pragma("unroll") for (int n = 0; n < 2; ++n) _Pragma("unroll") for (int k = 0; k < 2; ++k) dst[n][k] = *(const LAS bf16x8*)(lds + PG8_SB(b, h) + boff + n * 2048 + k * 1024); } while (0)
; #define PG8_MMA(ai, bj, At, Bt) do { __builtin_amdgcn_s_setprio(1); _Pragma("unroll") for (int m = 0; m < 4; ++m) _Pragma("unroll") for (int n = 0; n < 2; ++n) _Pragma("unroll") for (int k = 0; k < 2; ++k) \
;         acc[ai][bj][m][n] = __builtin_amdgcn_mfma_f32_16x16x32_bf16(Bt[n][k], At[m][k], acc[ai][bj][m][n], 0, 0, 0); __builtin_amdgcn_s_setprio(0); } while (0)
; #define PG8_WAIT_V(n) asm volatile("s_waitcnt vmcnt(" #n ")" ::: "memory")
; #define PG8_WAIT_L(n) asm volatile("s_waitcnt lgkmcnt(" #n ")" ::: "memory")
; #define PG8_BAR __builtin_amdgcn_s_barrier()
; #define PG8_SCHED __builtin_amdgcn_sched_barrier(0)
; template <class Epi>
; __device__ __forceinline__ void gemm_phase(LAS unsigned char* lds, const Gemm g, const StaticOrder& S, const Epi& E) {
;     ...
;             PG8_LDB(B0, 1, 0); PG8_LDB(B1, 1, 1); PG8_SCHED; PG8_LDA(At, 1, 0); PG8_STAGE(PG8_SA(0, 1), a2 + hstep, voffA);
;             PG8_WAIT_V(8); PG8_WAIT_L(0); PG8_BAR; PG8_MMA(0, 0, At, B0); PG8_MMA(0, 1, At, B1); PG8_BAR; PG8_SCHED;
;             PG8_LDA(At, 1, 1); PG8_STAGE(PG8_SB(1, 0), b3, voffB); PG8_STAGE(PG8_SB(1, 1), b3 + hstep, voffB); PG8_STAGE(PG8_SA(1, 0), a3, voffA);
;             PG8_WAIT_V(8); PG8_WAIT_L(0); PG8_BAR; PG8_MMA(1, 0, At, B0); PG8_MMA(1, 1, At, B1); PG8_BAR; PG8_SCHED;
;         }
	s_add_i32 s68, 0, 0x18000
	s_add_i32 s69, 0, 0x1c000
	v_add_u32_e32 v174, s68, v148
	v_add_u32_e32 v190, s69, v148
	ds_read_b128 v[158:161], v174
	ds_read_b128 v[162:165], v174 offset:1024
	ds_read_b128 v[166:169], v174 offset:2048
	ds_read_b128 v[174:177], v174 offset:3072
	ds_read_b128 v[178:181], v190
	ds_read_b128 v[182:185], v190 offset:1024
	ds_read_b128 v[186:189], v190 offset:2048
	ds_read_b128 v[190:193], v190 offset:3072
	s_add_u32 s48, s48, 0x40000
	s_addc_u32 s49, s49, 0
	s_mov_b32 m0, s51
	ds_read_b128 v[194:197], v152 offset:32768
	ds_read_b128 v[198:201], v152 offset:33792
	ds_read_b128 v[202:205], v152 offset:34816
	ds_read_b128 v[206:209], v152 offset:35840
	ds_read_b128 v[210:213], v152 offset:36864
	ds_read_b128 v[214:217], v152 offset:37888
	ds_read_b128 v[218:221], v152 offset:38912
	ds_read_b128 v[222:225], v152 offset:39936
	global_load_lds_dwordx4 v130, s[48:49]
	s_mov_b32 m0, s52
	s_nop 0
	global_load_lds_dwordx4 v134, s[48:49]
	s_waitcnt vmcnt(8)
	s_waitcnt lgkmcnt(0)
	s_barrier
	v_mfma_f32_16x16x32_bf16 v[126:129], v[158:161], v[194:197], v[126:129]
	v_mfma_f32_16x16x32_bf16 v[118:121], v[166:169], v[194:197], v[118:121]
	v_mfma_f32_16x16x32_bf16 v[110:113], v[158:161], v[202:205], v[110:113]
	v_mfma_f32_16x16x32_bf16 v[102:105], v[166:169], v[202:205], v[102:105]
	v_mfma_f32_16x16x32_bf16 v[94:97], v[158:161], v[210:213], v[94:97]
	v_mfma_f32_16x16x32_bf16 v[86:89], v[166:169], v[210:213], v[86:89]
	v_mfma_f32_16x16x32_bf16 v[78:81], v[158:161], v[218:221], v[78:81]
	v_mfma_f32_16x16x32_bf16 v[70:73], v[166:169], v[218:221], v[70:73]
	v_mfma_f32_16x16x32_bf16 v[126:129], v[162:165], v[198:201], v[126:129]
	v_mfma_f32_16x16x32_bf16 v[118:121], v[174:177], v[198:201], v[118:121]
	v_mfma_f32_16x16x32_bf16 v[110:113], v[162:165], v[206:209], v[110:113]
	v_mfma_f32_16x16x32_bf16 v[102:105], v[174:177], v[206:209], v[102:105]
	v_mfma_f32_16x16x32_bf16 v[94:97], v[162:165], v[214:217], v[94:97]
	v_mfma_f32_16x16x32_bf16 v[86:89], v[174:177], v[214:217], v[86:89]
	v_mfma_f32_16x16x32_bf16 v[78:81], v[162:165], v[222:225], v[78:81]
	v_mfma_f32_16x16x32_bf16 v[70:73], v[174:177], v[222:225], v[70:73]
	v_mfma_f32_16x16x32_bf16 v[122:125], v[178:181], v[194:197], v[122:125]
	v_mfma_f32_16x16x32_bf16 v[114:117], v[186:189], v[194:197], v[114:117]
	v_mfma_f32_16x16x32_bf16 v[106:109], v[178:181], v[202:205], v[106:109]
	v_mfma_f32_16x16x32_bf16 v[98:101], v[186:189], v[202:205], v[98:101]
	v_mfma_f32_16x16x32_bf16 v[90:93], v[178:181], v[210:213], v[90:93]
	v_mfma_f32_16x16x32_bf16 v[82:85], v[186:189], v[210:213], v[82:85]
	v_mfma_f32_16x16x32_bf16 v[74:77], v[178:181], v[218:221], v[74:77]
	v_mfma_f32_16x16x32_bf16 v[66:69], v[186:189], v[218:221], v[66:69]
	v_mfma_f32_16x16x32_bf16 v[122:125], v[182:185], v[198:201], v[122:125]
	v_mfma_f32_16x16x32_bf16 v[114:117], v[190:193], v[198:201], v[114:117]
	v_mfma_f32_16x16x32_bf16 v[106:109], v[182:185], v[206:209], v[106:109]
	v_mfma_f32_16x16x32_bf16 v[98:101], v[190:193], v[206:209], v[98:101]
	v_mfma_f32_16x16x32_bf16 v[90:93], v[182:185], v[214:217], v[90:93]
	v_mfma_f32_16x16x32_bf16 v[82:85], v[190:193], v[214:217], v[82:85]
	v_mfma_f32_16x16x32_bf16 v[74:77], v[182:185], v[222:225], v[74:77]
	v_mfma_f32_16x16x32_bf16 v[66:69], v[190:193], v[222:225], v[66:69]
	s_barrier
	s_add_i32 s48, s68, s6
	s_mov_b32 m0, s48
	ds_read_b128 v[194:197], v152 offset:49152
	ds_read_b128 v[198:201], v152 offset:50176
	ds_read_b128 v[202:205], v152 offset:51200
	ds_read_b128 v[206:209], v152 offset:52224
	ds_read_b128 v[210:213], v152 offset:53248
	ds_read_b128 v[214:217], v152 offset:54272
	ds_read_b128 v[218:221], v152 offset:55296
	ds_read_b128 v[222:225], v152 offset:56320
	global_load_lds_dwordx4 v132, s[98:99]
	s_add_i32 m0, s48, 0x2000
	s_add_u32 s46, s46, 0x40080
	s_addc_u32 s47, s47, 0
	s_add_i32 s48, s69, s6
	global_load_lds_dwordx4 v136, s[98:99]
	s_mov_b32 m0, s48
	s_nop 0
	global_load_lds_dwordx4 v132, s[46:47]
	s_add_i32 m0, s48, 0x2000
	s_nop 0
	global_load_lds_dwordx4 v136, s[46:47]
	s_mov_b32 m0, s53
	s_nop 0
	global_load_lds_dwordx4 v130, s[100:101]
	s_mov_b32 m0, s54
	s_nop 0
	global_load_lds_dwordx4 v134, s[100:101]
	s_waitcnt vmcnt(8)
	s_waitcnt lgkmcnt(0)
	s_barrier
	v_mfma_f32_16x16x32_bf16 v[62:65], v[158:161], v[194:197], v[62:65]
	v_mfma_f32_16x16x32_bf16 v[54:57], v[166:169], v[194:197], v[54:57]
	v_mfma_f32_16x16x32_bf16 v[46:49], v[158:161], v[202:205], v[46:49]
	v_mfma_f32_16x16x32_bf16 v[38:41], v[166:169], v[202:205], v[38:41]
	v_mfma_f32_16x16x32_bf16 v[30:33], v[158:161], v[210:213], v[30:33]
	v_mfma_f32_16x16x32_bf16 v[22:25], v[166:169], v[210:213], v[22:25]
	v_mfma_f32_16x16x32_bf16 v[14:17], v[158:161], v[218:221], v[14:17]
	v_mfma_f32_16x16x32_bf16 v[6:9], v[166:169], v[218:221], v[6:9]
	v_mfma_f32_16x16x32_bf16 v[62:65], v[162:165], v[198:201], v[62:65]
	v_mfma_f32_16x16x32_bf16 v[54:57], v[174:177], v[198:201], v[54:57]
	v_mfma_f32_16x16x32_bf16 v[46:49], v[162:165], v[206:209], v[46:49]
	v_mfma_f32_16x16x32_bf16 v[38:41], v[174:177], v[206:209], v[38:41]
	v_mfma_f32_16x16x32_bf16 v[30:33], v[162:165], v[214:217], v[30:33]
	v_mfma_f32_16x16x32_bf16 v[22:25], v[174:177], v[214:217], v[22:25]
	v_mfma_f32_16x16x32_bf16 v[14:17], v[162:165], v[222:225], v[14:17]
	v_mfma_f32_16x16x32_bf16 v[6:9], v[174:177], v[222:225], v[6:9]
	v_mfma_f32_16x16x32_bf16 v[58:61], v[178:181], v[194:197], v[58:61]
	v_mfma_f32_16x16x32_bf16 v[50:53], v[186:189], v[194:197], v[50:53]
	v_mfma_f32_16x16x32_bf16 v[42:45], v[178:181], v[202:205], v[42:45]
	v_mfma_f32_16x16x32_bf16 v[34:37], v[186:189], v[202:205], v[34:37]
	v_mfma_f32_16x16x32_bf16 v[26:29], v[178:181], v[210:213], v[26:29]
	v_mfma_f32_16x16x32_bf16 v[18:21], v[186:189], v[210:213], v[18:21]
	v_mfma_f32_16x16x32_bf16 v[10:13], v[178:181], v[218:221], v[10:13]
	v_mfma_f32_16x16x32_bf16 v[2:5], v[186:189], v[218:221], v[2:5]
	v_mfma_f32_16x16x32_bf16 v[58:61], v[182:185], v[198:201], v[58:61]
	v_mfma_f32_16x16x32_bf16 v[50:53], v[190:193], v[198:201], v[50:53]
	v_mfma_f32_16x16x32_bf16 v[42:45], v[182:185], v[206:209], v[42:45]
	v_mfma_f32_16x16x32_bf16 v[34:37], v[190:193], v[206:209], v[34:37]
	v_mfma_f32_16x16x32_bf16 v[26:29], v[182:185], v[214:217], v[26:29]
	v_mfma_f32_16x16x32_bf16 v[18:21], v[190:193], v[214:217], v[18:21]
	v_mfma_f32_16x16x32_bf16 v[10:13], v[182:185], v[222:225], v[10:13]
	v_mfma_f32_16x16x32_bf16 v[2:5], v[190:193], v[222:225], v[2:5]
	s_barrier
	s_add_i32 s67, s67, 2
	s_add_u32 s44, s44, 0x100
	s_addc_u32 s45, s45, 0
	s_add_u32 s65, s65, 0x100
	s_addc_u32 s66, s66, 0
	s_cmp_gt_u32 s67, 13
	s_cbranch_scc0 .LBB0_884
	s_and_b64 vcc, exec, s[14:15]
	s_cbranch_vccz .LBB0_887
	s_barrier

; #define PG8_STAGE(bufoff, gbase, voff) do { _Pragma("unroll") for (int _i = 0; _i < 2; ++_i) \
;         __builtin_amdgcn_global_load_lds((const unsigned*)((const char*)(gbase) + (voff)[_i]), (LAS unsigned*)(lds + (bufoff) + ldsw + _i * 8192), 16, 0, 0); } while (0)
; #define PG8_LDA(dst, b, h) do { _Pragma("unroll") for (int m = 0; m < 4; ++m) _Pragma("unroll") for (int k = 0; k < 2; ++k) dst[m][k] = *(const LAS bf16x8*)(lds + PG8_SA(b, h) + aoff + m * 2048 + k * 1024); } while (0)
; #define PG8_LDB(dst, b, h) do { _Pragma("unroll") for (int n = 0; n < 2; ++n) _Pragma("unroll") for (int k = 0; k < 2; ++k) dst[n][k] = *(const LAS bf16x8*)(lds + PG8_SB(b, h) + boff + n * 2048 + k * 1024); } while (0)
; #define PG8_MMA(ai, bj, At, Bt) do { __builtin_amdgcn_s_setprio(1); _Pragma("unroll") for (int m = 0; m < 4; ++m) _Pragma("unroll") for (int n = 0; n < 2; ++n) _Pragma("unroll") for (int k = 0; k < 2; ++k) \
;         acc[ai][bj][m][n] = __builtin_amdgcn_mfma_f32_16x16x32_bf16(Bt[n][k], At[m][k], acc[ai][bj][m][n], 0, 0, 0); __builtin_amdgcn_s_setprio(0); } while (0)
; #define PG8_WAIT_V(n) asm volatile("s_waitcnt vmcnt(" #n ")" ::: "memory")
; #define PG8_WAIT_L(n) asm volatile("s_waitcnt lgkmcnt(" #n ")" ::: "memory")
; #define PG8_BAR __builtin_amdgcn_s_barrier()
; template <class Epi>
; __device__ __forceinline__ void gemm_phase(LAS unsigned char* lds, const Gemm g, const StaticOrder& S, const Epi& E) {
;     ...
;         for (int t = 0; t < nt; t += 2) {
;             const bool last = (t == nt - 2);
;             const char* a1 = cA + (size_t)(t + 1) * kstep;
;             const char* a2 = last ? nA : cA + (size_t)(t + 2) * kstep; const char* b2 = last ? nB : cB + (size_t)(t + 2) * kstep;
;             const char* a3 = a2 + kstep; const char* b3 = b2 + kstep;
;             if constexpr (Epi::MIDK > 0) { if (t == Epi::MIDK) E.mid(acc, cur, wr, wc, fr, fq); }
;             PG8_LDB(B0, 0, 0); PG8_LDB(B1, 0, 1); PG8_SCHED; PG8_LDA(At, 0, 0); PG8_STAGE(PG8_SA(1, 1), a1 + hstep, voffA);
;             PG8_WAIT_V(8); PG8_WAIT_L(0); PG8_BAR; PG8_MMA(0, 0, At, B0); PG8_MMA(0, 1, At, B1); PG8_BAR; PG8_SCHED;
;             PG8_LDA(At, 0, 1); PG8_STAGE(PG8_SB(0, 0), b2, voffB); PG8_STAGE(PG8_SB(0, 1), b2 + hstep, voffB); PG8_STAGE(PG8_SA(0, 0), a2, voffA);
;             PG8_WAIT_V(8); PG8_WAIT_L(0); PG8_BAR; PG8_MMA(1, 0, At, B0); PG8_MMA(1, 1, At, B1); PG8_BAR; PG8_SCHED;
.LBB0_971:
	ds_read_b128 v[130:133], v162
	ds_read_b128 v[134:137], v162 offset:1024
	ds_read_b128 v[154:157], v162 offset:2048
	ds_read_b128 v[166:169], v162 offset:3072
	ds_read_b128 v[174:177], v163
	ds_read_b128 v[178:181], v163 offset:1024
	ds_read_b128 v[182:185], v163 offset:2048
	ds_read_b128 v[186:189], v163 offset:3072
	s_add_u32 s24, s22, 0xfff50080
	s_addc_u32 s25, s23, -1
	s_cmp_eq_u32 s59, 40
	s_cselect_b32 s27, s5, s25
	s_cselect_b32 s26, s4, s24
	s_cselect_b32 s25, s21, s58
	s_cselect_b32 s24, s20, s57
	s_add_i32 m0, s39, 0xc000
	ds_read_b128 v[190:193], v164
	ds_read_b128 v[194:197], v164 offset:1024
	ds_read_b128 v[198:201], v164 offset:2048
	ds_read_b128 v[202:205], v164 offset:3072
	ds_read_b128 v[206:209], v164 offset:4096
	ds_read_b128 v[210:213], v164 offset:5120
	ds_read_b128 v[214:217], v164 offset:6144
	ds_read_b128 v[218:221], v164 offset:7168
	global_load_lds_dwordx4 v146, s[22:23]
	s_add_i32 m0, s39, 0xe000
	s_nop 0
	global_load_lds_dwordx4 v148, s[22:23]
	s_waitcnt vmcnt(8)
	s_waitcnt lgkmcnt(0)
	s_barrier
	v_mfma_f32_16x16x32_bf16 v[126:129], v[130:133], v[190:193], v[126:129]
	v_mfma_f32_16x16x32_bf16 v[122:125], v[154:157], v[190:193], v[122:125]
	v_mfma_f32_16x16x32_bf16 v[110:113], v[130:133], v[198:201], v[110:113]
	v_mfma_f32_16x16x32_bf16 v[106:109], v[154:157], v[198:201], v[106:109]
	v_mfma_f32_16x16x32_bf16 v[94:97], v[130:133], v[206:209], v[94:97]
	v_mfma_f32_16x16x32_bf16 v[90:93], v[154:157], v[206:209], v[90:93]
	v_mfma_f32_16x16x32_bf16 v[78:81], v[130:133], v[214:217], v[78:81]
	v_mfma_f32_16x16x32_bf16 v[74:77], v[154:157], v[214:217], v[74:77]
	v_mfma_f32_16x16x32_bf16 v[126:129], v[134:137], v[194:197], v[126:129]
	v_mfma_f32_16x16x32_bf16 v[122:125], v[166:169], v[194:197], v[122:125]
	v_mfma_f32_16x16x32_bf16 v[110:113], v[134:137], v[202:205], v[110:113]
	v_mfma_f32_16x16x32_bf16 v[106:109], v[166:169], v[202:205], v[106:109]
	v_mfma_f32_16x16x32_bf16 v[94:97], v[134:137], v[210:213], v[94:97]
	v_mfma_f32_16x16x32_bf16 v[90:93], v[166:169], v[210:213], v[90:93]
	v_mfma_f32_16x16x32_bf16 v[78:81], v[134:137], v[218:221], v[78:81]
	v_mfma_f32_16x16x32_bf16 v[74:77], v[166:169], v[218:221], v[74:77]
	v_mfma_f32_16x16x32_bf16 v[118:121], v[174:177], v[190:193], v[118:121]
	v_mfma_f32_16x16x32_bf16 v[114:117], v[182:185], v[190:193], v[114:117]
	v_mfma_f32_16x16x32_bf16 v[102:105], v[174:177], v[198:201], v[102:105]
	v_mfma_f32_16x16x32_bf16 v[98:101], v[182:185], v[198:201], v[98:101]
	v_mfma_f32_16x16x32_bf16 v[86:89], v[174:177], v[206:209], v[86:89]
	v_mfma_f32_16x16x32_bf16 v[82:85], v[182:185], v[206:209], v[82:85]
	v_mfma_f32_16x16x32_bf16 v[70:73], v[174:177], v[214:217], v[70:73]
	v_mfma_f32_16x16x32_bf16 v[66:69], v[182:185], v[214:217], v[66:69]
	v_mfma_f32_16x16x32_bf16 v[118:121], v[178:181], v[194:197], v[118:121]
	v_mfma_f32_16x16x32_bf16 v[114:117], v[186:189], v[194:197], v[114:117]
	v_mfma_f32_16x16x32_bf16 v[102:105], v[178:181], v[202:205], v[102:105]
	v_mfma_f32_16x16x32_bf16 v[98:101], v[186:189], v[202:205], v[98:101]
	v_mfma_f32_16x16x32_bf16 v[86:89], v[178:181], v[210:213], v[86:89]
	v_mfma_f32_16x16x32_bf16 v[82:85], v[186:189], v[210:213], v[82:85]
	v_mfma_f32_16x16x32_bf16 v[70:73], v[178:181], v[218:221], v[70:73]
	v_mfma_f32_16x16x32_bf16 v[66:69], v[186:189], v[218:221], v[66:69]
	s_barrier
	s_add_u32 s98, s24, s14
	s_addc_u32 s99, s25, s15
	s_add_u32 s100, s26, s14
	s_addc_u32 s101, s27, s15
	s_add_i32 s60, s51, s38
	s_mov_b32 m0, s60
	ds_read_b128 v[190:193], v164 offset:16384
	ds_read_b128 v[194:197], v164 offset:17408
	ds_read_b128 v[198:201], v164 offset:18432
	ds_read_b128 v[202:205], v164 offset:19456
	ds_read_b128 v[206:209], v164 offset:20480
	ds_read_b128 v[210:213], v164 offset:21504
	ds_read_b128 v[214:217], v164 offset:22528
	ds_read_b128 v[218:221], v164 offset:23552
	global_load_lds_dwordx4 v140, s[24:25]
	s_add_i32 m0, s60, 0x2000
	s_add_u32 s60, s24, 0xb0000
	s_addc_u32 s61, s25, 0
	s_add_i32 s62, s52, s38
	global_load_lds_dwordx4 v144, s[24:25]
	s_mov_b32 m0, s62
	s_nop 0
	global_load_lds_dwordx4 v140, s[60:61]
	s_add_i32 m0, s62, 0x2000
	s_nop 0
	global_load_lds_dwordx4 v144, s[60:61]
	s_mov_b32 m0, s39
	s_nop 0
	global_load_lds_dwordx4 v138, s[26:27]
	s_mov_b32 m0, s40
	s_nop 0
	global_load_lds_dwordx4 v142, s[26:27]
	s_waitcnt vmcnt(8)
	s_waitcnt lgkmcnt(0)
	s_barrier
	v_mfma_f32_16x16x32_bf16 v[62:65], v[130:133], v[190:193], v[62:65]
	v_mfma_f32_16x16x32_bf16 v[58:61], v[154:157], v[190:193], v[58:61]
	v_mfma_f32_16x16x32_bf16 v[46:49], v[130:133], v[198:201], v[46:49]
	v_mfma_f32_16x16x32_bf16 v[42:45], v[154:157], v[198:201], v[42:45]
	v_mfma_f32_16x16x32_bf16 v[30:33], v[130:133], v[206:209], v[30:33]
	v_mfma_f32_16x16x32_bf16 v[26:29], v[154:157], v[206:209], v[26:29]
	v_mfma_f32_16x16x32_bf16 v[14:17], v[130:133], v[214:217], v[14:17]
	v_mfma_f32_16x16x32_bf16 v[10:13], v[154:157], v[214:217], v[10:13]
	v_mfma_f32_16x16x32_bf16 v[62:65], v[134:137], v[194:197], v[62:65]
	v_mfma_f32_16x16x32_bf16 v[58:61], v[166:169], v[194:197], v[58:61]
	v_mfma_f32_16x16x32_bf16 v[46:49], v[134:137], v[202:205], v[46:49]
	v_mfma_f32_16x16x32_bf16 v[42:45], v[166:169], v[202:205], v[42:45]
	v_mfma_f32_16x16x32_bf16 v[30:33], v[134:137], v[210:213], v[30:33]
	v_mfma_f32_16x16x32_bf16 v[26:29], v[166:169], v[210:213], v[26:29]
	v_mfma_f32_16x16x32_bf16 v[14:17], v[134:137], v[218:221], v[14:17]
	v_mfma_f32_16x16x32_bf16 v[10:13], v[166:169], v[218:221], v[10:13]
	v_mfma_f32_16x16x32_bf16 v[54:57], v[174:177], v[190:193], v[54:57]
	v_mfma_f32_16x16x32_bf16 v[50:53], v[182:185], v[190:193], v[50:53]
	v_mfma_f32_16x16x32_bf16 v[38:41], v[174:177], v[198:201], v[38:41]
	v_mfma_f32_16x16x32_bf16 v[34:37], v[182:185], v[198:201], v[34:37]
	v_mfma_f32_16x16x32_bf16 v[22:25], v[174:177], v[206:209], v[22:25]
	v_mfma_f32_16x16x32_bf16 v[18:21], v[182:185], v[206:209], v[18:21]
	v_mfma_f32_16x16x32_bf16 v[6:9], v[174:177], v[214:217], v[6:9]
	v_mfma_f32_16x16x32_bf16 v[2:5], v[182:185], v[214:217], v[2:5]
	v_mfma_f32_16x16x32_bf16 v[54:57], v[178:181], v[194:197], v[54:57]
	v_mfma_f32_16x16x32_bf16 v[50:53], v[186:189], v[194:197], v[50:53]
	v_mfma_f32_16x16x32_bf16 v[38:41], v[178:181], v[202:205], v[38:41]
	v_mfma_f32_16x16x32_bf16 v[34:37], v[186:189], v[202:205], v[34:37]
	v_mfma_f32_16x16x32_bf16 v[22:25], v[178:181], v[210:213], v[22:25]
	v_mfma_f32_16x16x32_bf16 v[18:21], v[186:189], v[210:213], v[18:21]
	v_mfma_f32_16x16x32_bf16 v[6:9], v[178:181], v[218:221], v[6:9]
	v_mfma_f32_16x16x32_bf16 v[2:5], v[186:189], v[218:221], v[2:5]
	s_barrier
; #define PG8_STAGE(bufoff, gbase, voff) do { _Pragma("unroll") for (int _i = 0; _i < 2; ++_i) \
;         __builtin_amdgcn_global_load_lds((const unsigned*)((const char*)(gbase) + (voff)[_i]), (LAS unsigned*)(lds + (bufoff) + ldsw + _i * 8192), 16, 0, 0); } while (0)
; #define PG8_LDA(dst, b, h) do { _Pragma("unroll") for (int m = 0; m < 4; ++m) _Pragma("unroll") for (int k = 0; k < 2; ++k) dst[m][k] = *(const LAS bf16x8*)(lds + PG8_SA(b, h) + aoff + m * 2048 + k * 1024); } while (0)
; #define PG8_LDB(dst, b, h) do { _Pragma("unroll") for (int n = 0; n < 2; ++n) _Pragma("unroll") for (int k = 0; k < 2; ++k) dst[n][k] = *(const LAS bf16x8*)(lds + PG8_SB(b, h) + boff + n * 2048 + k * 1024); } while (0)
; #define PG8_MMA(ai, bj, At, Bt) do { __builtin_amdgcn_s_setprio(1); _Pragma("unroll") for (int m = 0; m < 4; ++m) _Pragma("unroll") for (int n = 0; n < 2; ++n) _Pragma("unroll") for (int k = 0; k < 2; ++k) \
;         acc[ai][bj][m][n] = __builtin_amdgcn_mfma_f32_16x16x32_bf16(Bt[n][k], At[m][k], acc[ai][bj][m][n], 0, 0, 0); __builtin_amdgcn_s_setprio(0); } while (0)
; #define PG8_WAIT_V(n) asm volatile("s_waitcnt vmcnt(" #n ")" ::: "memory")
; #define PG8_WAIT_L(n) asm volatile("s_waitcnt lgkmcnt(" #n ")" ::: "memory")
; #define PG8_BAR __builtin_amdgcn_s_barrier()
; #define PG8_SCHED __builtin_amdgcn_sched_barrier(0)
; template <class Epi>
; __device__ __forceinline__ void gemm_phase(LAS unsigned char* lds, const Gemm g, const StaticOrder& S, const Epi& E) {
;     ...
;             PG8_LDB(B0, 1, 0); PG8_LDB(B1, 1, 1); PG8_SCHED; PG8_LDA(At, 1, 0); PG8_STAGE(PG8_SA(0, 1), a2 + hstep, voffA);
;             PG8_WAIT_V(8); PG8_WAIT_L(0); PG8_BAR; PG8_MMA(0, 0, At, B0); PG8_MMA(0, 1, At, B1); PG8_BAR; PG8_SCHED;
;             PG8_LDA(At, 1, 1); PG8_STAGE(PG8_SB(1, 0), b3, voffB); PG8_STAGE(PG8_SB(1, 1), b3 + hstep, voffB); PG8_STAGE(PG8_SA(1, 0), a3, voffA);
;             PG8_WAIT_V(8); PG8_WAIT_L(0); PG8_BAR; PG8_MMA(1, 0, At, B0); PG8_MMA(1, 1, At, B1); PG8_BAR; PG8_SCHED;
;         }
	s_add_i32 s60, 0, 0x18000
	s_add_i32 s61, 0, 0x1c000
	v_add_u32_e32 v166, s60, v160
	v_add_u32_e32 v186, s61, v160
	ds_read_b128 v[130:133], v166
	ds_read_b128 v[134:137], v166 offset:1024
	ds_read_b128 v[154:157], v166 offset:2048
	ds_read_b128 v[166:169], v166 offset:3072
	ds_read_b128 v[174:177], v186
	ds_read_b128 v[178:181], v186 offset:1024
	ds_read_b128 v[182:185], v186 offset:2048
	ds_read_b128 v[186:189], v186 offset:3072
	s_add_u32 s26, s26, 0xb0000
	s_addc_u32 s27, s27, 0
	s_mov_b32 m0, s41
	ds_read_b128 v[190:193], v164 offset:32768
	ds_read_b128 v[194:197], v164 offset:33792
	ds_read_b128 v[198:201], v164 offset:34816
	ds_read_b128 v[202:205], v164 offset:35840
	ds_read_b128 v[206:209], v164 offset:36864
	ds_read_b128 v[210:213], v164 offset:37888
	ds_read_b128 v[214:217], v164 offset:38912
	ds_read_b128 v[218:221], v164 offset:39936
	global_load_lds_dwordx4 v138, s[26:27]
	s_mov_b32 m0, s42
	s_nop 0
	global_load_lds_dwordx4 v142, s[26:27]
	s_waitcnt vmcnt(8)
	s_waitcnt lgkmcnt(0)
	s_barrier
	v_mfma_f32_16x16x32_bf16 v[126:129], v[130:133], v[190:193], v[126:129]
	v_mfma_f32_16x16x32_bf16 v[122:125], v[154:157], v[190:193], v[122:125]
	v_mfma_f32_16x16x32_bf16 v[110:113], v[130:133], v[198:201], v[110:113]
	v_mfma_f32_16x16x32_bf16 v[106:109], v[154:157], v[198:201], v[106:109]
	v_mfma_f32_16x16x32_bf16 v[94:97], v[130:133], v[206:209], v[94:97]
	v_mfma_f32_16x16x32_bf16 v[90:93], v[154:157], v[206:209], v[90:93]
	v_mfma_f32_16x16x32_bf16 v[78:81], v[130:133], v[214:217], v[78:81]
	v_mfma_f32_16x16x32_bf16 v[74:77], v[154:157], v[214:217], v[74:77]
	v_mfma_f32_16x16x32_bf16 v[126:129], v[134:137], v[194:197], v[126:129]
	v_mfma_f32_16x16x32_bf16 v[122:125], v[166:169], v[194:197], v[122:125]
	v_mfma_f32_16x16x32_bf16 v[110:113], v[134:137], v[202:205], v[110:113]
	v_mfma_f32_16x16x32_bf16 v[106:109], v[166:169], v[202:205], v[106:109]
	v_mfma_f32_16x16x32_bf16 v[94:97], v[134:137], v[210:213], v[94:97]
	v_mfma_f32_16x16x32_bf16 v[90:93], v[166:169], v[210:213], v[90:93]
	v_mfma_f32_16x16x32_bf16 v[78:81], v[134:137], v[218:221], v[78:81]
	v_mfma_f32_16x16x32_bf16 v[74:77], v[166:169], v[218:221], v[74:77]
	v_mfma_f32_16x16x32_bf16 v[118:121], v[174:177], v[190:193], v[118:121]
	v_mfma_f32_16x16x32_bf16 v[114:117], v[182:185], v[190:193], v[114:117]
	v_mfma_f32_16x16x32_bf16 v[102:105], v[174:177], v[198:201], v[102:105]
	v_mfma_f32_16x16x32_bf16 v[98:101], v[182:185], v[198:201], v[98:101]
	v_mfma_f32_16x16x32_bf16 v[86:89], v[174:177], v[206:209], v[86:89]
	v_mfma_f32_16x16x32_bf16 v[82:85], v[182:185], v[206:209], v[82:85]
	v_mfma_f32_16x16x32_bf16 v[70:73], v[174:177], v[214:217], v[70:73]
	v_mfma_f32_16x16x32_bf16 v[66:69], v[182:185], v[214:217], v[66:69]
	v_mfma_f32_16x16x32_bf16 v[118:121], v[178:181], v[194:197], v[118:121]
	v_mfma_f32_16x16x32_bf16 v[114:117], v[186:189], v[194:197], v[114:117]
	v_mfma_f32_16x16x32_bf16 v[102:105], v[178:181], v[202:205], v[102:105]
	v_mfma_f32_16x16x32_bf16 v[98:101], v[186:189], v[202:205], v[98:101]
	v_mfma_f32_16x16x32_bf16 v[86:89], v[178:181], v[210:213], v[86:89]
	v_mfma_f32_16x16x32_bf16 v[82:85], v[186:189], v[210:213], v[82:85]
	v_mfma_f32_16x16x32_bf16 v[70:73], v[178:181], v[218:221], v[70:73]
	v_mfma_f32_16x16x32_bf16 v[66:69], v[186:189], v[218:221], v[66:69]
	s_barrier
	s_add_i32 s26, s60, s38
	s_mov_b32 m0, s26
	ds_read_b128 v[190:193], v164 offset:49152
	ds_read_b128 v[194:197], v164 offset:50176
	ds_read_b128 v[198:201], v164 offset:51200
	ds_read_b128 v[202:205], v164 offset:52224
	ds_read_b128 v[206:209], v164 offset:53248
	ds_read_b128 v[210:213], v164 offset:54272
	ds_read_b128 v[214:217], v164 offset:55296
	ds_read_b128 v[218:221], v164 offset:56320
	global_load_lds_dwordx4 v140, s[98:99]
	s_add_i32 m0, s26, 0x2000
	s_add_u32 s24, s24, 0xb0080
	s_addc_u32 s25, s25, 0
	s_add_i32 s26, s61, s38
	global_load_lds_dwordx4 v144, s[98:99]
	s_mov_b32 m0, s26
	s_nop 0
	global_load_lds_dwordx4 v140, s[24:25]
	s_add_i32 m0, s26, 0x2000
	s_nop 0
	global_load_lds_dwordx4 v144, s[24:25]
	s_mov_b32 m0, s44
	s_nop 0
	global_load_lds_dwordx4 v138, s[100:101]
	s_mov_b32 m0, s45
	s_nop 0
	global_load_lds_dwordx4 v142, s[100:101]
	s_waitcnt vmcnt(8)
	s_waitcnt lgkmcnt(0)
	s_barrier
	v_mfma_f32_16x16x32_bf16 v[62:65], v[130:133], v[190:193], v[62:65]
	v_mfma_f32_16x16x32_bf16 v[58:61], v[154:157], v[190:193], v[58:61]
	v_mfma_f32_16x16x32_bf16 v[46:49], v[130:133], v[198:201], v[46:49]
	v_mfma_f32_16x16x32_bf16 v[42:45], v[154:157], v[198:201], v[42:45]
	v_mfma_f32_16x16x32_bf16 v[30:33], v[130:133], v[206:209], v[30:33]
	v_mfma_f32_16x16x32_bf16 v[26:29], v[154:157], v[206:209], v[26:29]
	v_mfma_f32_16x16x32_bf16 v[14:17], v[130:133], v[214:217], v[14:17]
	v_mfma_f32_16x16x32_bf16 v[10:13], v[154:157], v[214:217], v[10:13]
	v_mfma_f32_16x16x32_bf16 v[62:65], v[134:137], v[194:197], v[62:65]
	v_mfma_f32_16x16x32_bf16 v[58:61], v[166:169], v[194:197], v[58:61]
	v_mfma_f32_16x16x32_bf16 v[46:49], v[134:137], v[202:205], v[46:49]
	v_mfma_f32_16x16x32_bf16 v[42:45], v[166:169], v[202:205], v[42:45]
	v_mfma_f32_16x16x32_bf16 v[30:33], v[134:137], v[210:213], v[30:33]
	v_mfma_f32_16x16x32_bf16 v[26:29], v[166:169], v[210:213], v[26:29]
	v_mfma_f32_16x16x32_bf16 v[14:17], v[134:137], v[218:221], v[14:17]
	v_mfma_f32_16x16x32_bf16 v[10:13], v[166:169], v[218:221], v[10:13]
	v_mfma_f32_16x16x32_bf16 v[54:57], v[174:177], v[190:193], v[54:57]
	v_mfma_f32_16x16x32_bf16 v[50:53], v[182:185], v[190:193], v[50:53]
	v_mfma_f32_16x16x32_bf16 v[38:41], v[174:177], v[198:201], v[38:41]
	v_mfma_f32_16x16x32_bf16 v[34:37], v[182:185], v[198:201], v[34:37]
	v_mfma_f32_16x16x32_bf16 v[22:25], v[174:177], v[206:209], v[22:25]
	v_mfma_f32_16x16x32_bf16 v[18:21], v[182:185], v[206:209], v[18:21]
	v_mfma_f32_16x16x32_bf16 v[6:9], v[174:177], v[214:217], v[6:9]
	v_mfma_f32_16x16x32_bf16 v[2:5], v[182:185], v[214:217], v[2:5]
	v_mfma_f32_16x16x32_bf16 v[54:57], v[178:181], v[194:197], v[54:57]
	v_mfma_f32_16x16x32_bf16 v[50:53], v[186:189], v[194:197], v[50:53]
	v_mfma_f32_16x16x32_bf16 v[38:41], v[178:181], v[202:205], v[38:41]
	v_mfma_f32_16x16x32_bf16 v[34:37], v[186:189], v[202:205], v[34:37]
	v_mfma_f32_16x16x32_bf16 v[22:25], v[178:181], v[210:213], v[22:25]
	v_mfma_f32_16x16x32_bf16 v[18:21], v[186:189], v[210:213], v[18:21]
	v_mfma_f32_16x16x32_bf16 v[6:9], v[178:181], v[218:221], v[6:9]
	v_mfma_f32_16x16x32_bf16 v[2:5], v[186:189], v[218:221], v[2:5]
	s_barrier
	s_add_i32 s59, s59, 2
	s_add_u32 s22, s22, 0x100
	s_addc_u32 s23, s23, 0
	s_add_u32 s57, s57, 0x100
	s_addc_u32 s58, s58, 0
	s_cmp_gt_u32 s59, 41
	s_cbranch_scc0 .LBB0_971
	s_and_b64 vcc, exec, s[18:19]
	s_cbranch_vccz .LBB0_974
	s_barrier
